# K-loop: redundant lgkmcnt(0) after the barrier removed, vmcnt+lgkmcnt wait pairs merged into one s_waitcnt
# speedup vs baseline: 1.0133x; 1.0133x over previous
.LBB0_322:
	s_ashr_i32 s43, s42, 31
	s_lshl_b64 s[46:47], s[42:43], 19
	s_add_u32 s46, s12, s46
	s_addc_u32 s47, s13, s47
	s_and_b64 s[48:49], s[4:5], exec
	s_cselect_b32 s18, s47, s7
	s_cselect_b32 s43, s46, s6
	s_ashr_i32 s45, s44, 31
	s_lshl_b64 s[48:49], s[44:45], 19
	s_add_u32 s48, s59, s48
	s_addc_u32 s49, s60, s49
	s_and_b64 s[50:51], s[4:5], exec
	s_cselect_b32 s45, s49, s9
	s_cselect_b32 s55, s48, s8
	s_add_u32 s6, s6, 0x40080
	s_addc_u32 s7, s7, 0
	s_add_u32 s56, s8, 0x100
	s_addc_u32 s57, s9, 0
	s_mov_b32 s78, -2
	ds_read_b128 v[96:99], v209
	ds_read_b128 v[100:103], v209 offset:1024
	ds_read_b128 v[120:123], v209 offset:2048
	ds_read_b128 v[124:127], v209 offset:3072
	ds_read_b128 v[144:147], v210
	ds_read_b128 v[148:151], v210 offset:1024
	ds_read_b128 v[152:155], v210 offset:2048
	ds_read_b128 v[156:159], v210 offset:3072
	s_add_u32 s8, s6, 0xfffc0080
	s_addc_u32 s9, s7, -1
	s_cmp_eq_u32 s78, 12
	s_cselect_b32 s51, s18, s9
	s_cselect_b32 s50, s43, s8
	s_cselect_b32 s9, s45, s57
	s_cselect_b32 s8, s55, s56
	v_lshl_add_u64 v[206:207], s[6:7], 0, v[170:171]
	s_add_i32 m0, s17, 0xc000
	ds_read_b128 v[178:181], v211
	ds_read_b128 v[182:185], v211 offset:1024
	ds_read_b128 v[186:189], v211 offset:2048
	ds_read_b128 v[190:193], v211 offset:3072
	ds_read_b128 v[194:197], v211 offset:4096
	ds_read_b128 v[198:201], v211 offset:5120
	ds_read_b128 v[202:205], v211 offset:6144
	ds_read_b128 v[218:221], v211 offset:7168
	global_load_lds_dwordx4 v[206:207], off
	s_add_i32 m0, s17, 0xe000
	v_lshl_add_u64 v[206:207], s[6:7], 0, v[172:173]
	global_load_lds_dwordx4 v[206:207], off
	s_waitcnt vmcnt(8) lgkmcnt(0)
	s_barrier
	s_setprio 1
	v_mfma_f32_16x16x32_bf16 v[140:143], v[96:99], v[178:181], 0
	v_mfma_f32_16x16x32_bf16 v[136:139], v[120:123], v[178:181], 0
	v_mfma_f32_16x16x32_bf16 v[116:119], v[96:99], v[186:189], 0
	v_mfma_f32_16x16x32_bf16 v[112:115], v[120:123], v[186:189], 0
	v_mfma_f32_16x16x32_bf16 v[92:95], v[96:99], v[194:197], 0
	v_mfma_f32_16x16x32_bf16 v[88:91], v[120:123], v[194:197], 0
	v_mfma_f32_16x16x32_bf16 v[76:79], v[96:99], v[202:205], 0
	v_mfma_f32_16x16x32_bf16 v[72:75], v[120:123], v[202:205], 0
	v_mfma_f32_16x16x32_bf16 v[140:143], v[100:103], v[182:185], v[140:143]
	v_mfma_f32_16x16x32_bf16 v[136:139], v[124:127], v[182:185], v[136:139]
	v_mfma_f32_16x16x32_bf16 v[116:119], v[100:103], v[190:193], v[116:119]
	v_mfma_f32_16x16x32_bf16 v[112:115], v[124:127], v[190:193], v[112:115]
	v_mfma_f32_16x16x32_bf16 v[92:95], v[100:103], v[198:201], v[92:95]
	v_mfma_f32_16x16x32_bf16 v[88:91], v[124:127], v[198:201], v[88:91]
	v_mfma_f32_16x16x32_bf16 v[76:79], v[100:103], v[218:221], v[76:79]
	v_mfma_f32_16x16x32_bf16 v[72:75], v[124:127], v[218:221], v[72:75]
	s_setprio 0
	s_setprio 1
	v_mfma_f32_16x16x32_bf16 v[132:135], v[144:147], v[178:181], 0
	v_mfma_f32_16x16x32_bf16 v[128:131], v[152:155], v[178:181], 0
	v_mfma_f32_16x16x32_bf16 v[108:111], v[144:147], v[186:189], 0
	v_mfma_f32_16x16x32_bf16 v[104:107], v[152:155], v[186:189], 0
	v_mfma_f32_16x16x32_bf16 v[84:87], v[144:147], v[194:197], 0
	v_mfma_f32_16x16x32_bf16 v[80:83], v[152:155], v[194:197], 0
	v_mfma_f32_16x16x32_bf16 v[68:71], v[144:147], v[202:205], 0
	v_mfma_f32_16x16x32_bf16 v[64:67], v[152:155], v[202:205], 0
	v_mfma_f32_16x16x32_bf16 v[132:135], v[148:151], v[182:185], v[132:135]
	v_mfma_f32_16x16x32_bf16 v[128:131], v[156:159], v[182:185], v[128:131]
	v_mfma_f32_16x16x32_bf16 v[108:111], v[148:151], v[190:193], v[108:111]
	v_mfma_f32_16x16x32_bf16 v[104:107], v[156:159], v[190:193], v[104:107]
	s_setprio 2
	s_barrier
	v_mfma_f32_16x16x32_bf16 v[84:87], v[148:151], v[198:201], v[84:87]
	v_mfma_f32_16x16x32_bf16 v[80:83], v[156:159], v[198:201], v[80:83]
	v_mfma_f32_16x16x32_bf16 v[68:71], v[148:151], v[218:221], v[68:71]
	v_mfma_f32_16x16x32_bf16 v[64:67], v[156:159], v[218:221], v[64:67]
	s_setprio 2
	s_add_i32 s79, s73, s61
	v_lshl_add_u64 v[206:207], s[8:9], 0, v[162:163]
	s_mov_b32 m0, s79
	ds_read_b128 v[178:181], v211 offset:16384
	ds_read_b128 v[182:185], v211 offset:17408
	ds_read_b128 v[186:189], v211 offset:18432
	ds_read_b128 v[190:193], v211 offset:19456
	ds_read_b128 v[194:197], v211 offset:20480
	ds_read_b128 v[198:201], v211 offset:21504
	ds_read_b128 v[202:205], v211 offset:22528
	ds_read_b128 v[218:221], v211 offset:23552
	global_load_lds_dwordx4 v[206:207], off
	s_add_i32 m0, s79, 0x2000
	s_add_u32 s80, s8, 0x40000
	v_lshl_add_u64 v[222:223], s[8:9], 0, v[166:167]
	s_addc_u32 s81, s9, 0
	s_add_i32 s79, s74, s61
	global_load_lds_dwordx4 v[222:223], off
	v_lshl_add_u64 v[224:225], s[80:81], 0, v[162:163]
	s_mov_b32 m0, s79
	v_lshl_add_u64 v[226:227], s[50:51], 0, v[164:165]
	global_load_lds_dwordx4 v[224:225], off
	s_add_i32 m0, s79, 0x2000
	v_lshl_add_u64 v[224:225], s[80:81], 0, v[166:167]
	global_load_lds_dwordx4 v[224:225], off
	s_mov_b32 m0, s17
	v_lshl_add_u64 v[224:225], s[50:51], 0, v[160:161]
	global_load_lds_dwordx4 v[224:225], off
	s_mov_b32 m0, s62
	s_nop 0
	global_load_lds_dwordx4 v[226:227], off
	s_waitcnt vmcnt(8) lgkmcnt(0)
	s_barrier
	s_setprio 1
	v_mfma_f32_16x16x32_bf16 v[60:63], v[96:99], v[178:181], 0
	v_mfma_f32_16x16x32_bf16 v[56:59], v[120:123], v[178:181], 0
	v_mfma_f32_16x16x32_bf16 v[44:47], v[96:99], v[186:189], 0
	v_mfma_f32_16x16x32_bf16 v[40:43], v[120:123], v[186:189], 0
	v_mfma_f32_16x16x32_bf16 v[28:31], v[96:99], v[194:197], 0
	v_mfma_f32_16x16x32_bf16 v[24:27], v[120:123], v[194:197], 0
	v_mfma_f32_16x16x32_bf16 v[12:15], v[96:99], v[202:205], 0
	v_mfma_f32_16x16x32_bf16 v[8:11], v[120:123], v[202:205], 0
	v_mfma_f32_16x16x32_bf16 v[60:63], v[100:103], v[182:185], v[60:63]
	v_mfma_f32_16x16x32_bf16 v[56:59], v[124:127], v[182:185], v[56:59]
	v_mfma_f32_16x16x32_bf16 v[44:47], v[100:103], v[190:193], v[44:47]
	v_mfma_f32_16x16x32_bf16 v[40:43], v[124:127], v[190:193], v[40:43]
	v_mfma_f32_16x16x32_bf16 v[28:31], v[100:103], v[198:201], v[28:31]
	v_mfma_f32_16x16x32_bf16 v[24:27], v[124:127], v[198:201], v[24:27]
	v_mfma_f32_16x16x32_bf16 v[12:15], v[100:103], v[218:221], v[12:15]
	v_mfma_f32_16x16x32_bf16 v[8:11], v[124:127], v[218:221], v[8:11]
	s_setprio 0
	s_setprio 1
	v_mfma_f32_16x16x32_bf16 v[52:55], v[144:147], v[178:181], 0
	v_mfma_f32_16x16x32_bf16 v[48:51], v[152:155], v[178:181], 0
	v_mfma_f32_16x16x32_bf16 v[36:39], v[144:147], v[186:189], 0
	v_mfma_f32_16x16x32_bf16 v[32:35], v[152:155], v[186:189], 0
	v_mfma_f32_16x16x32_bf16 v[20:23], v[144:147], v[194:197], 0
	v_mfma_f32_16x16x32_bf16 v[16:19], v[152:155], v[194:197], 0
	v_mfma_f32_16x16x32_bf16 v[4:7], v[144:147], v[202:205], 0
	v_mfma_f32_16x16x32_bf16 v[0:3], v[152:155], v[202:205], 0
	v_mfma_f32_16x16x32_bf16 v[52:55], v[148:151], v[182:185], v[52:55]
	v_mfma_f32_16x16x32_bf16 v[48:51], v[156:159], v[182:185], v[48:51]
	v_mfma_f32_16x16x32_bf16 v[36:39], v[148:151], v[190:193], v[36:39]
	v_mfma_f32_16x16x32_bf16 v[32:35], v[156:159], v[190:193], v[32:35]
	s_setprio 2
	s_barrier
	v_mfma_f32_16x16x32_bf16 v[20:23], v[148:151], v[198:201], v[20:23]
	v_mfma_f32_16x16x32_bf16 v[16:19], v[156:159], v[198:201], v[16:19]
	v_mfma_f32_16x16x32_bf16 v[4:7], v[148:151], v[218:221], v[4:7]
	v_mfma_f32_16x16x32_bf16 v[0:3], v[156:159], v[218:221], v[0:3]
	s_setprio 0
	s_add_i32 s79, 0, 0x18000
	s_add_i32 s80, 0, 0x1c000
	v_add_u32_e32 v124, s79, v208
	v_add_u32_e32 v156, s80, v208
	ds_read_b128 v[96:99], v124
	ds_read_b128 v[100:103], v124 offset:1024
	ds_read_b128 v[120:123], v124 offset:2048
	ds_read_b128 v[124:127], v124 offset:3072
	ds_read_b128 v[144:147], v156
	ds_read_b128 v[148:151], v156 offset:1024
	ds_read_b128 v[152:155], v156 offset:2048
	ds_read_b128 v[156:159], v156 offset:3072
	s_add_u32 s50, s50, 0x40000
	s_addc_u32 s51, s51, 0
	s_mov_b32 m0, s63
	v_lshl_add_u64 v[228:229], s[50:51], 0, v[160:161]
	ds_read_b128 v[178:181], v211 offset:32768
	ds_read_b128 v[182:185], v211 offset:33792
	ds_read_b128 v[186:189], v211 offset:34816
	ds_read_b128 v[190:193], v211 offset:35840
	ds_read_b128 v[194:197], v211 offset:36864
	ds_read_b128 v[198:201], v211 offset:37888
	ds_read_b128 v[202:205], v211 offset:38912
	ds_read_b128 v[218:221], v211 offset:39936
	global_load_lds_dwordx4 v[228:229], off
	s_mov_b32 m0, s64
	v_lshl_add_u64 v[228:229], s[50:51], 0, v[164:165]
	global_load_lds_dwordx4 v[228:229], off
	s_waitcnt vmcnt(8) lgkmcnt(0)
	s_barrier
	s_setprio 1
	v_mfma_f32_16x16x32_bf16 v[140:143], v[96:99], v[178:181], v[140:143]
	v_mfma_f32_16x16x32_bf16 v[136:139], v[120:123], v[178:181], v[136:139]
	v_mfma_f32_16x16x32_bf16 v[116:119], v[96:99], v[186:189], v[116:119]
	v_mfma_f32_16x16x32_bf16 v[112:115], v[120:123], v[186:189], v[112:115]
	v_mfma_f32_16x16x32_bf16 v[92:95], v[96:99], v[194:197], v[92:95]
	v_mfma_f32_16x16x32_bf16 v[88:91], v[120:123], v[194:197], v[88:91]
	v_mfma_f32_16x16x32_bf16 v[76:79], v[96:99], v[202:205], v[76:79]
	v_mfma_f32_16x16x32_bf16 v[72:75], v[120:123], v[202:205], v[72:75]
	v_mfma_f32_16x16x32_bf16 v[140:143], v[100:103], v[182:185], v[140:143]
	v_mfma_f32_16x16x32_bf16 v[136:139], v[124:127], v[182:185], v[136:139]
	v_mfma_f32_16x16x32_bf16 v[116:119], v[100:103], v[190:193], v[116:119]
	v_mfma_f32_16x16x32_bf16 v[112:115], v[124:127], v[190:193], v[112:115]
	v_mfma_f32_16x16x32_bf16 v[92:95], v[100:103], v[198:201], v[92:95]
	v_mfma_f32_16x16x32_bf16 v[88:91], v[124:127], v[198:201], v[88:91]
	v_mfma_f32_16x16x32_bf16 v[76:79], v[100:103], v[218:221], v[76:79]
	v_mfma_f32_16x16x32_bf16 v[72:75], v[124:127], v[218:221], v[72:75]
	s_setprio 0
	s_setprio 1
	v_mfma_f32_16x16x32_bf16 v[132:135], v[144:147], v[178:181], v[132:135]
	v_mfma_f32_16x16x32_bf16 v[128:131], v[152:155], v[178:181], v[128:131]
	v_mfma_f32_16x16x32_bf16 v[108:111], v[144:147], v[186:189], v[108:111]
	v_mfma_f32_16x16x32_bf16 v[104:107], v[152:155], v[186:189], v[104:107]
	v_mfma_f32_16x16x32_bf16 v[84:87], v[144:147], v[194:197], v[84:87]
	v_mfma_f32_16x16x32_bf16 v[80:83], v[152:155], v[194:197], v[80:83]
	v_mfma_f32_16x16x32_bf16 v[68:71], v[144:147], v[202:205], v[68:71]
	v_mfma_f32_16x16x32_bf16 v[64:67], v[152:155], v[202:205], v[64:67]
	v_mfma_f32_16x16x32_bf16 v[132:135], v[148:151], v[182:185], v[132:135]
	v_mfma_f32_16x16x32_bf16 v[128:131], v[156:159], v[182:185], v[128:131]
	v_mfma_f32_16x16x32_bf16 v[108:111], v[148:151], v[190:193], v[108:111]
	v_mfma_f32_16x16x32_bf16 v[104:107], v[156:159], v[190:193], v[104:107]
	s_setprio 2
	s_barrier
	v_mfma_f32_16x16x32_bf16 v[84:87], v[148:151], v[198:201], v[84:87]
	v_mfma_f32_16x16x32_bf16 v[80:83], v[156:159], v[198:201], v[80:83]
	v_mfma_f32_16x16x32_bf16 v[68:71], v[148:151], v[218:221], v[68:71]
	v_mfma_f32_16x16x32_bf16 v[64:67], v[156:159], v[218:221], v[64:67]
	s_setprio 2
	s_add_i32 s50, s79, s61
	v_lshl_add_u64 v[206:207], v[206:207], 0, s[36:37]
	s_mov_b32 m0, s50
	ds_read_b128 v[178:181], v211 offset:49152
	ds_read_b128 v[182:185], v211 offset:50176
	ds_read_b128 v[186:189], v211 offset:51200
	ds_read_b128 v[190:193], v211 offset:52224
	ds_read_b128 v[194:197], v211 offset:53248
	ds_read_b128 v[198:201], v211 offset:54272
	ds_read_b128 v[202:205], v211 offset:55296
	ds_read_b128 v[218:221], v211 offset:56320
	global_load_lds_dwordx4 v[206:207], off
	s_add_i32 m0, s50, 0x2000
	s_add_u32 s8, s8, 0x40080
	v_lshl_add_u64 v[206:207], v[222:223], 0, s[36:37]
	s_addc_u32 s9, s9, 0
	s_add_i32 s50, s80, s61
	global_load_lds_dwordx4 v[206:207], off
	s_mov_b32 m0, s50
	v_lshl_add_u64 v[206:207], s[8:9], 0, v[162:163]
	global_load_lds_dwordx4 v[206:207], off
	s_add_i32 m0, s50, 0x2000
	v_lshl_add_u64 v[206:207], s[8:9], 0, v[166:167]
	global_load_lds_dwordx4 v[206:207], off
	s_mov_b32 m0, s68
	v_lshl_add_u64 v[206:207], v[224:225], 0, s[36:37]
	global_load_lds_dwordx4 v[206:207], off
	s_mov_b32 m0, s69
	v_lshl_add_u64 v[206:207], v[226:227], 0, s[36:37]
	global_load_lds_dwordx4 v[206:207], off
	s_waitcnt vmcnt(8) lgkmcnt(0)
	s_barrier
	s_setprio 1
	v_mfma_f32_16x16x32_bf16 v[60:63], v[96:99], v[178:181], v[60:63]
	v_mfma_f32_16x16x32_bf16 v[56:59], v[120:123], v[178:181], v[56:59]
	v_mfma_f32_16x16x32_bf16 v[44:47], v[96:99], v[186:189], v[44:47]
	v_mfma_f32_16x16x32_bf16 v[40:43], v[120:123], v[186:189], v[40:43]
	v_mfma_f32_16x16x32_bf16 v[28:31], v[96:99], v[194:197], v[28:31]
	v_mfma_f32_16x16x32_bf16 v[24:27], v[120:123], v[194:197], v[24:27]
	v_mfma_f32_16x16x32_bf16 v[12:15], v[96:99], v[202:205], v[12:15]
	v_mfma_f32_16x16x32_bf16 v[8:11], v[120:123], v[202:205], v[8:11]
	v_mfma_f32_16x16x32_bf16 v[60:63], v[100:103], v[182:185], v[60:63]
	v_mfma_f32_16x16x32_bf16 v[56:59], v[124:127], v[182:185], v[56:59]
	v_mfma_f32_16x16x32_bf16 v[44:47], v[100:103], v[190:193], v[44:47]
	v_mfma_f32_16x16x32_bf16 v[40:43], v[124:127], v[190:193], v[40:43]
	v_mfma_f32_16x16x32_bf16 v[28:31], v[100:103], v[198:201], v[28:31]
	v_mfma_f32_16x16x32_bf16 v[24:27], v[124:127], v[198:201], v[24:27]
	v_mfma_f32_16x16x32_bf16 v[12:15], v[100:103], v[218:221], v[12:15]
	v_mfma_f32_16x16x32_bf16 v[8:11], v[124:127], v[218:221], v[8:11]
	s_setprio 0
	s_setprio 1
	v_mfma_f32_16x16x32_bf16 v[52:55], v[144:147], v[178:181], v[52:55]
	v_mfma_f32_16x16x32_bf16 v[48:51], v[152:155], v[178:181], v[48:51]
	v_mfma_f32_16x16x32_bf16 v[36:39], v[144:147], v[186:189], v[36:39]
	v_mfma_f32_16x16x32_bf16 v[32:35], v[152:155], v[186:189], v[32:35]
	v_mfma_f32_16x16x32_bf16 v[20:23], v[144:147], v[194:197], v[20:23]
	v_mfma_f32_16x16x32_bf16 v[16:19], v[152:155], v[194:197], v[16:19]
	v_mfma_f32_16x16x32_bf16 v[4:7], v[144:147], v[202:205], v[4:7]
	v_mfma_f32_16x16x32_bf16 v[0:3], v[152:155], v[202:205], v[0:3]
	v_mfma_f32_16x16x32_bf16 v[52:55], v[148:151], v[182:185], v[52:55]
	v_mfma_f32_16x16x32_bf16 v[48:51], v[156:159], v[182:185], v[48:51]
	v_mfma_f32_16x16x32_bf16 v[36:39], v[148:151], v[190:193], v[36:39]
	v_mfma_f32_16x16x32_bf16 v[32:35], v[156:159], v[190:193], v[32:35]
	s_setprio 2
	s_barrier
	v_mfma_f32_16x16x32_bf16 v[20:23], v[148:151], v[198:201], v[20:23]
	v_mfma_f32_16x16x32_bf16 v[16:19], v[156:159], v[198:201], v[16:19]
	v_mfma_f32_16x16x32_bf16 v[4:7], v[148:151], v[218:221], v[4:7]
	v_mfma_f32_16x16x32_bf16 v[0:3], v[156:159], v[218:221], v[0:3]
	s_setprio 0
	s_add_i32 s78, s78, 2
	s_add_u32 s6, s6, 0x100
	s_addc_u32 s7, s7, 0
	s_add_u32 s56, s56, 0x100
	s_addc_u32 s57, s57, 0
	s_cmp_gt_u32 s78, 13
.LBB0_323:
	ds_read_b128 v[96:99], v209
	ds_read_b128 v[100:103], v209 offset:1024
	ds_read_b128 v[120:123], v209 offset:2048
	ds_read_b128 v[124:127], v209 offset:3072
	ds_read_b128 v[144:147], v210
	ds_read_b128 v[148:151], v210 offset:1024
	ds_read_b128 v[152:155], v210 offset:2048
	ds_read_b128 v[156:159], v210 offset:3072
	s_add_u32 s8, s6, 0xfffc0080
	s_addc_u32 s9, s7, -1
	s_cmp_eq_u32 s78, 12
	s_cselect_b32 s51, s18, s9
	s_cselect_b32 s50, s43, s8
	s_cselect_b32 s9, s45, s57
	s_cselect_b32 s8, s55, s56
	v_lshl_add_u64 v[206:207], s[6:7], 0, v[170:171]
	s_add_i32 m0, s17, 0xc000
	ds_read_b128 v[178:181], v211
	ds_read_b128 v[182:185], v211 offset:1024
	ds_read_b128 v[186:189], v211 offset:2048
	ds_read_b128 v[190:193], v211 offset:3072
	ds_read_b128 v[194:197], v211 offset:4096
	ds_read_b128 v[198:201], v211 offset:5120
	ds_read_b128 v[202:205], v211 offset:6144
	ds_read_b128 v[218:221], v211 offset:7168
	global_load_lds_dwordx4 v[206:207], off
	s_add_i32 m0, s17, 0xe000
	v_lshl_add_u64 v[206:207], s[6:7], 0, v[172:173]
	global_load_lds_dwordx4 v[206:207], off
	s_waitcnt vmcnt(8) lgkmcnt(0)
	s_barrier
	s_setprio 1
	v_mfma_f32_16x16x32_bf16 v[140:143], v[96:99], v[178:181], v[140:143]
	v_mfma_f32_16x16x32_bf16 v[136:139], v[120:123], v[178:181], v[136:139]
	v_mfma_f32_16x16x32_bf16 v[116:119], v[96:99], v[186:189], v[116:119]
	v_mfma_f32_16x16x32_bf16 v[112:115], v[120:123], v[186:189], v[112:115]
	v_mfma_f32_16x16x32_bf16 v[92:95], v[96:99], v[194:197], v[92:95]
	v_mfma_f32_16x16x32_bf16 v[88:91], v[120:123], v[194:197], v[88:91]
	v_mfma_f32_16x16x32_bf16 v[76:79], v[96:99], v[202:205], v[76:79]
	v_mfma_f32_16x16x32_bf16 v[72:75], v[120:123], v[202:205], v[72:75]
	v_mfma_f32_16x16x32_bf16 v[140:143], v[100:103], v[182:185], v[140:143]
	v_mfma_f32_16x16x32_bf16 v[136:139], v[124:127], v[182:185], v[136:139]
	v_mfma_f32_16x16x32_bf16 v[116:119], v[100:103], v[190:193], v[116:119]
	v_mfma_f32_16x16x32_bf16 v[112:115], v[124:127], v[190:193], v[112:115]
	v_mfma_f32_16x16x32_bf16 v[92:95], v[100:103], v[198:201], v[92:95]
	v_mfma_f32_16x16x32_bf16 v[88:91], v[124:127], v[198:201], v[88:91]
	v_mfma_f32_16x16x32_bf16 v[76:79], v[100:103], v[218:221], v[76:79]
	v_mfma_f32_16x16x32_bf16 v[72:75], v[124:127], v[218:221], v[72:75]
	s_setprio 0
	s_setprio 1
	v_mfma_f32_16x16x32_bf16 v[132:135], v[144:147], v[178:181], v[132:135]
	v_mfma_f32_16x16x32_bf16 v[128:131], v[152:155], v[178:181], v[128:131]
	v_mfma_f32_16x16x32_bf16 v[108:111], v[144:147], v[186:189], v[108:111]
	v_mfma_f32_16x16x32_bf16 v[104:107], v[152:155], v[186:189], v[104:107]
	v_mfma_f32_16x16x32_bf16 v[84:87], v[144:147], v[194:197], v[84:87]
	v_mfma_f32_16x16x32_bf16 v[80:83], v[152:155], v[194:197], v[80:83]
	v_mfma_f32_16x16x32_bf16 v[68:71], v[144:147], v[202:205], v[68:71]
	v_mfma_f32_16x16x32_bf16 v[64:67], v[152:155], v[202:205], v[64:67]
	v_mfma_f32_16x16x32_bf16 v[132:135], v[148:151], v[182:185], v[132:135]
	v_mfma_f32_16x16x32_bf16 v[128:131], v[156:159], v[182:185], v[128:131]
	v_mfma_f32_16x16x32_bf16 v[108:111], v[148:151], v[190:193], v[108:111]
	v_mfma_f32_16x16x32_bf16 v[104:107], v[156:159], v[190:193], v[104:107]
	s_setprio 2
	s_barrier
	v_mfma_f32_16x16x32_bf16 v[84:87], v[148:151], v[198:201], v[84:87]
	v_mfma_f32_16x16x32_bf16 v[80:83], v[156:159], v[198:201], v[80:83]
	v_mfma_f32_16x16x32_bf16 v[68:71], v[148:151], v[218:221], v[68:71]
	v_mfma_f32_16x16x32_bf16 v[64:67], v[156:159], v[218:221], v[64:67]
	s_setprio 2
	s_add_i32 s79, s73, s61
	v_lshl_add_u64 v[206:207], s[8:9], 0, v[162:163]
	s_mov_b32 m0, s79
	ds_read_b128 v[178:181], v211 offset:16384
	ds_read_b128 v[182:185], v211 offset:17408
	ds_read_b128 v[186:189], v211 offset:18432
	ds_read_b128 v[190:193], v211 offset:19456
	ds_read_b128 v[194:197], v211 offset:20480
	ds_read_b128 v[198:201], v211 offset:21504
	ds_read_b128 v[202:205], v211 offset:22528
	ds_read_b128 v[218:221], v211 offset:23552
	global_load_lds_dwordx4 v[206:207], off
	s_add_i32 m0, s79, 0x2000
	s_add_u32 s80, s8, 0x40000
	v_lshl_add_u64 v[222:223], s[8:9], 0, v[166:167]
	s_addc_u32 s81, s9, 0
	s_add_i32 s79, s74, s61
	global_load_lds_dwordx4 v[222:223], off
	v_lshl_add_u64 v[224:225], s[80:81], 0, v[162:163]
	s_mov_b32 m0, s79
	v_lshl_add_u64 v[226:227], s[50:51], 0, v[164:165]
	global_load_lds_dwordx4 v[224:225], off
	s_add_i32 m0, s79, 0x2000
	v_lshl_add_u64 v[224:225], s[80:81], 0, v[166:167]
	global_load_lds_dwordx4 v[224:225], off
	s_mov_b32 m0, s17
	v_lshl_add_u64 v[224:225], s[50:51], 0, v[160:161]
	global_load_lds_dwordx4 v[224:225], off
	s_mov_b32 m0, s62
	s_nop 0
	global_load_lds_dwordx4 v[226:227], off
	s_waitcnt vmcnt(8) lgkmcnt(0)
	s_barrier
	s_setprio 1
	v_mfma_f32_16x16x32_bf16 v[60:63], v[96:99], v[178:181], v[60:63]
	v_mfma_f32_16x16x32_bf16 v[56:59], v[120:123], v[178:181], v[56:59]
	v_mfma_f32_16x16x32_bf16 v[44:47], v[96:99], v[186:189], v[44:47]
	v_mfma_f32_16x16x32_bf16 v[40:43], v[120:123], v[186:189], v[40:43]
	v_mfma_f32_16x16x32_bf16 v[28:31], v[96:99], v[194:197], v[28:31]
	v_mfma_f32_16x16x32_bf16 v[24:27], v[120:123], v[194:197], v[24:27]
	v_mfma_f32_16x16x32_bf16 v[12:15], v[96:99], v[202:205], v[12:15]
	v_mfma_f32_16x16x32_bf16 v[8:11], v[120:123], v[202:205], v[8:11]
	v_mfma_f32_16x16x32_bf16 v[60:63], v[100:103], v[182:185], v[60:63]
	v_mfma_f32_16x16x32_bf16 v[56:59], v[124:127], v[182:185], v[56:59]
	v_mfma_f32_16x16x32_bf16 v[44:47], v[100:103], v[190:193], v[44:47]
	v_mfma_f32_16x16x32_bf16 v[40:43], v[124:127], v[190:193], v[40:43]
	v_mfma_f32_16x16x32_bf16 v[28:31], v[100:103], v[198:201], v[28:31]
	v_mfma_f32_16x16x32_bf16 v[24:27], v[124:127], v[198:201], v[24:27]
	v_mfma_f32_16x16x32_bf16 v[12:15], v[100:103], v[218:221], v[12:15]
	v_mfma_f32_16x16x32_bf16 v[8:11], v[124:127], v[218:221], v[8:11]
	s_setprio 0
	s_setprio 1
	v_mfma_f32_16x16x32_bf16 v[52:55], v[144:147], v[178:181], v[52:55]
	v_mfma_f32_16x16x32_bf16 v[48:51], v[152:155], v[178:181], v[48:51]
	v_mfma_f32_16x16x32_bf16 v[36:39], v[144:147], v[186:189], v[36:39]
	v_mfma_f32_16x16x32_bf16 v[32:35], v[152:155], v[186:189], v[32:35]
	v_mfma_f32_16x16x32_bf16 v[20:23], v[144:147], v[194:197], v[20:23]
	v_mfma_f32_16x16x32_bf16 v[16:19], v[152:155], v[194:197], v[16:19]
	v_mfma_f32_16x16x32_bf16 v[4:7], v[144:147], v[202:205], v[4:7]
	v_mfma_f32_16x16x32_bf16 v[0:3], v[152:155], v[202:205], v[0:3]
	v_mfma_f32_16x16x32_bf16 v[52:55], v[148:151], v[182:185], v[52:55]
	v_mfma_f32_16x16x32_bf16 v[48:51], v[156:159], v[182:185], v[48:51]
	v_mfma_f32_16x16x32_bf16 v[36:39], v[148:151], v[190:193], v[36:39]
	v_mfma_f32_16x16x32_bf16 v[32:35], v[156:159], v[190:193], v[32:35]
	s_setprio 2
	s_barrier
	v_mfma_f32_16x16x32_bf16 v[20:23], v[148:151], v[198:201], v[20:23]
	v_mfma_f32_16x16x32_bf16 v[16:19], v[156:159], v[198:201], v[16:19]
	v_mfma_f32_16x16x32_bf16 v[4:7], v[148:151], v[218:221], v[4:7]
	v_mfma_f32_16x16x32_bf16 v[0:3], v[156:159], v[218:221], v[0:3]
	s_setprio 0
	s_add_i32 s79, 0, 0x18000
	s_add_i32 s80, 0, 0x1c000
	v_add_u32_e32 v124, s79, v208
	v_add_u32_e32 v156, s80, v208
	ds_read_b128 v[96:99], v124
	ds_read_b128 v[100:103], v124 offset:1024
	ds_read_b128 v[120:123], v124 offset:2048
	ds_read_b128 v[124:127], v124 offset:3072
	ds_read_b128 v[144:147], v156
	ds_read_b128 v[148:151], v156 offset:1024
	ds_read_b128 v[152:155], v156 offset:2048
	ds_read_b128 v[156:159], v156 offset:3072
	s_add_u32 s50, s50, 0x40000
	s_addc_u32 s51, s51, 0
	s_mov_b32 m0, s63
	v_lshl_add_u64 v[228:229], s[50:51], 0, v[160:161]
	ds_read_b128 v[178:181], v211 offset:32768
	ds_read_b128 v[182:185], v211 offset:33792
	ds_read_b128 v[186:189], v211 offset:34816
	ds_read_b128 v[190:193], v211 offset:35840
	ds_read_b128 v[194:197], v211 offset:36864
	ds_read_b128 v[198:201], v211 offset:37888
	ds_read_b128 v[202:205], v211 offset:38912
	ds_read_b128 v[218:221], v211 offset:39936
	global_load_lds_dwordx4 v[228:229], off
	s_mov_b32 m0, s64
	v_lshl_add_u64 v[228:229], s[50:51], 0, v[164:165]
	global_load_lds_dwordx4 v[228:229], off
	s_waitcnt vmcnt(8) lgkmcnt(0)
	s_barrier
	s_setprio 1
	v_mfma_f32_16x16x32_bf16 v[140:143], v[96:99], v[178:181], v[140:143]
	v_mfma_f32_16x16x32_bf16 v[136:139], v[120:123], v[178:181], v[136:139]
	v_mfma_f32_16x16x32_bf16 v[116:119], v[96:99], v[186:189], v[116:119]
	v_mfma_f32_16x16x32_bf16 v[112:115], v[120:123], v[186:189], v[112:115]
	v_mfma_f32_16x16x32_bf16 v[92:95], v[96:99], v[194:197], v[92:95]
	v_mfma_f32_16x16x32_bf16 v[88:91], v[120:123], v[194:197], v[88:91]
	v_mfma_f32_16x16x32_bf16 v[76:79], v[96:99], v[202:205], v[76:79]
	v_mfma_f32_16x16x32_bf16 v[72:75], v[120:123], v[202:205], v[72:75]
	v_mfma_f32_16x16x32_bf16 v[140:143], v[100:103], v[182:185], v[140:143]
	v_mfma_f32_16x16x32_bf16 v[136:139], v[124:127], v[182:185], v[136:139]
	v_mfma_f32_16x16x32_bf16 v[116:119], v[100:103], v[190:193], v[116:119]
	v_mfma_f32_16x16x32_bf16 v[112:115], v[124:127], v[190:193], v[112:115]
	v_mfma_f32_16x16x32_bf16 v[92:95], v[100:103], v[198:201], v[92:95]
	v_mfma_f32_16x16x32_bf16 v[88:91], v[124:127], v[198:201], v[88:91]
	v_mfma_f32_16x16x32_bf16 v[76:79], v[100:103], v[218:221], v[76:79]
	v_mfma_f32_16x16x32_bf16 v[72:75], v[124:127], v[218:221], v[72:75]
	s_setprio 0
	s_setprio 1
	v_mfma_f32_16x16x32_bf16 v[132:135], v[144:147], v[178:181], v[132:135]
	v_mfma_f32_16x16x32_bf16 v[128:131], v[152:155], v[178:181], v[128:131]
	v_mfma_f32_16x16x32_bf16 v[108:111], v[144:147], v[186:189], v[108:111]
	v_mfma_f32_16x16x32_bf16 v[104:107], v[152:155], v[186:189], v[104:107]
	v_mfma_f32_16x16x32_bf16 v[84:87], v[144:147], v[194:197], v[84:87]
	v_mfma_f32_16x16x32_bf16 v[80:83], v[152:155], v[194:197], v[80:83]
	v_mfma_f32_16x16x32_bf16 v[68:71], v[144:147], v[202:205], v[68:71]
	v_mfma_f32_16x16x32_bf16 v[64:67], v[152:155], v[202:205], v[64:67]
	v_mfma_f32_16x16x32_bf16 v[132:135], v[148:151], v[182:185], v[132:135]
	v_mfma_f32_16x16x32_bf16 v[128:131], v[156:159], v[182:185], v[128:131]
	v_mfma_f32_16x16x32_bf16 v[108:111], v[148:151], v[190:193], v[108:111]
	v_mfma_f32_16x16x32_bf16 v[104:107], v[156:159], v[190:193], v[104:107]
	s_setprio 2
	s_barrier
	v_mfma_f32_16x16x32_bf16 v[84:87], v[148:151], v[198:201], v[84:87]
	v_mfma_f32_16x16x32_bf16 v[80:83], v[156:159], v[198:201], v[80:83]
	v_mfma_f32_16x16x32_bf16 v[68:71], v[148:151], v[218:221], v[68:71]
	v_mfma_f32_16x16x32_bf16 v[64:67], v[156:159], v[218:221], v[64:67]
	s_setprio 2
	s_add_i32 s50, s79, s61
	v_lshl_add_u64 v[206:207], v[206:207], 0, s[36:37]
	s_mov_b32 m0, s50
	ds_read_b128 v[178:181], v211 offset:49152
	ds_read_b128 v[182:185], v211 offset:50176
	ds_read_b128 v[186:189], v211 offset:51200
	ds_read_b128 v[190:193], v211 offset:52224
	ds_read_b128 v[194:197], v211 offset:53248
	ds_read_b128 v[198:201], v211 offset:54272
	ds_read_b128 v[202:205], v211 offset:55296
	ds_read_b128 v[218:221], v211 offset:56320
	global_load_lds_dwordx4 v[206:207], off
	s_add_i32 m0, s50, 0x2000
	s_add_u32 s8, s8, 0x40080
	v_lshl_add_u64 v[206:207], v[222:223], 0, s[36:37]
	s_addc_u32 s9, s9, 0
	s_add_i32 s50, s80, s61
	global_load_lds_dwordx4 v[206:207], off
	s_mov_b32 m0, s50
	v_lshl_add_u64 v[206:207], s[8:9], 0, v[162:163]
	global_load_lds_dwordx4 v[206:207], off
	s_add_i32 m0, s50, 0x2000
	v_lshl_add_u64 v[206:207], s[8:9], 0, v[166:167]
	global_load_lds_dwordx4 v[206:207], off
	s_mov_b32 m0, s68
	v_lshl_add_u64 v[206:207], v[224:225], 0, s[36:37]
	global_load_lds_dwordx4 v[206:207], off
	s_mov_b32 m0, s69
	v_lshl_add_u64 v[206:207], v[226:227], 0, s[36:37]
	global_load_lds_dwordx4 v[206:207], off
	s_waitcnt vmcnt(8) lgkmcnt(0)
	s_barrier
	s_setprio 1
	v_mfma_f32_16x16x32_bf16 v[60:63], v[96:99], v[178:181], v[60:63]
	v_mfma_f32_16x16x32_bf16 v[56:59], v[120:123], v[178:181], v[56:59]
	v_mfma_f32_16x16x32_bf16 v[44:47], v[96:99], v[186:189], v[44:47]
	v_mfma_f32_16x16x32_bf16 v[40:43], v[120:123], v[186:189], v[40:43]
	v_mfma_f32_16x16x32_bf16 v[28:31], v[96:99], v[194:197], v[28:31]
	v_mfma_f32_16x16x32_bf16 v[24:27], v[120:123], v[194:197], v[24:27]
	v_mfma_f32_16x16x32_bf16 v[12:15], v[96:99], v[202:205], v[12:15]
	v_mfma_f32_16x16x32_bf16 v[8:11], v[120:123], v[202:205], v[8:11]
	v_mfma_f32_16x16x32_bf16 v[60:63], v[100:103], v[182:185], v[60:63]
	v_mfma_f32_16x16x32_bf16 v[56:59], v[124:127], v[182:185], v[56:59]
	v_mfma_f32_16x16x32_bf16 v[44:47], v[100:103], v[190:193], v[44:47]
	v_mfma_f32_16x16x32_bf16 v[40:43], v[124:127], v[190:193], v[40:43]
	v_mfma_f32_16x16x32_bf16 v[28:31], v[100:103], v[198:201], v[28:31]
	v_mfma_f32_16x16x32_bf16 v[24:27], v[124:127], v[198:201], v[24:27]
	v_mfma_f32_16x16x32_bf16 v[12:15], v[100:103], v[218:221], v[12:15]
	v_mfma_f32_16x16x32_bf16 v[8:11], v[124:127], v[218:221], v[8:11]
	s_setprio 0
	s_setprio 1
	v_mfma_f32_16x16x32_bf16 v[52:55], v[144:147], v[178:181], v[52:55]
	v_mfma_f32_16x16x32_bf16 v[48:51], v[152:155], v[178:181], v[48:51]
	v_mfma_f32_16x16x32_bf16 v[36:39], v[144:147], v[186:189], v[36:39]
	v_mfma_f32_16x16x32_bf16 v[32:35], v[152:155], v[186:189], v[32:35]
	v_mfma_f32_16x16x32_bf16 v[20:23], v[144:147], v[194:197], v[20:23]
	v_mfma_f32_16x16x32_bf16 v[16:19], v[152:155], v[194:197], v[16:19]
	v_mfma_f32_16x16x32_bf16 v[4:7], v[144:147], v[202:205], v[4:7]
	v_mfma_f32_16x16x32_bf16 v[0:3], v[152:155], v[202:205], v[0:3]
	v_mfma_f32_16x16x32_bf16 v[52:55], v[148:151], v[182:185], v[52:55]
	v_mfma_f32_16x16x32_bf16 v[48:51], v[156:159], v[182:185], v[48:51]
	v_mfma_f32_16x16x32_bf16 v[36:39], v[148:151], v[190:193], v[36:39]
	v_mfma_f32_16x16x32_bf16 v[32:35], v[156:159], v[190:193], v[32:35]
	s_setprio 2
	s_barrier
	v_mfma_f32_16x16x32_bf16 v[20:23], v[148:151], v[198:201], v[20:23]
	v_mfma_f32_16x16x32_bf16 v[16:19], v[156:159], v[198:201], v[16:19]
	v_mfma_f32_16x16x32_bf16 v[4:7], v[148:151], v[218:221], v[4:7]
	v_mfma_f32_16x16x32_bf16 v[0:3], v[156:159], v[218:221], v[0:3]
	s_setprio 0
	s_add_i32 s78, s78, 2
	s_add_u32 s6, s6, 0x100
	s_addc_u32 s7, s7, 0
	s_add_u32 s56, s56, 0x100
	s_addc_u32 s57, s57, 0
	s_cmp_gt_u32 s78, 13
	s_cbranch_scc0 .LBB0_323

.LBB0_697:
	s_and_b32 s29, s69, 0x1000
	s_add_i32 s70, s66, s29
	s_ashr_i32 s29, s28, 31
	ds_read_b128 v[0:3], v195 offset:3072
	ds_read_b128 v[4:7], v195 offset:2048
	ds_read_b128 v[8:11], v195 offset:1024
	ds_read_b128 v[12:15], v195
	ds_read_b128 v[16:19], v203 offset:3072
	ds_read_b128 v[20:23], v203 offset:2048
	ds_read_b128 v[24:27], v203 offset:1024
	ds_read_b128 v[28:31], v203
	s_lshl_b64 s[36:37], s[28:29], 20
	s_add_u32 s36, s50, s36
	s_addc_u32 s37, s51, s37
	s_and_b64 s[38:39], s[4:5], exec
	s_cselect_b32 s29, s37, s45
	s_cselect_b32 s71, s36, s44
	s_ashr_i32 s31, s30, 31
	s_lshl_b64 s[38:39], s[30:31], 20
	s_add_u32 s38, s54, s38
	s_addc_u32 s39, s55, s39
	s_and_b64 s[48:49], s[4:5], exec
	s_cselect_b32 s31, s39, s47
	s_cselect_b32 s72, s38, s46
	s_add_u32 s48, s44, 0x80080
	s_addc_u32 s49, s45, 0
	s_add_i32 s73, s56, 0xc000
	v_lshl_add_u64 v[64:65], s[48:49], 0, v[176:177]
	s_mov_b32 m0, s73
	s_add_i32 s74, s56, 0xe000
	ds_read_b128 v[32:35], v211
	ds_read_b128 v[36:39], v211 offset:1024
	ds_read_b128 v[40:43], v211 offset:2048
	ds_read_b128 v[44:47], v211 offset:3072
	ds_read_b128 v[48:51], v211 offset:4096
	ds_read_b128 v[52:55], v211 offset:5120
	ds_read_b128 v[56:59], v211 offset:6144
	ds_read_b128 v[60:63], v211 offset:7168
	global_load_lds_dwordx4 v[64:65], off
	s_mov_b32 m0, s74
	v_lshl_add_u64 v[64:65], s[48:49], 0, v[178:179]
	global_load_lds_dwordx4 v[64:65], off
	s_waitcnt vmcnt(8) lgkmcnt(0)
	s_barrier
	s_setprio 1
	v_mfma_f32_16x16x32_bf16 v[88:91], v[28:31], v[56:59], 0
	v_mfma_f32_16x16x32_bf16 v[64:67], v[28:31], v[32:35], 0
	v_mfma_f32_16x16x32_bf16 v[68:71], v[20:23], v[32:35], 0
	v_mfma_f32_16x16x32_bf16 v[72:75], v[28:31], v[40:43], 0
	v_mfma_f32_16x16x32_bf16 v[76:79], v[20:23], v[40:43], 0
	v_mfma_f32_16x16x32_bf16 v[80:83], v[28:31], v[48:51], 0
	v_mfma_f32_16x16x32_bf16 v[84:87], v[20:23], v[48:51], 0
	v_mfma_f32_16x16x32_bf16 v[96:99], v[24:27], v[60:63], v[88:91]
	v_mfma_f32_16x16x32_bf16 v[88:91], v[20:23], v[56:59], 0
	v_mfma_f32_16x16x32_bf16 v[64:67], v[24:27], v[36:39], v[64:67]
	v_mfma_f32_16x16x32_bf16 v[68:71], v[16:19], v[36:39], v[68:71]
	v_mfma_f32_16x16x32_bf16 v[72:75], v[24:27], v[44:47], v[72:75]
	v_mfma_f32_16x16x32_bf16 v[76:79], v[16:19], v[44:47], v[76:79]
	v_mfma_f32_16x16x32_bf16 v[80:83], v[24:27], v[52:55], v[80:83]
	v_mfma_f32_16x16x32_bf16 v[84:87], v[16:19], v[52:55], v[84:87]
	v_mfma_f32_16x16x32_bf16 v[100:103], v[16:19], v[60:63], v[88:91]
	s_setprio 0
	s_setprio 1
	v_mfma_f32_16x16x32_bf16 v[88:91], v[12:15], v[32:35], 0
	v_mfma_f32_16x16x32_bf16 v[32:35], v[4:7], v[32:35], 0
	v_mfma_f32_16x16x32_bf16 v[112:115], v[8:11], v[36:39], v[88:91]
	v_mfma_f32_16x16x32_bf16 v[32:35], v[0:3], v[36:39], v[32:35]
	v_mfma_f32_16x16x32_bf16 v[36:39], v[12:15], v[40:43], 0
	v_mfma_f32_16x16x32_bf16 v[40:43], v[4:7], v[40:43], 0
	v_mfma_f32_16x16x32_bf16 v[36:39], v[8:11], v[44:47], v[36:39]
	v_mfma_f32_16x16x32_bf16 v[40:43], v[0:3], v[44:47], v[40:43]
	v_mfma_f32_16x16x32_bf16 v[44:47], v[12:15], v[48:51], 0
	v_mfma_f32_16x16x32_bf16 v[48:51], v[4:7], v[48:51], 0
	v_mfma_f32_16x16x32_bf16 v[44:47], v[8:11], v[52:55], v[44:47]
	v_mfma_f32_16x16x32_bf16 v[48:51], v[0:3], v[52:55], v[48:51]
	s_setprio 2
	s_barrier
	v_mfma_f32_16x16x32_bf16 v[52:55], v[12:15], v[56:59], 0
	v_mfma_f32_16x16x32_bf16 v[56:59], v[4:7], v[56:59], 0
	v_mfma_f32_16x16x32_bf16 v[52:55], v[8:11], v[60:63], v[52:55]
	v_mfma_f32_16x16x32_bf16 v[56:59], v[0:3], v[60:63], v[56:59]
	s_setprio 2
	s_add_i32 s75, s68, s43
	v_lshl_add_u64 v[174:175], s[46:47], 0, v[176:177]
	s_add_i32 s76, s75, 0x2000
	v_lshl_add_u64 v[128:129], v[174:175], 0, s[24:25]
	s_mov_b32 m0, s75
	v_lshl_add_u64 v[200:201], s[46:47], 0, v[178:179]
	s_add_u32 s48, s46, 0x80100
	ds_read_b128 v[60:63], v211 offset:16384
	ds_read_b128 v[88:91], v211 offset:17408
	ds_read_b128 v[92:95], v211 offset:18432
	ds_read_b128 v[104:107], v211 offset:19456
	ds_read_b128 v[108:111], v211 offset:20480
	ds_read_b128 v[116:119], v211 offset:21504
	ds_read_b128 v[120:123], v211 offset:22528
	ds_read_b128 v[124:127], v211 offset:23552
	global_load_lds_dwordx4 v[128:129], off
	v_lshl_add_u64 v[128:129], v[200:201], 0, s[24:25]
	s_mov_b32 m0, s76
	s_addc_u32 s49, s47, 0
	s_add_i32 s77, s67, s43
	global_load_lds_dwordx4 v[128:129], off
	v_lshl_add_u64 v[128:129], s[48:49], 0, v[176:177]
	s_mov_b32 m0, s77
	s_add_i32 s78, s77, 0x2000
	global_load_lds_dwordx4 v[128:129], off
	v_lshl_add_u64 v[128:129], s[48:49], 0, v[178:179]
	s_mov_b32 m0, s78
	v_lshl_add_u64 v[208:209], s[44:45], 0, v[176:177]
	global_load_lds_dwordx4 v[128:129], off
	v_lshl_add_u64 v[128:129], v[208:209], 0, s[24:25]
	s_mov_b32 m0, s56
	v_lshl_add_u64 v[252:253], s[44:45], 0, v[178:179]
	global_load_lds_dwordx4 v[128:129], off
	s_mov_b32 m0, s57
	v_lshl_add_u64 v[128:129], v[252:253], 0, s[24:25]
	global_load_lds_dwordx4 v[128:129], off
	s_waitcnt vmcnt(8) lgkmcnt(0)
	s_barrier
	s_setprio 1
	v_mfma_f32_16x16x32_bf16 v[134:137], v[20:23], v[60:63], 0
	v_mfma_f32_16x16x32_bf16 v[142:145], v[20:23], v[92:95], 0
	v_mfma_f32_16x16x32_bf16 v[150:153], v[20:23], v[108:111], 0
	v_mfma_f32_16x16x32_bf16 v[20:23], v[20:23], v[120:123], 0
	v_mfma_f32_16x16x32_bf16 v[128:131], v[28:31], v[60:63], 0
	v_mfma_f32_16x16x32_bf16 v[134:137], v[16:19], v[88:91], v[134:137]
	v_mfma_f32_16x16x32_bf16 v[138:141], v[28:31], v[92:95], 0
	v_mfma_f32_16x16x32_bf16 v[142:145], v[16:19], v[104:107], v[142:145]
	v_mfma_f32_16x16x32_bf16 v[146:149], v[28:31], v[108:111], 0
	v_mfma_f32_16x16x32_bf16 v[150:153], v[16:19], v[116:119], v[150:153]
	v_mfma_f32_16x16x32_bf16 v[28:31], v[28:31], v[120:123], 0
	v_mfma_f32_16x16x32_bf16 v[16:19], v[16:19], v[124:127], v[20:23]
	v_mfma_f32_16x16x32_bf16 v[130:133], v[24:27], v[88:91], v[128:131]
	v_mfma_f32_16x16x32_bf16 v[138:141], v[24:27], v[104:107], v[138:141]
	v_mfma_f32_16x16x32_bf16 v[146:149], v[24:27], v[116:119], v[146:149]
	v_mfma_f32_16x16x32_bf16 v[154:157], v[24:27], v[124:127], v[28:31]
	s_setprio 0
	s_setprio 1
	v_mfma_f32_16x16x32_bf16 v[24:27], v[4:7], v[60:63], 0
	v_mfma_f32_16x16x32_bf16 v[158:161], v[0:3], v[88:91], v[24:27]
	v_mfma_f32_16x16x32_bf16 v[24:27], v[12:15], v[92:95], 0
	v_mfma_f32_16x16x32_bf16 v[162:165], v[8:11], v[104:107], v[24:27]
	v_mfma_f32_16x16x32_bf16 v[24:27], v[4:7], v[92:95], 0
	v_mfma_f32_16x16x32_bf16 v[166:169], v[0:3], v[104:107], v[24:27]
	v_mfma_f32_16x16x32_bf16 v[24:27], v[12:15], v[108:111], 0
	v_mfma_f32_16x16x32_bf16 v[20:23], v[12:15], v[60:63], 0
	v_mfma_f32_16x16x32_bf16 v[170:173], v[8:11], v[116:119], v[24:27]
	v_mfma_f32_16x16x32_bf16 v[24:27], v[4:7], v[108:111], 0
	v_mfma_f32_16x16x32_bf16 v[4:7], v[4:7], v[120:123], 0
	v_mfma_f32_16x16x32_bf16 v[20:23], v[8:11], v[88:91], v[20:23]
	s_setprio 2
	s_barrier
	v_mfma_f32_16x16x32_bf16 v[190:193], v[0:3], v[116:119], v[24:27]
	v_mfma_f32_16x16x32_bf16 v[12:15], v[12:15], v[120:123], 0
	v_mfma_f32_16x16x32_bf16 v[0:3], v[0:3], v[124:127], v[4:7]
	v_mfma_f32_16x16x32_bf16 v[196:199], v[8:11], v[124:127], v[12:15]
	s_setprio 0
	s_add_i32 s79, 0, 0x18000
	s_add_i32 s81, 0, 0x1c000
	v_add_u32_e32 v128, s79, v189
	v_add_u32_e32 v129, s81, v189
	ds_read_b128 v[4:7], v128
	ds_read_b128 v[8:11], v128 offset:1024
	ds_read_b128 v[204:207], v128 offset:2048
	ds_read_b128 v[212:215], v128 offset:3072
	ds_read_b128 v[216:219], v129
	ds_read_b128 v[220:223], v129 offset:1024
	ds_read_b128 v[224:227], v129 offset:2048
	ds_read_b128 v[228:231], v129 offset:3072
	s_add_u32 s48, s44, 0x80100
	s_addc_u32 s49, s45, 0
	s_mov_b32 m0, s58
	v_lshl_add_u64 v[88:89], s[48:49], 0, v[176:177]
	ds_read_b128 v[12:15], v211 offset:32768
	ds_read_b128 v[24:27], v211 offset:33792
	ds_read_b128 v[28:31], v211 offset:34816
	ds_read_b128 v[60:63], v211 offset:35840
	ds_read_b128 v[232:235], v211 offset:36864
	ds_read_b128 v[236:239], v211 offset:37888
	ds_read_b128 v[240:243], v211 offset:38912
	ds_read_b128 v[244:247], v211 offset:39936
	global_load_lds_dwordx4 v[88:89], off
	s_mov_b32 m0, s59
	v_lshl_add_u64 v[88:89], s[48:49], 0, v[178:179]
	global_load_lds_dwordx4 v[88:89], off
	s_waitcnt vmcnt(8) lgkmcnt(0)
	s_barrier
	s_setprio 1
	v_mfma_f32_16x16x32_bf16 v[64:67], v[4:7], v[12:15], v[64:67]
	v_mfma_f32_16x16x32_bf16 v[124:127], v[8:11], v[24:27], v[64:67]
	v_mfma_f32_16x16x32_bf16 v[64:67], v[204:207], v[12:15], v[68:71]
	v_mfma_f32_16x16x32_bf16 v[120:123], v[212:215], v[24:27], v[64:67]
	v_mfma_f32_16x16x32_bf16 v[64:67], v[4:7], v[28:31], v[72:75]
	v_mfma_f32_16x16x32_bf16 v[108:111], v[8:11], v[60:63], v[64:67]
	v_mfma_f32_16x16x32_bf16 v[64:67], v[204:207], v[28:31], v[76:79]
	v_mfma_f32_16x16x32_bf16 v[104:107], v[212:215], v[60:63], v[64:67]
	v_mfma_f32_16x16x32_bf16 v[64:67], v[4:7], v[232:235], v[80:83]
	v_mfma_f32_16x16x32_bf16 v[92:95], v[8:11], v[236:239], v[64:67]
	v_mfma_f32_16x16x32_bf16 v[64:67], v[204:207], v[232:235], v[84:87]
	v_mfma_f32_16x16x32_bf16 v[88:91], v[212:215], v[236:239], v[64:67]
	v_mfma_f32_16x16x32_bf16 v[64:67], v[4:7], v[240:243], v[96:99]
	v_mfma_f32_16x16x32_bf16 v[76:79], v[8:11], v[244:247], v[64:67]
	v_mfma_f32_16x16x32_bf16 v[64:67], v[204:207], v[240:243], v[100:103]
	v_mfma_f32_16x16x32_bf16 v[72:75], v[212:215], v[244:247], v[64:67]
	s_setprio 0
	s_setprio 1
	v_mfma_f32_16x16x32_bf16 v[64:67], v[216:219], v[12:15], v[112:115]
	v_mfma_f32_16x16x32_bf16 v[12:15], v[224:227], v[12:15], v[32:35]
	v_mfma_f32_16x16x32_bf16 v[112:115], v[228:231], v[24:27], v[12:15]
	v_mfma_f32_16x16x32_bf16 v[12:15], v[216:219], v[28:31], v[36:39]
	v_mfma_f32_16x16x32_bf16 v[100:103], v[220:223], v[60:63], v[12:15]
	v_mfma_f32_16x16x32_bf16 v[12:15], v[224:227], v[28:31], v[40:43]
	v_mfma_f32_16x16x32_bf16 v[96:99], v[228:231], v[60:63], v[12:15]
	v_mfma_f32_16x16x32_bf16 v[12:15], v[216:219], v[232:235], v[44:47]
	v_mfma_f32_16x16x32_bf16 v[84:87], v[220:223], v[236:239], v[12:15]
	v_mfma_f32_16x16x32_bf16 v[12:15], v[224:227], v[232:235], v[48:51]
	v_mfma_f32_16x16x32_bf16 v[80:83], v[228:231], v[236:239], v[12:15]
	v_mfma_f32_16x16x32_bf16 v[12:15], v[216:219], v[240:243], v[52:55]
	s_setprio 2
	s_barrier
	v_mfma_f32_16x16x32_bf16 v[68:71], v[220:223], v[244:247], v[12:15]
	v_mfma_f32_16x16x32_bf16 v[12:15], v[224:227], v[240:243], v[56:59]
	v_mfma_f32_16x16x32_bf16 v[116:119], v[220:223], v[24:27], v[64:67]
	v_mfma_f32_16x16x32_bf16 v[64:67], v[228:231], v[244:247], v[12:15]
	s_setprio 2
	s_add_i32 s79, s79, s43
	s_add_i32 s80, s79, 0x2000
	s_nop 1
	v_lshl_add_u64 v[12:13], v[174:175], 0, s[26:27]
	s_mov_b32 m0, s79
	s_add_u32 s48, s46, 0x80180
	ds_read_b128 v[32:35], v211 offset:49152
	ds_read_b128 v[36:39], v211 offset:50176
	ds_read_b128 v[232:235], v211 offset:51200
	ds_read_b128 v[236:239], v211 offset:52224
	ds_read_b128 v[240:243], v211 offset:53248
	ds_read_b128 v[244:247], v211 offset:54272
	ds_read_b128 v[248:251], v211 offset:55296
	ds_read_b128 v[184:187], v211 offset:56320
	global_load_lds_dwordx4 v[12:13], off
	v_lshl_add_u64 v[12:13], v[200:201], 0, s[26:27]
	s_mov_b32 m0, s80
	s_addc_u32 s49, s47, 0
	s_add_i32 s81, s81, s43
	global_load_lds_dwordx4 v[12:13], off
	v_lshl_add_u64 v[12:13], s[48:49], 0, v[176:177]
	s_mov_b32 m0, s81
	s_add_i32 s82, s81, 0x2000
	global_load_lds_dwordx4 v[12:13], off
	s_mov_b32 m0, s82
	v_lshl_add_u64 v[12:13], s[48:49], 0, v[178:179]
	global_load_lds_dwordx4 v[12:13], off
	s_mov_b32 m0, s61
	v_lshl_add_u64 v[12:13], v[208:209], 0, s[26:27]
	global_load_lds_dwordx4 v[12:13], off
	s_mov_b32 m0, s62
	v_lshl_add_u64 v[12:13], v[252:253], 0, s[26:27]
	global_load_lds_dwordx4 v[12:13], off
	s_waitcnt vmcnt(8) lgkmcnt(0)
	s_barrier
	s_setprio 1
	v_mfma_f32_16x16x32_bf16 v[12:15], v[4:7], v[32:35], v[130:133]
	v_mfma_f32_16x16x32_bf16 v[60:63], v[8:11], v[36:39], v[12:15]
	v_mfma_f32_16x16x32_bf16 v[12:15], v[204:207], v[32:35], v[134:137]
	v_mfma_f32_16x16x32_bf16 v[56:59], v[212:215], v[36:39], v[12:15]
	v_mfma_f32_16x16x32_bf16 v[12:15], v[4:7], v[232:235], v[138:141]
	v_mfma_f32_16x16x32_bf16 v[44:47], v[8:11], v[236:239], v[12:15]
	v_mfma_f32_16x16x32_bf16 v[12:15], v[204:207], v[232:235], v[142:145]
	v_mfma_f32_16x16x32_bf16 v[40:43], v[212:215], v[236:239], v[12:15]
	v_mfma_f32_16x16x32_bf16 v[12:15], v[4:7], v[240:243], v[146:149]
	v_mfma_f32_16x16x32_bf16 v[28:31], v[8:11], v[244:247], v[12:15]
	v_mfma_f32_16x16x32_bf16 v[12:15], v[204:207], v[240:243], v[150:153]
	v_mfma_f32_16x16x32_bf16 v[4:7], v[4:7], v[248:251], v[154:157]
	v_mfma_f32_16x16x32_bf16 v[24:27], v[212:215], v[244:247], v[12:15]
	v_mfma_f32_16x16x32_bf16 v[12:15], v[8:11], v[184:187], v[4:7]
	v_mfma_f32_16x16x32_bf16 v[4:7], v[204:207], v[248:251], v[16:19]
	v_mfma_f32_16x16x32_bf16 v[8:11], v[212:215], v[184:187], v[4:7]
	s_setprio 0
	s_setprio 1
	v_mfma_f32_16x16x32_bf16 v[4:7], v[216:219], v[32:35], v[20:23]
	v_mfma_f32_16x16x32_bf16 v[52:55], v[220:223], v[36:39], v[4:7]
	v_mfma_f32_16x16x32_bf16 v[4:7], v[224:227], v[32:35], v[158:161]
	v_mfma_f32_16x16x32_bf16 v[48:51], v[228:231], v[36:39], v[4:7]
	v_mfma_f32_16x16x32_bf16 v[4:7], v[216:219], v[232:235], v[162:165]
	v_mfma_f32_16x16x32_bf16 v[36:39], v[220:223], v[236:239], v[4:7]
	v_mfma_f32_16x16x32_bf16 v[4:7], v[224:227], v[232:235], v[166:169]
	v_mfma_f32_16x16x32_bf16 v[32:35], v[228:231], v[236:239], v[4:7]
	v_mfma_f32_16x16x32_bf16 v[4:7], v[216:219], v[240:243], v[170:173]
	v_mfma_f32_16x16x32_bf16 v[20:23], v[220:223], v[244:247], v[4:7]
	v_mfma_f32_16x16x32_bf16 v[4:7], v[224:227], v[240:243], v[190:193]
	v_mfma_f32_16x16x32_bf16 v[16:19], v[228:231], v[244:247], v[4:7]
	s_setprio 2
	s_barrier
	v_mfma_f32_16x16x32_bf16 v[4:7], v[216:219], v[248:251], v[196:199]
	v_mfma_f32_16x16x32_bf16 v[0:3], v[224:227], v[248:251], v[0:3]
	v_mfma_f32_16x16x32_bf16 v[4:7], v[220:223], v[184:187], v[4:7]
	v_mfma_f32_16x16x32_bf16 v[0:3], v[228:231], v[184:187], v[0:3]
	s_setprio 0
	s_add_u32 s44, s44, 0x80180
	s_addc_u32 s45, s45, 0
	s_add_u32 s83, s46, 0x200
	s_addc_u32 s84, s47, 0
	s_mov_b32 s46, 0
	s_add_i32 s85, s46, 2
	s_and_b32 s47, s85, 6
	s_cmp_lg_u32 s47, 0
	s_cbranch_scc1 .LBB0_700
	s_branch .LBB0_699

.LBB0_700:
	ds_read_b128 v[130:133], v203
	ds_read_b128 v[134:137], v203 offset:1024
	ds_read_b128 v[138:141], v203 offset:2048
	ds_read_b128 v[142:145], v203 offset:3072
	ds_read_b128 v[146:149], v195
	ds_read_b128 v[150:153], v195 offset:1024
	ds_read_b128 v[154:157], v195 offset:2048
	ds_read_b128 v[158:161], v195 offset:3072
	s_add_u32 s47, s44, 0xfff80080
	s_addc_u32 s48, s45, -1
	s_cmp_eq_u32 s46, 28
	s_cselect_b32 s49, s29, s48
	s_cselect_b32 s48, s71, s47
	s_cselect_b32 s47, s31, s84
	s_cselect_b32 s46, s72, s83
	s_mov_b32 m0, s73
	v_lshl_add_u64 v[174:175], s[44:45], 0, v[180:181]
	ds_read_b128 v[162:165], v211
	ds_read_b128 v[166:169], v211 offset:1024
	ds_read_b128 v[170:173], v211 offset:2048
	ds_read_b128 v[184:187], v211 offset:3072
	ds_read_b128 v[190:193], v211 offset:4096
	ds_read_b128 v[196:199], v211 offset:5120
	ds_read_b128 v[204:207], v211 offset:6144
	ds_read_b128 v[212:215], v211 offset:7168
	global_load_lds_dwordx4 v[174:175], off
	s_mov_b32 m0, s74
	v_lshl_add_u64 v[174:175], s[44:45], 0, v[182:183]
	global_load_lds_dwordx4 v[174:175], off
	s_waitcnt vmcnt(8) lgkmcnt(0)
	s_barrier
	s_setprio 1
	v_mfma_f32_16x16x32_bf16 v[124:127], v[130:133], v[162:165], v[124:127]
	v_mfma_f32_16x16x32_bf16 v[120:123], v[138:141], v[162:165], v[120:123]
	v_mfma_f32_16x16x32_bf16 v[108:111], v[130:133], v[170:173], v[108:111]
	v_mfma_f32_16x16x32_bf16 v[104:107], v[138:141], v[170:173], v[104:107]
	v_mfma_f32_16x16x32_bf16 v[92:95], v[130:133], v[190:193], v[92:95]
	v_mfma_f32_16x16x32_bf16 v[88:91], v[138:141], v[190:193], v[88:91]
	v_mfma_f32_16x16x32_bf16 v[76:79], v[130:133], v[204:207], v[76:79]
	v_mfma_f32_16x16x32_bf16 v[72:75], v[138:141], v[204:207], v[72:75]
	v_mfma_f32_16x16x32_bf16 v[124:127], v[134:137], v[166:169], v[124:127]
	v_mfma_f32_16x16x32_bf16 v[120:123], v[142:145], v[166:169], v[120:123]
	v_mfma_f32_16x16x32_bf16 v[108:111], v[134:137], v[184:187], v[108:111]
	v_mfma_f32_16x16x32_bf16 v[104:107], v[142:145], v[184:187], v[104:107]
	v_mfma_f32_16x16x32_bf16 v[92:95], v[134:137], v[196:199], v[92:95]
	v_mfma_f32_16x16x32_bf16 v[88:91], v[142:145], v[196:199], v[88:91]
	v_mfma_f32_16x16x32_bf16 v[76:79], v[134:137], v[212:215], v[76:79]
	v_mfma_f32_16x16x32_bf16 v[72:75], v[142:145], v[212:215], v[72:75]
	s_setprio 0
	s_setprio 1
	v_mfma_f32_16x16x32_bf16 v[116:119], v[146:149], v[162:165], v[116:119]
	v_mfma_f32_16x16x32_bf16 v[112:115], v[154:157], v[162:165], v[112:115]
	v_mfma_f32_16x16x32_bf16 v[100:103], v[146:149], v[170:173], v[100:103]
	v_mfma_f32_16x16x32_bf16 v[96:99], v[154:157], v[170:173], v[96:99]
	v_mfma_f32_16x16x32_bf16 v[84:87], v[146:149], v[190:193], v[84:87]
	v_mfma_f32_16x16x32_bf16 v[80:83], v[154:157], v[190:193], v[80:83]
	v_mfma_f32_16x16x32_bf16 v[68:71], v[146:149], v[204:207], v[68:71]
	v_mfma_f32_16x16x32_bf16 v[64:67], v[154:157], v[204:207], v[64:67]
	v_mfma_f32_16x16x32_bf16 v[116:119], v[150:153], v[166:169], v[116:119]
	v_mfma_f32_16x16x32_bf16 v[112:115], v[158:161], v[166:169], v[112:115]
	v_mfma_f32_16x16x32_bf16 v[100:103], v[150:153], v[184:187], v[100:103]
	v_mfma_f32_16x16x32_bf16 v[96:99], v[158:161], v[184:187], v[96:99]
	s_setprio 2
	s_barrier
	v_mfma_f32_16x16x32_bf16 v[84:87], v[150:153], v[196:199], v[84:87]
	v_mfma_f32_16x16x32_bf16 v[80:83], v[158:161], v[196:199], v[80:83]
	v_mfma_f32_16x16x32_bf16 v[68:71], v[150:153], v[212:215], v[68:71]
	v_mfma_f32_16x16x32_bf16 v[64:67], v[158:161], v[212:215], v[64:67]
	s_setprio 2
	s_mov_b32 m0, s75
	v_lshl_add_u64 v[174:175], s[46:47], 0, v[176:177]
	s_add_u32 s86, s46, 0x80000
	ds_read_b128 v[162:165], v211 offset:16384
	ds_read_b128 v[166:169], v211 offset:17408
	ds_read_b128 v[170:173], v211 offset:18432
	ds_read_b128 v[184:187], v211 offset:19456
	ds_read_b128 v[190:193], v211 offset:20480
	ds_read_b128 v[196:199], v211 offset:21504
	ds_read_b128 v[204:207], v211 offset:22528
	ds_read_b128 v[212:215], v211 offset:23552
	global_load_lds_dwordx4 v[174:175], off
	v_lshl_add_u64 v[200:201], s[46:47], 0, v[178:179]
	s_mov_b32 m0, s76
	s_addc_u32 s87, s47, 0
	global_load_lds_dwordx4 v[200:201], off
	v_lshl_add_u64 v[208:209], s[86:87], 0, v[176:177]
	s_mov_b32 m0, s77
	v_lshl_add_u64 v[216:217], s[48:49], 0, v[178:179]
	global_load_lds_dwordx4 v[208:209], off
	s_mov_b32 m0, s78
	v_lshl_add_u64 v[208:209], s[86:87], 0, v[178:179]
	global_load_lds_dwordx4 v[208:209], off
	s_mov_b32 m0, s56
	v_lshl_add_u64 v[208:209], s[48:49], 0, v[176:177]
	global_load_lds_dwordx4 v[208:209], off
	s_mov_b32 m0, s57
	s_nop 0
	global_load_lds_dwordx4 v[216:217], off
	s_waitcnt vmcnt(8) lgkmcnt(0)
	s_barrier
	s_setprio 1
	v_mfma_f32_16x16x32_bf16 v[60:63], v[130:133], v[162:165], v[60:63]
	v_mfma_f32_16x16x32_bf16 v[56:59], v[138:141], v[162:165], v[56:59]
	v_mfma_f32_16x16x32_bf16 v[44:47], v[130:133], v[170:173], v[44:47]
	v_mfma_f32_16x16x32_bf16 v[40:43], v[138:141], v[170:173], v[40:43]
	v_mfma_f32_16x16x32_bf16 v[28:31], v[130:133], v[190:193], v[28:31]
	v_mfma_f32_16x16x32_bf16 v[24:27], v[138:141], v[190:193], v[24:27]
	v_mfma_f32_16x16x32_bf16 v[12:15], v[130:133], v[204:207], v[12:15]
	v_mfma_f32_16x16x32_bf16 v[8:11], v[138:141], v[204:207], v[8:11]
	v_mfma_f32_16x16x32_bf16 v[60:63], v[134:137], v[166:169], v[60:63]
	v_mfma_f32_16x16x32_bf16 v[56:59], v[142:145], v[166:169], v[56:59]
	v_mfma_f32_16x16x32_bf16 v[44:47], v[134:137], v[184:187], v[44:47]
	v_mfma_f32_16x16x32_bf16 v[40:43], v[142:145], v[184:187], v[40:43]
	v_mfma_f32_16x16x32_bf16 v[28:31], v[134:137], v[196:199], v[28:31]
	v_mfma_f32_16x16x32_bf16 v[24:27], v[142:145], v[196:199], v[24:27]
	v_mfma_f32_16x16x32_bf16 v[12:15], v[134:137], v[212:215], v[12:15]
	v_mfma_f32_16x16x32_bf16 v[8:11], v[142:145], v[212:215], v[8:11]
	s_setprio 0
	s_setprio 1
	v_mfma_f32_16x16x32_bf16 v[52:55], v[146:149], v[162:165], v[52:55]
	v_mfma_f32_16x16x32_bf16 v[48:51], v[154:157], v[162:165], v[48:51]
	v_mfma_f32_16x16x32_bf16 v[36:39], v[146:149], v[170:173], v[36:39]
	v_mfma_f32_16x16x32_bf16 v[32:35], v[154:157], v[170:173], v[32:35]
	v_mfma_f32_16x16x32_bf16 v[20:23], v[146:149], v[190:193], v[20:23]
	v_mfma_f32_16x16x32_bf16 v[16:19], v[154:157], v[190:193], v[16:19]
	v_mfma_f32_16x16x32_bf16 v[4:7], v[146:149], v[204:207], v[4:7]
	v_mfma_f32_16x16x32_bf16 v[0:3], v[154:157], v[204:207], v[0:3]
	v_mfma_f32_16x16x32_bf16 v[52:55], v[150:153], v[166:169], v[52:55]
	v_mfma_f32_16x16x32_bf16 v[48:51], v[158:161], v[166:169], v[48:51]
	v_mfma_f32_16x16x32_bf16 v[36:39], v[150:153], v[184:187], v[36:39]
	v_mfma_f32_16x16x32_bf16 v[32:35], v[158:161], v[184:187], v[32:35]
	s_setprio 2
	s_barrier
	v_mfma_f32_16x16x32_bf16 v[20:23], v[150:153], v[196:199], v[20:23]
	v_mfma_f32_16x16x32_bf16 v[16:19], v[158:161], v[196:199], v[16:19]
	v_mfma_f32_16x16x32_bf16 v[4:7], v[150:153], v[212:215], v[4:7]
	v_mfma_f32_16x16x32_bf16 v[0:3], v[158:161], v[212:215], v[0:3]
	s_setprio 0
	ds_read_b128 v[130:133], v128
	ds_read_b128 v[134:137], v128 offset:1024
	ds_read_b128 v[138:141], v128 offset:2048
	ds_read_b128 v[142:145], v128 offset:3072
	ds_read_b128 v[146:149], v129
	ds_read_b128 v[150:153], v129 offset:1024
	ds_read_b128 v[154:157], v129 offset:2048
	ds_read_b128 v[158:161], v129 offset:3072
	s_add_u32 s48, s48, 0x80000
	s_addc_u32 s49, s49, 0
	s_mov_b32 m0, s58
	v_lshl_add_u64 v[218:219], s[48:49], 0, v[176:177]
	ds_read_b128 v[162:165], v211 offset:32768
	ds_read_b128 v[166:169], v211 offset:33792
	ds_read_b128 v[170:173], v211 offset:34816
	ds_read_b128 v[184:187], v211 offset:35840
	ds_read_b128 v[190:193], v211 offset:36864
	ds_read_b128 v[196:199], v211 offset:37888
	ds_read_b128 v[204:207], v211 offset:38912
	ds_read_b128 v[212:215], v211 offset:39936
	global_load_lds_dwordx4 v[218:219], off
	s_mov_b32 m0, s59
	v_lshl_add_u64 v[218:219], s[48:49], 0, v[178:179]
	global_load_lds_dwordx4 v[218:219], off
	s_waitcnt vmcnt(8) lgkmcnt(0)
	s_barrier
	s_setprio 1
	v_mfma_f32_16x16x32_bf16 v[124:127], v[130:133], v[162:165], v[124:127]
	v_mfma_f32_16x16x32_bf16 v[120:123], v[138:141], v[162:165], v[120:123]
	v_mfma_f32_16x16x32_bf16 v[108:111], v[130:133], v[170:173], v[108:111]
	v_mfma_f32_16x16x32_bf16 v[104:107], v[138:141], v[170:173], v[104:107]
	v_mfma_f32_16x16x32_bf16 v[92:95], v[130:133], v[190:193], v[92:95]
	v_mfma_f32_16x16x32_bf16 v[88:91], v[138:141], v[190:193], v[88:91]
	v_mfma_f32_16x16x32_bf16 v[76:79], v[130:133], v[204:207], v[76:79]
	v_mfma_f32_16x16x32_bf16 v[72:75], v[138:141], v[204:207], v[72:75]
	v_mfma_f32_16x16x32_bf16 v[124:127], v[134:137], v[166:169], v[124:127]
	v_mfma_f32_16x16x32_bf16 v[120:123], v[142:145], v[166:169], v[120:123]
	v_mfma_f32_16x16x32_bf16 v[108:111], v[134:137], v[184:187], v[108:111]
	v_mfma_f32_16x16x32_bf16 v[104:107], v[142:145], v[184:187], v[104:107]
	v_mfma_f32_16x16x32_bf16 v[92:95], v[134:137], v[196:199], v[92:95]
	v_mfma_f32_16x16x32_bf16 v[88:91], v[142:145], v[196:199], v[88:91]
	v_mfma_f32_16x16x32_bf16 v[76:79], v[134:137], v[212:215], v[76:79]
	v_mfma_f32_16x16x32_bf16 v[72:75], v[142:145], v[212:215], v[72:75]
	s_setprio 0
	s_setprio 1
	v_mfma_f32_16x16x32_bf16 v[116:119], v[146:149], v[162:165], v[116:119]
	v_mfma_f32_16x16x32_bf16 v[112:115], v[154:157], v[162:165], v[112:115]
	v_mfma_f32_16x16x32_bf16 v[100:103], v[146:149], v[170:173], v[100:103]
	v_mfma_f32_16x16x32_bf16 v[96:99], v[154:157], v[170:173], v[96:99]
	v_mfma_f32_16x16x32_bf16 v[84:87], v[146:149], v[190:193], v[84:87]
	v_mfma_f32_16x16x32_bf16 v[80:83], v[154:157], v[190:193], v[80:83]
	v_mfma_f32_16x16x32_bf16 v[68:71], v[146:149], v[204:207], v[68:71]
	v_mfma_f32_16x16x32_bf16 v[64:67], v[154:157], v[204:207], v[64:67]
	v_mfma_f32_16x16x32_bf16 v[116:119], v[150:153], v[166:169], v[116:119]
	v_mfma_f32_16x16x32_bf16 v[112:115], v[158:161], v[166:169], v[112:115]
	v_mfma_f32_16x16x32_bf16 v[100:103], v[150:153], v[184:187], v[100:103]
	v_mfma_f32_16x16x32_bf16 v[96:99], v[158:161], v[184:187], v[96:99]
	s_setprio 2
	s_barrier
	v_mfma_f32_16x16x32_bf16 v[84:87], v[150:153], v[196:199], v[84:87]
	v_mfma_f32_16x16x32_bf16 v[80:83], v[158:161], v[196:199], v[80:83]
	v_mfma_f32_16x16x32_bf16 v[68:71], v[150:153], v[212:215], v[68:71]
	v_mfma_f32_16x16x32_bf16 v[64:67], v[158:161], v[212:215], v[64:67]
	s_setprio 2
	s_mov_b32 m0, s79
	v_lshl_add_u64 v[174:175], v[174:175], 0, s[20:21]
	s_add_u32 s46, s46, 0x80080
	ds_read_b128 v[162:165], v211 offset:49152
	ds_read_b128 v[166:169], v211 offset:50176
	ds_read_b128 v[170:173], v211 offset:51200
	ds_read_b128 v[184:187], v211 offset:52224
	ds_read_b128 v[190:193], v211 offset:53248
	ds_read_b128 v[196:199], v211 offset:54272
	ds_read_b128 v[204:207], v211 offset:55296
	ds_read_b128 v[212:215], v211 offset:56320
	global_load_lds_dwordx4 v[174:175], off
	v_lshl_add_u64 v[174:175], v[200:201], 0, s[20:21]
	s_mov_b32 m0, s80
	s_addc_u32 s47, s47, 0
	global_load_lds_dwordx4 v[174:175], off
	s_mov_b32 m0, s81
	v_lshl_add_u64 v[174:175], s[46:47], 0, v[176:177]
	global_load_lds_dwordx4 v[174:175], off
	s_mov_b32 m0, s82
	v_lshl_add_u64 v[174:175], s[46:47], 0, v[178:179]
	global_load_lds_dwordx4 v[174:175], off
	s_mov_b32 m0, s61
	v_lshl_add_u64 v[174:175], v[208:209], 0, s[20:21]
	global_load_lds_dwordx4 v[174:175], off
	s_mov_b32 m0, s62
	v_lshl_add_u64 v[174:175], v[216:217], 0, s[20:21]
	global_load_lds_dwordx4 v[174:175], off
	s_waitcnt vmcnt(8) lgkmcnt(0)
	s_barrier
	s_setprio 1
	v_mfma_f32_16x16x32_bf16 v[60:63], v[130:133], v[162:165], v[60:63]
	v_mfma_f32_16x16x32_bf16 v[56:59], v[138:141], v[162:165], v[56:59]
	v_mfma_f32_16x16x32_bf16 v[44:47], v[130:133], v[170:173], v[44:47]
	v_mfma_f32_16x16x32_bf16 v[40:43], v[138:141], v[170:173], v[40:43]
	v_mfma_f32_16x16x32_bf16 v[28:31], v[130:133], v[190:193], v[28:31]
	v_mfma_f32_16x16x32_bf16 v[24:27], v[138:141], v[190:193], v[24:27]
	v_mfma_f32_16x16x32_bf16 v[12:15], v[130:133], v[204:207], v[12:15]
	v_mfma_f32_16x16x32_bf16 v[8:11], v[138:141], v[204:207], v[8:11]
	v_mfma_f32_16x16x32_bf16 v[60:63], v[134:137], v[166:169], v[60:63]
	v_mfma_f32_16x16x32_bf16 v[56:59], v[142:145], v[166:169], v[56:59]
	v_mfma_f32_16x16x32_bf16 v[44:47], v[134:137], v[184:187], v[44:47]
	v_mfma_f32_16x16x32_bf16 v[40:43], v[142:145], v[184:187], v[40:43]
	v_mfma_f32_16x16x32_bf16 v[28:31], v[134:137], v[196:199], v[28:31]
	v_mfma_f32_16x16x32_bf16 v[24:27], v[142:145], v[196:199], v[24:27]
	v_mfma_f32_16x16x32_bf16 v[12:15], v[134:137], v[212:215], v[12:15]
	v_mfma_f32_16x16x32_bf16 v[8:11], v[142:145], v[212:215], v[8:11]
	s_setprio 0
	s_setprio 1
	v_mfma_f32_16x16x32_bf16 v[52:55], v[146:149], v[162:165], v[52:55]
	v_mfma_f32_16x16x32_bf16 v[48:51], v[154:157], v[162:165], v[48:51]
	v_mfma_f32_16x16x32_bf16 v[36:39], v[146:149], v[170:173], v[36:39]
	v_mfma_f32_16x16x32_bf16 v[32:35], v[154:157], v[170:173], v[32:35]
	v_mfma_f32_16x16x32_bf16 v[20:23], v[146:149], v[190:193], v[20:23]
	v_mfma_f32_16x16x32_bf16 v[16:19], v[154:157], v[190:193], v[16:19]
	v_mfma_f32_16x16x32_bf16 v[4:7], v[146:149], v[204:207], v[4:7]
	v_mfma_f32_16x16x32_bf16 v[0:3], v[154:157], v[204:207], v[0:3]
	v_mfma_f32_16x16x32_bf16 v[52:55], v[150:153], v[166:169], v[52:55]
	v_mfma_f32_16x16x32_bf16 v[48:51], v[158:161], v[166:169], v[48:51]
	v_mfma_f32_16x16x32_bf16 v[36:39], v[150:153], v[184:187], v[36:39]
	v_mfma_f32_16x16x32_bf16 v[32:35], v[158:161], v[184:187], v[32:35]
	s_setprio 2
	s_barrier
	v_mfma_f32_16x16x32_bf16 v[20:23], v[150:153], v[196:199], v[20:23]
	v_mfma_f32_16x16x32_bf16 v[16:19], v[158:161], v[196:199], v[16:19]
	v_mfma_f32_16x16x32_bf16 v[4:7], v[150:153], v[212:215], v[4:7]
	v_mfma_f32_16x16x32_bf16 v[0:3], v[158:161], v[212:215], v[0:3]
	s_setprio 0
	s_add_i32 s70, s70, 1
	s_add_u32 s44, s44, 0x100
	s_addc_u32 s45, s45, 0
	s_add_u32 s83, s83, 0x100
	s_addc_u32 s84, s84, 0
	s_cmp_gt_u32 s85, 29
	s_cbranch_scc0 .LBB0_698
	s_lshl_b32 s29, s41, 12
	s_and_b32 s29, s29, 0x1000
	s_add_i32 s29, s29, 0
	v_mbcnt_lo_u32_b32 v128, -1, 0
	v_mbcnt_hi_u32_b32 v128, -1, v128
	s_add_i32 s29, s29, s63
	v_lshlrev_b32_e32 v128, 4, v128
	s_add_i32 s29, s29, 0x20400
	v_and_b32_e32 v128, 0xf0, v128
	v_add_u32_e32 v128, s29, v128
	ds_read2_b32 v[214:215], v128 offset0:3 offset1:67
	ds_read2_b32 v[206:207], v128 offset0:131 offset1:195
	v_add_u32_e32 v128, 12, v128
	ds_read2st64_b32 v[196:197], v128 offset0:8 offset1:9
	ds_read2st64_b32 v[190:191], v128 offset0:10 offset1:11
	s_and_b64 vcc, exec, s[22:23]
	s_waitcnt lgkmcnt(0)
	v_mov_b32_e32 v210, v215
	v_mov_b32_e32 v202, v207
	v_mov_b32_e32 v194, v197
	v_mov_b32_e32 v188, v191
	s_cbranch_vccz .LBB0_703
	s_barrier

.LBB0_783:
	s_ashr_i32 s23, s22, 31
	s_lshl_b64 s[26:27], s[22:23], 19
	s_add_u32 s26, s43, s26
	s_addc_u32 s27, s44, s27
	s_and_b64 s[28:29], s[4:5], exec
	s_cselect_b32 s23, s27, s37
	s_cselect_b32 s31, s26, s36
	s_ashr_i32 s25, s24, 31
	s_lshl_b64 s[28:29], s[24:25], 19
	s_add_u32 s28, s45, s28
	s_addc_u32 s29, s46, s29
	s_and_b64 s[40:41], s[4:5], exec
	s_cselect_b32 s25, s29, s39
	s_cselect_b32 s62, s28, s38
	s_add_u32 s36, s36, 0x40080
	s_addc_u32 s37, s37, 0
	s_add_u32 s63, s38, 0x100
	s_addc_u32 s64, s39, 0
	s_mov_b32 s65, -2
	ds_read_b128 v[144:147], v163
	ds_read_b128 v[148:151], v163 offset:1024
	ds_read_b128 v[152:155], v163 offset:2048
	ds_read_b128 v[156:159], v163 offset:3072
	ds_read_b128 v[168:171], v164
	ds_read_b128 v[172:175], v164 offset:1024
	ds_read_b128 v[176:179], v164 offset:2048
	ds_read_b128 v[180:183], v164 offset:3072
	s_add_u32 s38, s36, 0xfffc0080
	s_addc_u32 s39, s37, -1
	s_cmp_eq_u32 s65, 12
	s_cselect_b32 s41, s23, s39
	s_cselect_b32 s40, s31, s38
	s_cselect_b32 s39, s25, s64
	s_cselect_b32 s38, s62, s63
	v_lshl_add_u64 v[160:161], s[36:37], 0, v[136:137]
	s_add_i32 m0, s50, 0xc000
	ds_read_b128 v[184:187], v165
	ds_read_b128 v[188:191], v165 offset:1024
	ds_read_b128 v[192:195], v165 offset:2048
	ds_read_b128 v[196:199], v165 offset:3072
	ds_read_b128 v[200:203], v165 offset:4096
	ds_read_b128 v[204:207], v165 offset:5120
	ds_read_b128 v[208:211], v165 offset:6144
	ds_read_b128 v[212:215], v165 offset:7168
	global_load_lds_dwordx4 v[160:161], off
	s_add_i32 m0, s50, 0xe000
	v_lshl_add_u64 v[160:161], s[36:37], 0, v[138:139]
	global_load_lds_dwordx4 v[160:161], off
	s_waitcnt vmcnt(8) lgkmcnt(0)
	s_barrier
	s_setprio 1
	v_mfma_f32_16x16x32_bf16 v[124:127], v[144:147], v[184:187], 0
	v_mfma_f32_16x16x32_bf16 v[120:123], v[152:155], v[184:187], 0
	v_mfma_f32_16x16x32_bf16 v[108:111], v[144:147], v[192:195], 0
	v_mfma_f32_16x16x32_bf16 v[104:107], v[152:155], v[192:195], 0
	v_mfma_f32_16x16x32_bf16 v[92:95], v[144:147], v[200:203], 0
	v_mfma_f32_16x16x32_bf16 v[88:91], v[152:155], v[200:203], 0
	v_mfma_f32_16x16x32_bf16 v[76:79], v[144:147], v[208:211], 0
	v_mfma_f32_16x16x32_bf16 v[72:75], v[152:155], v[208:211], 0
	v_mfma_f32_16x16x32_bf16 v[124:127], v[148:151], v[188:191], v[124:127]
	v_mfma_f32_16x16x32_bf16 v[120:123], v[156:159], v[188:191], v[120:123]
	v_mfma_f32_16x16x32_bf16 v[108:111], v[148:151], v[196:199], v[108:111]
	v_mfma_f32_16x16x32_bf16 v[104:107], v[156:159], v[196:199], v[104:107]
	v_mfma_f32_16x16x32_bf16 v[92:95], v[148:151], v[204:207], v[92:95]
	v_mfma_f32_16x16x32_bf16 v[88:91], v[156:159], v[204:207], v[88:91]
	v_mfma_f32_16x16x32_bf16 v[76:79], v[148:151], v[212:215], v[76:79]
	v_mfma_f32_16x16x32_bf16 v[72:75], v[156:159], v[212:215], v[72:75]
	s_setprio 0
	s_setprio 1
	v_mfma_f32_16x16x32_bf16 v[116:119], v[168:171], v[184:187], 0
	v_mfma_f32_16x16x32_bf16 v[112:115], v[176:179], v[184:187], 0
	v_mfma_f32_16x16x32_bf16 v[100:103], v[168:171], v[192:195], 0
	v_mfma_f32_16x16x32_bf16 v[96:99], v[176:179], v[192:195], 0
	v_mfma_f32_16x16x32_bf16 v[84:87], v[168:171], v[200:203], 0
	v_mfma_f32_16x16x32_bf16 v[80:83], v[176:179], v[200:203], 0
	v_mfma_f32_16x16x32_bf16 v[68:71], v[168:171], v[208:211], 0
	v_mfma_f32_16x16x32_bf16 v[64:67], v[176:179], v[208:211], 0
	v_mfma_f32_16x16x32_bf16 v[116:119], v[172:175], v[188:191], v[116:119]
	v_mfma_f32_16x16x32_bf16 v[112:115], v[180:183], v[188:191], v[112:115]
	v_mfma_f32_16x16x32_bf16 v[100:103], v[172:175], v[196:199], v[100:103]
	v_mfma_f32_16x16x32_bf16 v[96:99], v[180:183], v[196:199], v[96:99]
	s_setprio 2
	s_barrier
	v_mfma_f32_16x16x32_bf16 v[84:87], v[172:175], v[204:207], v[84:87]
	v_mfma_f32_16x16x32_bf16 v[80:83], v[180:183], v[204:207], v[80:83]
	v_mfma_f32_16x16x32_bf16 v[68:71], v[172:175], v[212:215], v[68:71]
	v_mfma_f32_16x16x32_bf16 v[64:67], v[180:183], v[212:215], v[64:67]
	s_setprio 2
	s_add_i32 s66, s59, s47
	v_lshl_add_u64 v[160:161], s[38:39], 0, v[132:133]
	s_mov_b32 m0, s66
	ds_read_b128 v[184:187], v165 offset:16384
	ds_read_b128 v[188:191], v165 offset:17408
	ds_read_b128 v[192:195], v165 offset:18432
	ds_read_b128 v[196:199], v165 offset:19456
	ds_read_b128 v[200:203], v165 offset:20480
	ds_read_b128 v[204:207], v165 offset:21504
	ds_read_b128 v[208:211], v165 offset:22528
	ds_read_b128 v[212:215], v165 offset:23552
	global_load_lds_dwordx4 v[160:161], off
	s_add_i32 m0, s66, 0x2000
	s_add_u32 s66, s38, 0x40000
	v_lshl_add_u64 v[216:217], s[38:39], 0, v[128:129]
	s_addc_u32 s67, s39, 0
	s_add_i32 s68, s60, s47
	global_load_lds_dwordx4 v[216:217], off
	v_lshl_add_u64 v[218:219], s[66:67], 0, v[132:133]
	s_mov_b32 m0, s68
	v_lshl_add_u64 v[220:221], s[40:41], 0, v[130:131]
	global_load_lds_dwordx4 v[218:219], off
	s_add_i32 m0, s68, 0x2000
	v_lshl_add_u64 v[218:219], s[66:67], 0, v[128:129]
	global_load_lds_dwordx4 v[218:219], off
	s_mov_b32 m0, s50
	v_lshl_add_u64 v[218:219], s[40:41], 0, v[134:135]
	global_load_lds_dwordx4 v[218:219], off
	s_mov_b32 m0, s51
	s_nop 0
	global_load_lds_dwordx4 v[220:221], off
	s_waitcnt vmcnt(8) lgkmcnt(0)
	s_barrier
	s_setprio 1
	v_mfma_f32_16x16x32_bf16 v[60:63], v[144:147], v[184:187], 0
	v_mfma_f32_16x16x32_bf16 v[56:59], v[152:155], v[184:187], 0
	v_mfma_f32_16x16x32_bf16 v[44:47], v[144:147], v[192:195], 0
	v_mfma_f32_16x16x32_bf16 v[40:43], v[152:155], v[192:195], 0
	v_mfma_f32_16x16x32_bf16 v[28:31], v[144:147], v[200:203], 0
	v_mfma_f32_16x16x32_bf16 v[24:27], v[152:155], v[200:203], 0
	v_mfma_f32_16x16x32_bf16 v[12:15], v[144:147], v[208:211], 0
	v_mfma_f32_16x16x32_bf16 v[8:11], v[152:155], v[208:211], 0
	v_mfma_f32_16x16x32_bf16 v[60:63], v[148:151], v[188:191], v[60:63]
	v_mfma_f32_16x16x32_bf16 v[56:59], v[156:159], v[188:191], v[56:59]
	v_mfma_f32_16x16x32_bf16 v[44:47], v[148:151], v[196:199], v[44:47]
	v_mfma_f32_16x16x32_bf16 v[40:43], v[156:159], v[196:199], v[40:43]
	v_mfma_f32_16x16x32_bf16 v[28:31], v[148:151], v[204:207], v[28:31]
	v_mfma_f32_16x16x32_bf16 v[24:27], v[156:159], v[204:207], v[24:27]
	v_mfma_f32_16x16x32_bf16 v[12:15], v[148:151], v[212:215], v[12:15]
	v_mfma_f32_16x16x32_bf16 v[8:11], v[156:159], v[212:215], v[8:11]
	s_setprio 0
	s_setprio 1
	v_mfma_f32_16x16x32_bf16 v[52:55], v[168:171], v[184:187], 0
	v_mfma_f32_16x16x32_bf16 v[48:51], v[176:179], v[184:187], 0
	v_mfma_f32_16x16x32_bf16 v[36:39], v[168:171], v[192:195], 0
	v_mfma_f32_16x16x32_bf16 v[32:35], v[176:179], v[192:195], 0
	v_mfma_f32_16x16x32_bf16 v[20:23], v[168:171], v[200:203], 0
	v_mfma_f32_16x16x32_bf16 v[16:19], v[176:179], v[200:203], 0
	v_mfma_f32_16x16x32_bf16 v[4:7], v[168:171], v[208:211], 0
	v_mfma_f32_16x16x32_bf16 v[0:3], v[176:179], v[208:211], 0
	v_mfma_f32_16x16x32_bf16 v[52:55], v[172:175], v[188:191], v[52:55]
	v_mfma_f32_16x16x32_bf16 v[48:51], v[180:183], v[188:191], v[48:51]
	v_mfma_f32_16x16x32_bf16 v[36:39], v[172:175], v[196:199], v[36:39]
	v_mfma_f32_16x16x32_bf16 v[32:35], v[180:183], v[196:199], v[32:35]
	s_setprio 2
	s_barrier
	v_mfma_f32_16x16x32_bf16 v[20:23], v[172:175], v[204:207], v[20:23]
	v_mfma_f32_16x16x32_bf16 v[16:19], v[180:183], v[204:207], v[16:19]
	v_mfma_f32_16x16x32_bf16 v[4:7], v[172:175], v[212:215], v[4:7]
	v_mfma_f32_16x16x32_bf16 v[0:3], v[180:183], v[212:215], v[0:3]
	s_setprio 0
	s_add_i32 s66, 0, 0x18000
	s_add_i32 s67, 0, 0x1c000
	v_add_u32_e32 v156, s66, v162
	v_add_u32_e32 v167, s67, v162
	ds_read_b128 v[144:147], v156
	ds_read_b128 v[148:151], v156 offset:1024
	ds_read_b128 v[152:155], v156 offset:2048
	ds_read_b128 v[156:159], v156 offset:3072
	ds_read_b128 v[168:171], v167
	ds_read_b128 v[172:175], v167 offset:1024
	ds_read_b128 v[176:179], v167 offset:2048
	ds_read_b128 v[180:183], v167 offset:3072
	s_add_u32 s40, s40, 0x40000
	s_addc_u32 s41, s41, 0
	s_mov_b32 m0, s54
	v_lshl_add_u64 v[222:223], s[40:41], 0, v[134:135]
	ds_read_b128 v[184:187], v165 offset:32768
	ds_read_b128 v[188:191], v165 offset:33792
	ds_read_b128 v[192:195], v165 offset:34816
	ds_read_b128 v[196:199], v165 offset:35840
	ds_read_b128 v[200:203], v165 offset:36864
	ds_read_b128 v[204:207], v165 offset:37888
	ds_read_b128 v[208:211], v165 offset:38912
	ds_read_b128 v[212:215], v165 offset:39936
	global_load_lds_dwordx4 v[222:223], off
	s_mov_b32 m0, s55
	v_lshl_add_u64 v[222:223], s[40:41], 0, v[130:131]
	global_load_lds_dwordx4 v[222:223], off
	s_waitcnt vmcnt(8) lgkmcnt(0)
	s_barrier
	s_setprio 1
	v_mfma_f32_16x16x32_bf16 v[124:127], v[144:147], v[184:187], v[124:127]
	v_mfma_f32_16x16x32_bf16 v[120:123], v[152:155], v[184:187], v[120:123]
	v_mfma_f32_16x16x32_bf16 v[108:111], v[144:147], v[192:195], v[108:111]
	v_mfma_f32_16x16x32_bf16 v[104:107], v[152:155], v[192:195], v[104:107]
	v_mfma_f32_16x16x32_bf16 v[92:95], v[144:147], v[200:203], v[92:95]
	v_mfma_f32_16x16x32_bf16 v[88:91], v[152:155], v[200:203], v[88:91]
	v_mfma_f32_16x16x32_bf16 v[76:79], v[144:147], v[208:211], v[76:79]
	v_mfma_f32_16x16x32_bf16 v[72:75], v[152:155], v[208:211], v[72:75]
	v_mfma_f32_16x16x32_bf16 v[124:127], v[148:151], v[188:191], v[124:127]
	v_mfma_f32_16x16x32_bf16 v[120:123], v[156:159], v[188:191], v[120:123]
	v_mfma_f32_16x16x32_bf16 v[108:111], v[148:151], v[196:199], v[108:111]
	v_mfma_f32_16x16x32_bf16 v[104:107], v[156:159], v[196:199], v[104:107]
	v_mfma_f32_16x16x32_bf16 v[92:95], v[148:151], v[204:207], v[92:95]
	v_mfma_f32_16x16x32_bf16 v[88:91], v[156:159], v[204:207], v[88:91]
	v_mfma_f32_16x16x32_bf16 v[76:79], v[148:151], v[212:215], v[76:79]
	v_mfma_f32_16x16x32_bf16 v[72:75], v[156:159], v[212:215], v[72:75]
	s_setprio 0
	s_setprio 1
	v_mfma_f32_16x16x32_bf16 v[116:119], v[168:171], v[184:187], v[116:119]
	v_mfma_f32_16x16x32_bf16 v[112:115], v[176:179], v[184:187], v[112:115]
	v_mfma_f32_16x16x32_bf16 v[100:103], v[168:171], v[192:195], v[100:103]
	v_mfma_f32_16x16x32_bf16 v[96:99], v[176:179], v[192:195], v[96:99]
	v_mfma_f32_16x16x32_bf16 v[84:87], v[168:171], v[200:203], v[84:87]
	v_mfma_f32_16x16x32_bf16 v[80:83], v[176:179], v[200:203], v[80:83]
	v_mfma_f32_16x16x32_bf16 v[68:71], v[168:171], v[208:211], v[68:71]
	v_mfma_f32_16x16x32_bf16 v[64:67], v[176:179], v[208:211], v[64:67]
	v_mfma_f32_16x16x32_bf16 v[116:119], v[172:175], v[188:191], v[116:119]
	v_mfma_f32_16x16x32_bf16 v[112:115], v[180:183], v[188:191], v[112:115]
	v_mfma_f32_16x16x32_bf16 v[100:103], v[172:175], v[196:199], v[100:103]
	v_mfma_f32_16x16x32_bf16 v[96:99], v[180:183], v[196:199], v[96:99]
	s_setprio 2
	s_barrier
	v_mfma_f32_16x16x32_bf16 v[84:87], v[172:175], v[204:207], v[84:87]
	v_mfma_f32_16x16x32_bf16 v[80:83], v[180:183], v[204:207], v[80:83]
	v_mfma_f32_16x16x32_bf16 v[68:71], v[172:175], v[212:215], v[68:71]
	v_mfma_f32_16x16x32_bf16 v[64:67], v[180:183], v[212:215], v[64:67]
	s_setprio 2
	s_add_i32 s40, s66, s47
	v_lshl_add_u64 v[160:161], v[160:161], 0, s[16:17]
	s_mov_b32 m0, s40
	ds_read_b128 v[184:187], v165 offset:49152
	ds_read_b128 v[188:191], v165 offset:50176
	ds_read_b128 v[192:195], v165 offset:51200
	ds_read_b128 v[196:199], v165 offset:52224
	ds_read_b128 v[200:203], v165 offset:53248
	ds_read_b128 v[204:207], v165 offset:54272
	ds_read_b128 v[208:211], v165 offset:55296
	ds_read_b128 v[212:215], v165 offset:56320
	global_load_lds_dwordx4 v[160:161], off
	s_add_i32 m0, s40, 0x2000
	s_add_u32 s38, s38, 0x40080
	v_lshl_add_u64 v[160:161], v[216:217], 0, s[16:17]
	s_addc_u32 s39, s39, 0
	s_add_i32 s40, s67, s47
	global_load_lds_dwordx4 v[160:161], off
	s_mov_b32 m0, s40
	v_lshl_add_u64 v[160:161], s[38:39], 0, v[132:133]
	global_load_lds_dwordx4 v[160:161], off
	s_add_i32 m0, s40, 0x2000
	v_lshl_add_u64 v[160:161], s[38:39], 0, v[128:129]
	global_load_lds_dwordx4 v[160:161], off
	s_mov_b32 m0, s57
	v_lshl_add_u64 v[160:161], v[218:219], 0, s[16:17]
	global_load_lds_dwordx4 v[160:161], off
	s_mov_b32 m0, s58
	v_lshl_add_u64 v[160:161], v[220:221], 0, s[16:17]
	global_load_lds_dwordx4 v[160:161], off
	s_waitcnt vmcnt(8) lgkmcnt(0)
	s_barrier
	s_setprio 1
	v_mfma_f32_16x16x32_bf16 v[60:63], v[144:147], v[184:187], v[60:63]
	v_mfma_f32_16x16x32_bf16 v[56:59], v[152:155], v[184:187], v[56:59]
	v_mfma_f32_16x16x32_bf16 v[44:47], v[144:147], v[192:195], v[44:47]
	v_mfma_f32_16x16x32_bf16 v[40:43], v[152:155], v[192:195], v[40:43]
	v_mfma_f32_16x16x32_bf16 v[28:31], v[144:147], v[200:203], v[28:31]
	v_mfma_f32_16x16x32_bf16 v[24:27], v[152:155], v[200:203], v[24:27]
	v_mfma_f32_16x16x32_bf16 v[12:15], v[144:147], v[208:211], v[12:15]
	v_mfma_f32_16x16x32_bf16 v[8:11], v[152:155], v[208:211], v[8:11]
	v_mfma_f32_16x16x32_bf16 v[60:63], v[148:151], v[188:191], v[60:63]
	v_mfma_f32_16x16x32_bf16 v[56:59], v[156:159], v[188:191], v[56:59]
	v_mfma_f32_16x16x32_bf16 v[44:47], v[148:151], v[196:199], v[44:47]
	v_mfma_f32_16x16x32_bf16 v[40:43], v[156:159], v[196:199], v[40:43]
	v_mfma_f32_16x16x32_bf16 v[28:31], v[148:151], v[204:207], v[28:31]
	v_mfma_f32_16x16x32_bf16 v[24:27], v[156:159], v[204:207], v[24:27]
	v_mfma_f32_16x16x32_bf16 v[12:15], v[148:151], v[212:215], v[12:15]
	v_mfma_f32_16x16x32_bf16 v[8:11], v[156:159], v[212:215], v[8:11]
	s_setprio 0
	s_setprio 1
	v_mfma_f32_16x16x32_bf16 v[52:55], v[168:171], v[184:187], v[52:55]
	v_mfma_f32_16x16x32_bf16 v[48:51], v[176:179], v[184:187], v[48:51]
	v_mfma_f32_16x16x32_bf16 v[36:39], v[168:171], v[192:195], v[36:39]
	v_mfma_f32_16x16x32_bf16 v[32:35], v[176:179], v[192:195], v[32:35]
	v_mfma_f32_16x16x32_bf16 v[20:23], v[168:171], v[200:203], v[20:23]
	v_mfma_f32_16x16x32_bf16 v[16:19], v[176:179], v[200:203], v[16:19]
	v_mfma_f32_16x16x32_bf16 v[4:7], v[168:171], v[208:211], v[4:7]
	v_mfma_f32_16x16x32_bf16 v[0:3], v[176:179], v[208:211], v[0:3]
	v_mfma_f32_16x16x32_bf16 v[52:55], v[172:175], v[188:191], v[52:55]
	v_mfma_f32_16x16x32_bf16 v[48:51], v[180:183], v[188:191], v[48:51]
	v_mfma_f32_16x16x32_bf16 v[36:39], v[172:175], v[196:199], v[36:39]
	v_mfma_f32_16x16x32_bf16 v[32:35], v[180:183], v[196:199], v[32:35]
	s_setprio 2
	s_barrier
	v_mfma_f32_16x16x32_bf16 v[20:23], v[172:175], v[204:207], v[20:23]
	v_mfma_f32_16x16x32_bf16 v[16:19], v[180:183], v[204:207], v[16:19]
	v_mfma_f32_16x16x32_bf16 v[4:7], v[172:175], v[212:215], v[4:7]
	v_mfma_f32_16x16x32_bf16 v[0:3], v[180:183], v[212:215], v[0:3]
	s_setprio 0
	s_add_i32 s65, s65, 2
	s_add_u32 s36, s36, 0x100
	s_addc_u32 s37, s37, 0
	s_add_u32 s63, s63, 0x100
	s_addc_u32 s64, s64, 0
	s_cmp_gt_u32 s65, 13
.LBB0_784:
	ds_read_b128 v[144:147], v163
	ds_read_b128 v[148:151], v163 offset:1024
	ds_read_b128 v[152:155], v163 offset:2048
	ds_read_b128 v[156:159], v163 offset:3072
	ds_read_b128 v[168:171], v164
	ds_read_b128 v[172:175], v164 offset:1024
	ds_read_b128 v[176:179], v164 offset:2048
	ds_read_b128 v[180:183], v164 offset:3072
	s_add_u32 s38, s36, 0xfffc0080
	s_addc_u32 s39, s37, -1
	s_cmp_eq_u32 s65, 12
	s_cselect_b32 s41, s23, s39
	s_cselect_b32 s40, s31, s38
	s_cselect_b32 s39, s25, s64
	s_cselect_b32 s38, s62, s63
	v_lshl_add_u64 v[160:161], s[36:37], 0, v[136:137]
	s_add_i32 m0, s50, 0xc000
	ds_read_b128 v[184:187], v165
	ds_read_b128 v[188:191], v165 offset:1024
	ds_read_b128 v[192:195], v165 offset:2048
	ds_read_b128 v[196:199], v165 offset:3072
	ds_read_b128 v[200:203], v165 offset:4096
	ds_read_b128 v[204:207], v165 offset:5120
	ds_read_b128 v[208:211], v165 offset:6144
	ds_read_b128 v[212:215], v165 offset:7168
	global_load_lds_dwordx4 v[160:161], off
	s_add_i32 m0, s50, 0xe000
	v_lshl_add_u64 v[160:161], s[36:37], 0, v[138:139]
	global_load_lds_dwordx4 v[160:161], off
	s_waitcnt vmcnt(8) lgkmcnt(0)
	s_barrier
	s_setprio 1
	v_mfma_f32_16x16x32_bf16 v[124:127], v[144:147], v[184:187], v[124:127]
	v_mfma_f32_16x16x32_bf16 v[120:123], v[152:155], v[184:187], v[120:123]
	v_mfma_f32_16x16x32_bf16 v[108:111], v[144:147], v[192:195], v[108:111]
	v_mfma_f32_16x16x32_bf16 v[104:107], v[152:155], v[192:195], v[104:107]
	v_mfma_f32_16x16x32_bf16 v[92:95], v[144:147], v[200:203], v[92:95]
	v_mfma_f32_16x16x32_bf16 v[88:91], v[152:155], v[200:203], v[88:91]
	v_mfma_f32_16x16x32_bf16 v[76:79], v[144:147], v[208:211], v[76:79]
	v_mfma_f32_16x16x32_bf16 v[72:75], v[152:155], v[208:211], v[72:75]
	v_mfma_f32_16x16x32_bf16 v[124:127], v[148:151], v[188:191], v[124:127]
	v_mfma_f32_16x16x32_bf16 v[120:123], v[156:159], v[188:191], v[120:123]
	v_mfma_f32_16x16x32_bf16 v[108:111], v[148:151], v[196:199], v[108:111]
	v_mfma_f32_16x16x32_bf16 v[104:107], v[156:159], v[196:199], v[104:107]
	v_mfma_f32_16x16x32_bf16 v[92:95], v[148:151], v[204:207], v[92:95]
	v_mfma_f32_16x16x32_bf16 v[88:91], v[156:159], v[204:207], v[88:91]
	v_mfma_f32_16x16x32_bf16 v[76:79], v[148:151], v[212:215], v[76:79]
	v_mfma_f32_16x16x32_bf16 v[72:75], v[156:159], v[212:215], v[72:75]
	s_setprio 0
	s_setprio 1
	v_mfma_f32_16x16x32_bf16 v[116:119], v[168:171], v[184:187], v[116:119]
	v_mfma_f32_16x16x32_bf16 v[112:115], v[176:179], v[184:187], v[112:115]
	v_mfma_f32_16x16x32_bf16 v[100:103], v[168:171], v[192:195], v[100:103]
	v_mfma_f32_16x16x32_bf16 v[96:99], v[176:179], v[192:195], v[96:99]
	v_mfma_f32_16x16x32_bf16 v[84:87], v[168:171], v[200:203], v[84:87]
	v_mfma_f32_16x16x32_bf16 v[80:83], v[176:179], v[200:203], v[80:83]
	v_mfma_f32_16x16x32_bf16 v[68:71], v[168:171], v[208:211], v[68:71]
	v_mfma_f32_16x16x32_bf16 v[64:67], v[176:179], v[208:211], v[64:67]
	v_mfma_f32_16x16x32_bf16 v[116:119], v[172:175], v[188:191], v[116:119]
	v_mfma_f32_16x16x32_bf16 v[112:115], v[180:183], v[188:191], v[112:115]
	v_mfma_f32_16x16x32_bf16 v[100:103], v[172:175], v[196:199], v[100:103]
	v_mfma_f32_16x16x32_bf16 v[96:99], v[180:183], v[196:199], v[96:99]
	s_setprio 2
	s_barrier
	v_mfma_f32_16x16x32_bf16 v[84:87], v[172:175], v[204:207], v[84:87]
	v_mfma_f32_16x16x32_bf16 v[80:83], v[180:183], v[204:207], v[80:83]
	v_mfma_f32_16x16x32_bf16 v[68:71], v[172:175], v[212:215], v[68:71]
	v_mfma_f32_16x16x32_bf16 v[64:67], v[180:183], v[212:215], v[64:67]
	s_setprio 2
	s_add_i32 s66, s59, s47
	v_lshl_add_u64 v[160:161], s[38:39], 0, v[132:133]
	s_mov_b32 m0, s66
	ds_read_b128 v[184:187], v165 offset:16384
	ds_read_b128 v[188:191], v165 offset:17408
	ds_read_b128 v[192:195], v165 offset:18432
	ds_read_b128 v[196:199], v165 offset:19456
	ds_read_b128 v[200:203], v165 offset:20480
	ds_read_b128 v[204:207], v165 offset:21504
	ds_read_b128 v[208:211], v165 offset:22528
	ds_read_b128 v[212:215], v165 offset:23552
	global_load_lds_dwordx4 v[160:161], off
	s_add_i32 m0, s66, 0x2000
	s_add_u32 s66, s38, 0x40000
	v_lshl_add_u64 v[216:217], s[38:39], 0, v[128:129]
	s_addc_u32 s67, s39, 0
	s_add_i32 s68, s60, s47
	global_load_lds_dwordx4 v[216:217], off
	v_lshl_add_u64 v[218:219], s[66:67], 0, v[132:133]
	s_mov_b32 m0, s68
	v_lshl_add_u64 v[220:221], s[40:41], 0, v[130:131]
	global_load_lds_dwordx4 v[218:219], off
	s_add_i32 m0, s68, 0x2000
	v_lshl_add_u64 v[218:219], s[66:67], 0, v[128:129]
	global_load_lds_dwordx4 v[218:219], off
	s_mov_b32 m0, s50
	v_lshl_add_u64 v[218:219], s[40:41], 0, v[134:135]
	global_load_lds_dwordx4 v[218:219], off
	s_mov_b32 m0, s51
	s_nop 0
	global_load_lds_dwordx4 v[220:221], off
	s_waitcnt vmcnt(8) lgkmcnt(0)
	s_barrier
	s_setprio 1
	v_mfma_f32_16x16x32_bf16 v[60:63], v[144:147], v[184:187], v[60:63]
	v_mfma_f32_16x16x32_bf16 v[56:59], v[152:155], v[184:187], v[56:59]
	v_mfma_f32_16x16x32_bf16 v[44:47], v[144:147], v[192:195], v[44:47]
	v_mfma_f32_16x16x32_bf16 v[40:43], v[152:155], v[192:195], v[40:43]
	v_mfma_f32_16x16x32_bf16 v[28:31], v[144:147], v[200:203], v[28:31]
	v_mfma_f32_16x16x32_bf16 v[24:27], v[152:155], v[200:203], v[24:27]
	v_mfma_f32_16x16x32_bf16 v[12:15], v[144:147], v[208:211], v[12:15]
	v_mfma_f32_16x16x32_bf16 v[8:11], v[152:155], v[208:211], v[8:11]
	v_mfma_f32_16x16x32_bf16 v[60:63], v[148:151], v[188:191], v[60:63]
	v_mfma_f32_16x16x32_bf16 v[56:59], v[156:159], v[188:191], v[56:59]
	v_mfma_f32_16x16x32_bf16 v[44:47], v[148:151], v[196:199], v[44:47]
	v_mfma_f32_16x16x32_bf16 v[40:43], v[156:159], v[196:199], v[40:43]
	v_mfma_f32_16x16x32_bf16 v[28:31], v[148:151], v[204:207], v[28:31]
	v_mfma_f32_16x16x32_bf16 v[24:27], v[156:159], v[204:207], v[24:27]
	v_mfma_f32_16x16x32_bf16 v[12:15], v[148:151], v[212:215], v[12:15]
	v_mfma_f32_16x16x32_bf16 v[8:11], v[156:159], v[212:215], v[8:11]
	s_setprio 0
	s_setprio 1
	v_mfma_f32_16x16x32_bf16 v[52:55], v[168:171], v[184:187], v[52:55]
	v_mfma_f32_16x16x32_bf16 v[48:51], v[176:179], v[184:187], v[48:51]
	v_mfma_f32_16x16x32_bf16 v[36:39], v[168:171], v[192:195], v[36:39]
	v_mfma_f32_16x16x32_bf16 v[32:35], v[176:179], v[192:195], v[32:35]
	v_mfma_f32_16x16x32_bf16 v[20:23], v[168:171], v[200:203], v[20:23]
	v_mfma_f32_16x16x32_bf16 v[16:19], v[176:179], v[200:203], v[16:19]
	v_mfma_f32_16x16x32_bf16 v[4:7], v[168:171], v[208:211], v[4:7]
	v_mfma_f32_16x16x32_bf16 v[0:3], v[176:179], v[208:211], v[0:3]
	v_mfma_f32_16x16x32_bf16 v[52:55], v[172:175], v[188:191], v[52:55]
	v_mfma_f32_16x16x32_bf16 v[48:51], v[180:183], v[188:191], v[48:51]
	v_mfma_f32_16x16x32_bf16 v[36:39], v[172:175], v[196:199], v[36:39]
	v_mfma_f32_16x16x32_bf16 v[32:35], v[180:183], v[196:199], v[32:35]
	s_setprio 2
	s_barrier
	v_mfma_f32_16x16x32_bf16 v[20:23], v[172:175], v[204:207], v[20:23]
	v_mfma_f32_16x16x32_bf16 v[16:19], v[180:183], v[204:207], v[16:19]
	v_mfma_f32_16x16x32_bf16 v[4:7], v[172:175], v[212:215], v[4:7]
	v_mfma_f32_16x16x32_bf16 v[0:3], v[180:183], v[212:215], v[0:3]
	s_setprio 0
	s_add_i32 s66, 0, 0x18000
	s_add_i32 s67, 0, 0x1c000
	v_add_u32_e32 v156, s66, v162
	v_add_u32_e32 v167, s67, v162
	ds_read_b128 v[144:147], v156
	ds_read_b128 v[148:151], v156 offset:1024
	ds_read_b128 v[152:155], v156 offset:2048
	ds_read_b128 v[156:159], v156 offset:3072
	ds_read_b128 v[168:171], v167
	ds_read_b128 v[172:175], v167 offset:1024
	ds_read_b128 v[176:179], v167 offset:2048
	ds_read_b128 v[180:183], v167 offset:3072
	s_add_u32 s40, s40, 0x40000
	s_addc_u32 s41, s41, 0
	s_mov_b32 m0, s54
	v_lshl_add_u64 v[222:223], s[40:41], 0, v[134:135]
	ds_read_b128 v[184:187], v165 offset:32768
	ds_read_b128 v[188:191], v165 offset:33792
	ds_read_b128 v[192:195], v165 offset:34816
	ds_read_b128 v[196:199], v165 offset:35840
	ds_read_b128 v[200:203], v165 offset:36864
	ds_read_b128 v[204:207], v165 offset:37888
	ds_read_b128 v[208:211], v165 offset:38912
	ds_read_b128 v[212:215], v165 offset:39936
	global_load_lds_dwordx4 v[222:223], off
	s_mov_b32 m0, s55
	v_lshl_add_u64 v[222:223], s[40:41], 0, v[130:131]
	global_load_lds_dwordx4 v[222:223], off
	s_waitcnt vmcnt(8) lgkmcnt(0)
	s_barrier
	s_setprio 1
	v_mfma_f32_16x16x32_bf16 v[124:127], v[144:147], v[184:187], v[124:127]
	v_mfma_f32_16x16x32_bf16 v[120:123], v[152:155], v[184:187], v[120:123]
	v_mfma_f32_16x16x32_bf16 v[108:111], v[144:147], v[192:195], v[108:111]
	v_mfma_f32_16x16x32_bf16 v[104:107], v[152:155], v[192:195], v[104:107]
	v_mfma_f32_16x16x32_bf16 v[92:95], v[144:147], v[200:203], v[92:95]
	v_mfma_f32_16x16x32_bf16 v[88:91], v[152:155], v[200:203], v[88:91]
	v_mfma_f32_16x16x32_bf16 v[76:79], v[144:147], v[208:211], v[76:79]
	v_mfma_f32_16x16x32_bf16 v[72:75], v[152:155], v[208:211], v[72:75]
	v_mfma_f32_16x16x32_bf16 v[124:127], v[148:151], v[188:191], v[124:127]
	v_mfma_f32_16x16x32_bf16 v[120:123], v[156:159], v[188:191], v[120:123]
	v_mfma_f32_16x16x32_bf16 v[108:111], v[148:151], v[196:199], v[108:111]
	v_mfma_f32_16x16x32_bf16 v[104:107], v[156:159], v[196:199], v[104:107]
	v_mfma_f32_16x16x32_bf16 v[92:95], v[148:151], v[204:207], v[92:95]
	v_mfma_f32_16x16x32_bf16 v[88:91], v[156:159], v[204:207], v[88:91]
	v_mfma_f32_16x16x32_bf16 v[76:79], v[148:151], v[212:215], v[76:79]
	v_mfma_f32_16x16x32_bf16 v[72:75], v[156:159], v[212:215], v[72:75]
	s_setprio 0
	s_setprio 1
	v_mfma_f32_16x16x32_bf16 v[116:119], v[168:171], v[184:187], v[116:119]
	v_mfma_f32_16x16x32_bf16 v[112:115], v[176:179], v[184:187], v[112:115]
	v_mfma_f32_16x16x32_bf16 v[100:103], v[168:171], v[192:195], v[100:103]
	v_mfma_f32_16x16x32_bf16 v[96:99], v[176:179], v[192:195], v[96:99]
	v_mfma_f32_16x16x32_bf16 v[84:87], v[168:171], v[200:203], v[84:87]
	v_mfma_f32_16x16x32_bf16 v[80:83], v[176:179], v[200:203], v[80:83]
	v_mfma_f32_16x16x32_bf16 v[68:71], v[168:171], v[208:211], v[68:71]
	v_mfma_f32_16x16x32_bf16 v[64:67], v[176:179], v[208:211], v[64:67]
	v_mfma_f32_16x16x32_bf16 v[116:119], v[172:175], v[188:191], v[116:119]
	v_mfma_f32_16x16x32_bf16 v[112:115], v[180:183], v[188:191], v[112:115]
	v_mfma_f32_16x16x32_bf16 v[100:103], v[172:175], v[196:199], v[100:103]
	v_mfma_f32_16x16x32_bf16 v[96:99], v[180:183], v[196:199], v[96:99]
	s_setprio 2
	s_barrier
	v_mfma_f32_16x16x32_bf16 v[84:87], v[172:175], v[204:207], v[84:87]
	v_mfma_f32_16x16x32_bf16 v[80:83], v[180:183], v[204:207], v[80:83]
	v_mfma_f32_16x16x32_bf16 v[68:71], v[172:175], v[212:215], v[68:71]
	v_mfma_f32_16x16x32_bf16 v[64:67], v[180:183], v[212:215], v[64:67]
	s_setprio 2
	s_add_i32 s40, s66, s47
	v_lshl_add_u64 v[160:161], v[160:161], 0, s[16:17]
	s_mov_b32 m0, s40
	ds_read_b128 v[184:187], v165 offset:49152
	ds_read_b128 v[188:191], v165 offset:50176
	ds_read_b128 v[192:195], v165 offset:51200
	ds_read_b128 v[196:199], v165 offset:52224
	ds_read_b128 v[200:203], v165 offset:53248
	ds_read_b128 v[204:207], v165 offset:54272
	ds_read_b128 v[208:211], v165 offset:55296
	ds_read_b128 v[212:215], v165 offset:56320
	global_load_lds_dwordx4 v[160:161], off
	s_add_i32 m0, s40, 0x2000
	s_add_u32 s38, s38, 0x40080
	v_lshl_add_u64 v[160:161], v[216:217], 0, s[16:17]
	s_addc_u32 s39, s39, 0
	s_add_i32 s40, s67, s47
	global_load_lds_dwordx4 v[160:161], off
	s_mov_b32 m0, s40
	v_lshl_add_u64 v[160:161], s[38:39], 0, v[132:133]
	global_load_lds_dwordx4 v[160:161], off
	s_add_i32 m0, s40, 0x2000
	v_lshl_add_u64 v[160:161], s[38:39], 0, v[128:129]
	global_load_lds_dwordx4 v[160:161], off
	s_mov_b32 m0, s57
	v_lshl_add_u64 v[160:161], v[218:219], 0, s[16:17]
	global_load_lds_dwordx4 v[160:161], off
	s_mov_b32 m0, s58
	v_lshl_add_u64 v[160:161], v[220:221], 0, s[16:17]
	global_load_lds_dwordx4 v[160:161], off
	s_waitcnt vmcnt(8) lgkmcnt(0)
	s_barrier
	s_setprio 1
	v_mfma_f32_16x16x32_bf16 v[60:63], v[144:147], v[184:187], v[60:63]
	v_mfma_f32_16x16x32_bf16 v[56:59], v[152:155], v[184:187], v[56:59]
	v_mfma_f32_16x16x32_bf16 v[44:47], v[144:147], v[192:195], v[44:47]
	v_mfma_f32_16x16x32_bf16 v[40:43], v[152:155], v[192:195], v[40:43]
	v_mfma_f32_16x16x32_bf16 v[28:31], v[144:147], v[200:203], v[28:31]
	v_mfma_f32_16x16x32_bf16 v[24:27], v[152:155], v[200:203], v[24:27]
	v_mfma_f32_16x16x32_bf16 v[12:15], v[144:147], v[208:211], v[12:15]
	v_mfma_f32_16x16x32_bf16 v[8:11], v[152:155], v[208:211], v[8:11]
	v_mfma_f32_16x16x32_bf16 v[60:63], v[148:151], v[188:191], v[60:63]
	v_mfma_f32_16x16x32_bf16 v[56:59], v[156:159], v[188:191], v[56:59]
	v_mfma_f32_16x16x32_bf16 v[44:47], v[148:151], v[196:199], v[44:47]
	v_mfma_f32_16x16x32_bf16 v[40:43], v[156:159], v[196:199], v[40:43]
	v_mfma_f32_16x16x32_bf16 v[28:31], v[148:151], v[204:207], v[28:31]
	v_mfma_f32_16x16x32_bf16 v[24:27], v[156:159], v[204:207], v[24:27]
	v_mfma_f32_16x16x32_bf16 v[12:15], v[148:151], v[212:215], v[12:15]
	v_mfma_f32_16x16x32_bf16 v[8:11], v[156:159], v[212:215], v[8:11]
	s_setprio 0
	s_setprio 1
	v_mfma_f32_16x16x32_bf16 v[52:55], v[168:171], v[184:187], v[52:55]
	v_mfma_f32_16x16x32_bf16 v[48:51], v[176:179], v[184:187], v[48:51]
	v_mfma_f32_16x16x32_bf16 v[36:39], v[168:171], v[192:195], v[36:39]
	v_mfma_f32_16x16x32_bf16 v[32:35], v[176:179], v[192:195], v[32:35]
	v_mfma_f32_16x16x32_bf16 v[20:23], v[168:171], v[200:203], v[20:23]
	v_mfma_f32_16x16x32_bf16 v[16:19], v[176:179], v[200:203], v[16:19]
	v_mfma_f32_16x16x32_bf16 v[4:7], v[168:171], v[208:211], v[4:7]
	v_mfma_f32_16x16x32_bf16 v[0:3], v[176:179], v[208:211], v[0:3]
	v_mfma_f32_16x16x32_bf16 v[52:55], v[172:175], v[188:191], v[52:55]
	v_mfma_f32_16x16x32_bf16 v[48:51], v[180:183], v[188:191], v[48:51]
	v_mfma_f32_16x16x32_bf16 v[36:39], v[172:175], v[196:199], v[36:39]
	v_mfma_f32_16x16x32_bf16 v[32:35], v[180:183], v[196:199], v[32:35]
	s_setprio 2
	s_barrier
	v_mfma_f32_16x16x32_bf16 v[20:23], v[172:175], v[204:207], v[20:23]
	v_mfma_f32_16x16x32_bf16 v[16:19], v[180:183], v[204:207], v[16:19]
	v_mfma_f32_16x16x32_bf16 v[4:7], v[172:175], v[212:215], v[4:7]
	v_mfma_f32_16x16x32_bf16 v[0:3], v[180:183], v[212:215], v[0:3]
	s_setprio 0
	s_add_i32 s65, s65, 2
	s_add_u32 s36, s36, 0x100
	s_addc_u32 s37, s37, 0
	s_add_u32 s63, s63, 0x100
	s_addc_u32 s64, s64, 0
	s_cmp_gt_u32 s65, 13
	s_cbranch_scc0 .LBB0_784

.LBB0_865:
	s_add_u32 s62, s28, 0x100
	s_addc_u32 s63, s29, 0
	s_mov_b32 s64, -2
	ds_read_b128 v[120:123], v233
	ds_read_b128 v[124:127], v233 offset:1024
	ds_read_b128 v[136:139], v233 offset:2048
	ds_read_b128 v[140:143], v233 offset:3072
	ds_read_b128 v[144:147], v234
	ds_read_b128 v[148:151], v234 offset:1024
	ds_read_b128 v[152:155], v234 offset:2048
	ds_read_b128 v[156:159], v234 offset:3072
	s_add_u32 s28, s26, 0x100
	s_addc_u32 s29, s27, 0
	s_cmp_eq_u32 s64, 40
	s_cselect_b32 s37, s7, s29
	s_cselect_b32 s36, s6, s28
	s_cselect_b32 s31, s25, s63
	s_cselect_b32 s30, s24, s62
	v_lshl_add_u64 v[208:209], s[26:27], 0, v[192:193]
	s_add_i32 m0, s44, 0xc000
	ds_read_b128 v[160:163], v235
	ds_read_b128 v[164:167], v235 offset:1024
	ds_read_b128 v[168:171], v235 offset:2048
	ds_read_b128 v[172:175], v235 offset:3072
	ds_read_b128 v[176:179], v235 offset:4096
	ds_read_b128 v[180:183], v235 offset:5120
	ds_read_b128 v[200:203], v235 offset:6144
	ds_read_b128 v[204:207], v235 offset:7168
	global_load_lds_dwordx4 v[208:209], off
	s_add_i32 m0, s44, 0xe000
	v_lshl_add_u64 v[208:209], s[26:27], 0, v[194:195]
	global_load_lds_dwordx4 v[208:209], off
	s_waitcnt vmcnt(8) lgkmcnt(0)
	s_barrier
	s_setprio 1
	v_mfma_f32_16x16x32_bf16 v[132:135], v[120:123], v[160:163], 0
	v_mfma_f32_16x16x32_bf16 v[128:131], v[136:139], v[160:163], 0
	v_mfma_f32_16x16x32_bf16 v[108:111], v[120:123], v[168:171], 0
	v_mfma_f32_16x16x32_bf16 v[104:107], v[136:139], v[168:171], 0
	v_mfma_f32_16x16x32_bf16 v[92:95], v[120:123], v[176:179], 0
	v_mfma_f32_16x16x32_bf16 v[88:91], v[136:139], v[176:179], 0
	v_mfma_f32_16x16x32_bf16 v[76:79], v[120:123], v[200:203], 0
	v_mfma_f32_16x16x32_bf16 v[72:75], v[136:139], v[200:203], 0
	v_mfma_f32_16x16x32_bf16 v[132:135], v[124:127], v[164:167], v[132:135]
	v_mfma_f32_16x16x32_bf16 v[128:131], v[140:143], v[164:167], v[128:131]
	v_mfma_f32_16x16x32_bf16 v[108:111], v[124:127], v[172:175], v[108:111]
	v_mfma_f32_16x16x32_bf16 v[104:107], v[140:143], v[172:175], v[104:107]
	v_mfma_f32_16x16x32_bf16 v[92:95], v[124:127], v[180:183], v[92:95]
	v_mfma_f32_16x16x32_bf16 v[88:91], v[140:143], v[180:183], v[88:91]
	v_mfma_f32_16x16x32_bf16 v[76:79], v[124:127], v[204:207], v[76:79]
	v_mfma_f32_16x16x32_bf16 v[72:75], v[140:143], v[204:207], v[72:75]
	s_setprio 0
	s_setprio 1
	v_mfma_f32_16x16x32_bf16 v[116:119], v[144:147], v[160:163], 0
	v_mfma_f32_16x16x32_bf16 v[112:115], v[152:155], v[160:163], 0
	v_mfma_f32_16x16x32_bf16 v[100:103], v[144:147], v[168:171], 0
	v_mfma_f32_16x16x32_bf16 v[96:99], v[152:155], v[168:171], 0
	v_mfma_f32_16x16x32_bf16 v[84:87], v[144:147], v[176:179], 0
	v_mfma_f32_16x16x32_bf16 v[80:83], v[152:155], v[176:179], 0
	v_mfma_f32_16x16x32_bf16 v[68:71], v[144:147], v[200:203], 0
	v_mfma_f32_16x16x32_bf16 v[64:67], v[152:155], v[200:203], 0
	v_mfma_f32_16x16x32_bf16 v[116:119], v[148:151], v[164:167], v[116:119]
	v_mfma_f32_16x16x32_bf16 v[112:115], v[156:159], v[164:167], v[112:115]
	v_mfma_f32_16x16x32_bf16 v[100:103], v[148:151], v[172:175], v[100:103]
	v_mfma_f32_16x16x32_bf16 v[96:99], v[156:159], v[172:175], v[96:99]
	s_setprio 2
	s_barrier
	v_mfma_f32_16x16x32_bf16 v[84:87], v[148:151], v[180:183], v[84:87]
	v_mfma_f32_16x16x32_bf16 v[80:83], v[156:159], v[180:183], v[80:83]
	v_mfma_f32_16x16x32_bf16 v[68:71], v[148:151], v[204:207], v[68:71]
	v_mfma_f32_16x16x32_bf16 v[64:67], v[156:159], v[204:207], v[64:67]
	s_setprio 2
	s_add_i32 s26, s56, s43
	v_lshl_add_u64 v[208:209], s[30:31], 0, v[186:187]
	s_mov_b32 m0, s26
	ds_read_b128 v[160:163], v235 offset:16384
	ds_read_b128 v[164:167], v235 offset:17408
	ds_read_b128 v[168:171], v235 offset:18432
	ds_read_b128 v[172:175], v235 offset:19456
	ds_read_b128 v[176:179], v235 offset:20480
	ds_read_b128 v[180:183], v235 offset:21504
	ds_read_b128 v[200:203], v235 offset:22528
	ds_read_b128 v[204:207], v235 offset:23552
	global_load_lds_dwordx4 v[208:209], off
	s_add_i32 m0, s26, 0x2000
	s_add_u32 s26, s30, 0xb0000
	v_lshl_add_u64 v[210:211], s[30:31], 0, v[190:191]
	s_addc_u32 s27, s31, 0
	s_add_i32 s65, s57, s43
	global_load_lds_dwordx4 v[210:211], off
	v_lshl_add_u64 v[212:213], s[26:27], 0, v[186:187]
	s_mov_b32 m0, s65
	v_lshl_add_u64 v[214:215], s[36:37], 0, v[188:189]
	global_load_lds_dwordx4 v[212:213], off
	s_add_i32 m0, s65, 0x2000
	v_lshl_add_u64 v[212:213], s[26:27], 0, v[190:191]
	global_load_lds_dwordx4 v[212:213], off
	s_mov_b32 m0, s44
	v_lshl_add_u64 v[212:213], s[36:37], 0, v[184:185]
	global_load_lds_dwordx4 v[212:213], off
	s_mov_b32 m0, s45
	s_nop 0
	global_load_lds_dwordx4 v[214:215], off
	s_waitcnt vmcnt(8) lgkmcnt(0)
	s_barrier
	s_setprio 1
	v_mfma_f32_16x16x32_bf16 v[60:63], v[120:123], v[160:163], 0
	v_mfma_f32_16x16x32_bf16 v[56:59], v[136:139], v[160:163], 0
	v_mfma_f32_16x16x32_bf16 v[44:47], v[120:123], v[168:171], 0
	v_mfma_f32_16x16x32_bf16 v[40:43], v[136:139], v[168:171], 0
	v_mfma_f32_16x16x32_bf16 v[28:31], v[120:123], v[176:179], 0
	v_mfma_f32_16x16x32_bf16 v[24:27], v[136:139], v[176:179], 0
	v_mfma_f32_16x16x32_bf16 v[12:15], v[120:123], v[200:203], 0
	v_mfma_f32_16x16x32_bf16 v[8:11], v[136:139], v[200:203], 0
	v_mfma_f32_16x16x32_bf16 v[60:63], v[124:127], v[164:167], v[60:63]
	v_mfma_f32_16x16x32_bf16 v[56:59], v[140:143], v[164:167], v[56:59]
	v_mfma_f32_16x16x32_bf16 v[44:47], v[124:127], v[172:175], v[44:47]
	v_mfma_f32_16x16x32_bf16 v[40:43], v[140:143], v[172:175], v[40:43]
	v_mfma_f32_16x16x32_bf16 v[28:31], v[124:127], v[180:183], v[28:31]
	v_mfma_f32_16x16x32_bf16 v[24:27], v[140:143], v[180:183], v[24:27]
	v_mfma_f32_16x16x32_bf16 v[12:15], v[124:127], v[204:207], v[12:15]
	v_mfma_f32_16x16x32_bf16 v[8:11], v[140:143], v[204:207], v[8:11]
	s_setprio 0
	s_setprio 1
	v_mfma_f32_16x16x32_bf16 v[52:55], v[144:147], v[160:163], 0
	v_mfma_f32_16x16x32_bf16 v[48:51], v[152:155], v[160:163], 0
	v_mfma_f32_16x16x32_bf16 v[36:39], v[144:147], v[168:171], 0
	v_mfma_f32_16x16x32_bf16 v[32:35], v[152:155], v[168:171], 0
	v_mfma_f32_16x16x32_bf16 v[20:23], v[144:147], v[176:179], 0
	v_mfma_f32_16x16x32_bf16 v[16:19], v[152:155], v[176:179], 0
	v_mfma_f32_16x16x32_bf16 v[4:7], v[144:147], v[200:203], 0
	v_mfma_f32_16x16x32_bf16 v[0:3], v[152:155], v[200:203], 0
	v_mfma_f32_16x16x32_bf16 v[52:55], v[148:151], v[164:167], v[52:55]
	v_mfma_f32_16x16x32_bf16 v[48:51], v[156:159], v[164:167], v[48:51]
	v_mfma_f32_16x16x32_bf16 v[36:39], v[148:151], v[172:175], v[36:39]
	v_mfma_f32_16x16x32_bf16 v[32:35], v[156:159], v[172:175], v[32:35]
	s_setprio 2
	s_barrier
	v_mfma_f32_16x16x32_bf16 v[20:23], v[148:151], v[180:183], v[20:23]
	v_mfma_f32_16x16x32_bf16 v[16:19], v[156:159], v[180:183], v[16:19]
	v_mfma_f32_16x16x32_bf16 v[4:7], v[148:151], v[204:207], v[4:7]
	v_mfma_f32_16x16x32_bf16 v[0:3], v[156:159], v[204:207], v[0:3]
	s_setprio 0
	s_add_i32 s65, 0, 0x18000
	s_add_i32 s66, 0, 0x1c000
	v_add_u32_e32 v140, s65, v232
	v_add_u32_e32 v156, s66, v232
	ds_read_b128 v[120:123], v140
	ds_read_b128 v[124:127], v140 offset:1024
	ds_read_b128 v[136:139], v140 offset:2048
	ds_read_b128 v[140:143], v140 offset:3072
	ds_read_b128 v[144:147], v156
	ds_read_b128 v[148:151], v156 offset:1024
	ds_read_b128 v[152:155], v156 offset:2048
	ds_read_b128 v[156:159], v156 offset:3072
	s_add_u32 s26, s36, 0xb0000
	s_addc_u32 s27, s37, 0
	s_mov_b32 m0, s46
	v_lshl_add_u64 v[216:217], s[26:27], 0, v[184:185]
	ds_read_b128 v[160:163], v235 offset:32768
	ds_read_b128 v[164:167], v235 offset:33792
	ds_read_b128 v[168:171], v235 offset:34816
	ds_read_b128 v[172:175], v235 offset:35840
	ds_read_b128 v[176:179], v235 offset:36864
	ds_read_b128 v[180:183], v235 offset:37888
	ds_read_b128 v[200:203], v235 offset:38912
	ds_read_b128 v[204:207], v235 offset:39936
	global_load_lds_dwordx4 v[216:217], off
	s_mov_b32 m0, s47
	v_lshl_add_u64 v[216:217], s[26:27], 0, v[188:189]
	global_load_lds_dwordx4 v[216:217], off
	s_waitcnt vmcnt(8) lgkmcnt(0)
	s_barrier
	s_setprio 1
	v_mfma_f32_16x16x32_bf16 v[132:135], v[120:123], v[160:163], v[132:135]
	v_mfma_f32_16x16x32_bf16 v[128:131], v[136:139], v[160:163], v[128:131]
	v_mfma_f32_16x16x32_bf16 v[108:111], v[120:123], v[168:171], v[108:111]
	v_mfma_f32_16x16x32_bf16 v[104:107], v[136:139], v[168:171], v[104:107]
	v_mfma_f32_16x16x32_bf16 v[92:95], v[120:123], v[176:179], v[92:95]
	v_mfma_f32_16x16x32_bf16 v[88:91], v[136:139], v[176:179], v[88:91]
	v_mfma_f32_16x16x32_bf16 v[76:79], v[120:123], v[200:203], v[76:79]
	v_mfma_f32_16x16x32_bf16 v[72:75], v[136:139], v[200:203], v[72:75]
	v_mfma_f32_16x16x32_bf16 v[132:135], v[124:127], v[164:167], v[132:135]
	v_mfma_f32_16x16x32_bf16 v[128:131], v[140:143], v[164:167], v[128:131]
	v_mfma_f32_16x16x32_bf16 v[108:111], v[124:127], v[172:175], v[108:111]
	v_mfma_f32_16x16x32_bf16 v[104:107], v[140:143], v[172:175], v[104:107]
	v_mfma_f32_16x16x32_bf16 v[92:95], v[124:127], v[180:183], v[92:95]
	v_mfma_f32_16x16x32_bf16 v[88:91], v[140:143], v[180:183], v[88:91]
	v_mfma_f32_16x16x32_bf16 v[76:79], v[124:127], v[204:207], v[76:79]
	v_mfma_f32_16x16x32_bf16 v[72:75], v[140:143], v[204:207], v[72:75]
	s_setprio 0
	s_setprio 1
	v_mfma_f32_16x16x32_bf16 v[116:119], v[144:147], v[160:163], v[116:119]
	v_mfma_f32_16x16x32_bf16 v[112:115], v[152:155], v[160:163], v[112:115]
	v_mfma_f32_16x16x32_bf16 v[100:103], v[144:147], v[168:171], v[100:103]
	v_mfma_f32_16x16x32_bf16 v[96:99], v[152:155], v[168:171], v[96:99]
	v_mfma_f32_16x16x32_bf16 v[84:87], v[144:147], v[176:179], v[84:87]
	v_mfma_f32_16x16x32_bf16 v[80:83], v[152:155], v[176:179], v[80:83]
	v_mfma_f32_16x16x32_bf16 v[68:71], v[144:147], v[200:203], v[68:71]
	v_mfma_f32_16x16x32_bf16 v[64:67], v[152:155], v[200:203], v[64:67]
	v_mfma_f32_16x16x32_bf16 v[116:119], v[148:151], v[164:167], v[116:119]
	v_mfma_f32_16x16x32_bf16 v[112:115], v[156:159], v[164:167], v[112:115]
	v_mfma_f32_16x16x32_bf16 v[100:103], v[148:151], v[172:175], v[100:103]
	v_mfma_f32_16x16x32_bf16 v[96:99], v[156:159], v[172:175], v[96:99]
	s_setprio 2
	s_barrier
	v_mfma_f32_16x16x32_bf16 v[84:87], v[148:151], v[180:183], v[84:87]
	v_mfma_f32_16x16x32_bf16 v[80:83], v[156:159], v[180:183], v[80:83]
	v_mfma_f32_16x16x32_bf16 v[68:71], v[148:151], v[204:207], v[68:71]
	v_mfma_f32_16x16x32_bf16 v[64:67], v[156:159], v[204:207], v[64:67]
	s_setprio 2
	s_add_i32 s26, s65, s43
	v_lshl_add_u64 v[208:209], v[208:209], 0, s[20:21]
	s_mov_b32 m0, s26
	ds_read_b128 v[160:163], v235 offset:49152
	ds_read_b128 v[164:167], v235 offset:50176
	ds_read_b128 v[168:171], v235 offset:51200
	ds_read_b128 v[172:175], v235 offset:52224
	ds_read_b128 v[176:179], v235 offset:53248
	ds_read_b128 v[180:183], v235 offset:54272
	ds_read_b128 v[200:203], v235 offset:55296
	ds_read_b128 v[204:207], v235 offset:56320
	global_load_lds_dwordx4 v[208:209], off
	s_add_i32 m0, s26, 0x2000
	s_add_u32 s26, s30, 0xb0080
	v_lshl_add_u64 v[208:209], v[210:211], 0, s[20:21]
	s_addc_u32 s27, s31, 0
	s_add_i32 s30, s66, s43
	global_load_lds_dwordx4 v[208:209], off
	s_mov_b32 m0, s30
	v_lshl_add_u64 v[208:209], s[26:27], 0, v[186:187]
	global_load_lds_dwordx4 v[208:209], off
	s_add_i32 m0, s30, 0x2000
	v_lshl_add_u64 v[208:209], s[26:27], 0, v[190:191]
	global_load_lds_dwordx4 v[208:209], off
	s_mov_b32 m0, s49
	v_lshl_add_u64 v[208:209], v[212:213], 0, s[20:21]
	global_load_lds_dwordx4 v[208:209], off
	s_mov_b32 m0, s50
	v_lshl_add_u64 v[208:209], v[214:215], 0, s[20:21]
	global_load_lds_dwordx4 v[208:209], off
	s_waitcnt vmcnt(8) lgkmcnt(0)
	s_barrier
	s_setprio 1
	v_mfma_f32_16x16x32_bf16 v[60:63], v[120:123], v[160:163], v[60:63]
	v_mfma_f32_16x16x32_bf16 v[56:59], v[136:139], v[160:163], v[56:59]
	v_mfma_f32_16x16x32_bf16 v[44:47], v[120:123], v[168:171], v[44:47]
	v_mfma_f32_16x16x32_bf16 v[40:43], v[136:139], v[168:171], v[40:43]
	v_mfma_f32_16x16x32_bf16 v[28:31], v[120:123], v[176:179], v[28:31]
	v_mfma_f32_16x16x32_bf16 v[24:27], v[136:139], v[176:179], v[24:27]
	v_mfma_f32_16x16x32_bf16 v[12:15], v[120:123], v[200:203], v[12:15]
	v_mfma_f32_16x16x32_bf16 v[8:11], v[136:139], v[200:203], v[8:11]
	v_mfma_f32_16x16x32_bf16 v[60:63], v[124:127], v[164:167], v[60:63]
	v_mfma_f32_16x16x32_bf16 v[56:59], v[140:143], v[164:167], v[56:59]
	v_mfma_f32_16x16x32_bf16 v[44:47], v[124:127], v[172:175], v[44:47]
	v_mfma_f32_16x16x32_bf16 v[40:43], v[140:143], v[172:175], v[40:43]
	v_mfma_f32_16x16x32_bf16 v[28:31], v[124:127], v[180:183], v[28:31]
	v_mfma_f32_16x16x32_bf16 v[24:27], v[140:143], v[180:183], v[24:27]
	v_mfma_f32_16x16x32_bf16 v[12:15], v[124:127], v[204:207], v[12:15]
	v_mfma_f32_16x16x32_bf16 v[8:11], v[140:143], v[204:207], v[8:11]
	s_setprio 0
	s_setprio 1
	v_mfma_f32_16x16x32_bf16 v[52:55], v[144:147], v[160:163], v[52:55]
	v_mfma_f32_16x16x32_bf16 v[48:51], v[152:155], v[160:163], v[48:51]
	v_mfma_f32_16x16x32_bf16 v[36:39], v[144:147], v[168:171], v[36:39]
	v_mfma_f32_16x16x32_bf16 v[32:35], v[152:155], v[168:171], v[32:35]
	v_mfma_f32_16x16x32_bf16 v[20:23], v[144:147], v[176:179], v[20:23]
	v_mfma_f32_16x16x32_bf16 v[16:19], v[152:155], v[176:179], v[16:19]
	v_mfma_f32_16x16x32_bf16 v[4:7], v[144:147], v[200:203], v[4:7]
	v_mfma_f32_16x16x32_bf16 v[0:3], v[152:155], v[200:203], v[0:3]
	v_mfma_f32_16x16x32_bf16 v[52:55], v[148:151], v[164:167], v[52:55]
	v_mfma_f32_16x16x32_bf16 v[48:51], v[156:159], v[164:167], v[48:51]
	v_mfma_f32_16x16x32_bf16 v[36:39], v[148:151], v[172:175], v[36:39]
	v_mfma_f32_16x16x32_bf16 v[32:35], v[156:159], v[172:175], v[32:35]
	s_setprio 2
	s_barrier
	v_mfma_f32_16x16x32_bf16 v[20:23], v[148:151], v[180:183], v[20:23]
	v_mfma_f32_16x16x32_bf16 v[16:19], v[156:159], v[180:183], v[16:19]
	v_mfma_f32_16x16x32_bf16 v[4:7], v[148:151], v[204:207], v[4:7]
	v_mfma_f32_16x16x32_bf16 v[0:3], v[156:159], v[204:207], v[0:3]
	s_setprio 0
	s_add_i32 s64, s64, 2
	s_add_u32 s62, s62, 0x100
	s_addc_u32 s63, s63, 0
	s_cmp_gt_u32 s64, 41
	s_mov_b64 s[26:27], s[28:29]
.LBB0_866:
	ds_read_b128 v[120:123], v233
	ds_read_b128 v[124:127], v233 offset:1024
	ds_read_b128 v[136:139], v233 offset:2048
	ds_read_b128 v[140:143], v233 offset:3072
	ds_read_b128 v[144:147], v234
	ds_read_b128 v[148:151], v234 offset:1024
	ds_read_b128 v[152:155], v234 offset:2048
	ds_read_b128 v[156:159], v234 offset:3072
	s_add_u32 s28, s26, 0x100
	s_addc_u32 s29, s27, 0
	s_cmp_eq_u32 s64, 40
	s_cselect_b32 s37, s7, s29
	s_cselect_b32 s36, s6, s28
	s_cselect_b32 s31, s25, s63
	s_cselect_b32 s30, s24, s62
	v_lshl_add_u64 v[208:209], s[26:27], 0, v[192:193]
	s_add_i32 m0, s44, 0xc000
	ds_read_b128 v[160:163], v235
	ds_read_b128 v[164:167], v235 offset:1024
	ds_read_b128 v[168:171], v235 offset:2048
	ds_read_b128 v[172:175], v235 offset:3072
	ds_read_b128 v[176:179], v235 offset:4096
	ds_read_b128 v[180:183], v235 offset:5120
	ds_read_b128 v[200:203], v235 offset:6144
	ds_read_b128 v[204:207], v235 offset:7168
	global_load_lds_dwordx4 v[208:209], off
	s_add_i32 m0, s44, 0xe000
	v_lshl_add_u64 v[208:209], s[26:27], 0, v[194:195]
	global_load_lds_dwordx4 v[208:209], off
	s_waitcnt vmcnt(8) lgkmcnt(0)
	s_barrier
	s_setprio 1
	v_mfma_f32_16x16x32_bf16 v[132:135], v[120:123], v[160:163], v[132:135]
	v_mfma_f32_16x16x32_bf16 v[128:131], v[136:139], v[160:163], v[128:131]
	v_mfma_f32_16x16x32_bf16 v[108:111], v[120:123], v[168:171], v[108:111]
	v_mfma_f32_16x16x32_bf16 v[104:107], v[136:139], v[168:171], v[104:107]
	v_mfma_f32_16x16x32_bf16 v[92:95], v[120:123], v[176:179], v[92:95]
	v_mfma_f32_16x16x32_bf16 v[88:91], v[136:139], v[176:179], v[88:91]
	v_mfma_f32_16x16x32_bf16 v[76:79], v[120:123], v[200:203], v[76:79]
	v_mfma_f32_16x16x32_bf16 v[72:75], v[136:139], v[200:203], v[72:75]
	v_mfma_f32_16x16x32_bf16 v[132:135], v[124:127], v[164:167], v[132:135]
	v_mfma_f32_16x16x32_bf16 v[128:131], v[140:143], v[164:167], v[128:131]
	v_mfma_f32_16x16x32_bf16 v[108:111], v[124:127], v[172:175], v[108:111]
	v_mfma_f32_16x16x32_bf16 v[104:107], v[140:143], v[172:175], v[104:107]
	v_mfma_f32_16x16x32_bf16 v[92:95], v[124:127], v[180:183], v[92:95]
	v_mfma_f32_16x16x32_bf16 v[88:91], v[140:143], v[180:183], v[88:91]
	v_mfma_f32_16x16x32_bf16 v[76:79], v[124:127], v[204:207], v[76:79]
	v_mfma_f32_16x16x32_bf16 v[72:75], v[140:143], v[204:207], v[72:75]
	s_setprio 0
	s_setprio 1
	v_mfma_f32_16x16x32_bf16 v[116:119], v[144:147], v[160:163], v[116:119]
	v_mfma_f32_16x16x32_bf16 v[112:115], v[152:155], v[160:163], v[112:115]
	v_mfma_f32_16x16x32_bf16 v[100:103], v[144:147], v[168:171], v[100:103]
	v_mfma_f32_16x16x32_bf16 v[96:99], v[152:155], v[168:171], v[96:99]
	v_mfma_f32_16x16x32_bf16 v[84:87], v[144:147], v[176:179], v[84:87]
	v_mfma_f32_16x16x32_bf16 v[80:83], v[152:155], v[176:179], v[80:83]
	v_mfma_f32_16x16x32_bf16 v[68:71], v[144:147], v[200:203], v[68:71]
	v_mfma_f32_16x16x32_bf16 v[64:67], v[152:155], v[200:203], v[64:67]
	v_mfma_f32_16x16x32_bf16 v[116:119], v[148:151], v[164:167], v[116:119]
	v_mfma_f32_16x16x32_bf16 v[112:115], v[156:159], v[164:167], v[112:115]
	v_mfma_f32_16x16x32_bf16 v[100:103], v[148:151], v[172:175], v[100:103]
	v_mfma_f32_16x16x32_bf16 v[96:99], v[156:159], v[172:175], v[96:99]
	s_setprio 2
	s_barrier
	v_mfma_f32_16x16x32_bf16 v[84:87], v[148:151], v[180:183], v[84:87]
	v_mfma_f32_16x16x32_bf16 v[80:83], v[156:159], v[180:183], v[80:83]
	v_mfma_f32_16x16x32_bf16 v[68:71], v[148:151], v[204:207], v[68:71]
	v_mfma_f32_16x16x32_bf16 v[64:67], v[156:159], v[204:207], v[64:67]
	s_setprio 2
	s_add_i32 s26, s56, s43
	v_lshl_add_u64 v[208:209], s[30:31], 0, v[186:187]
	s_mov_b32 m0, s26
	ds_read_b128 v[160:163], v235 offset:16384
	ds_read_b128 v[164:167], v235 offset:17408
	ds_read_b128 v[168:171], v235 offset:18432
	ds_read_b128 v[172:175], v235 offset:19456
	ds_read_b128 v[176:179], v235 offset:20480
	ds_read_b128 v[180:183], v235 offset:21504
	ds_read_b128 v[200:203], v235 offset:22528
	ds_read_b128 v[204:207], v235 offset:23552
	global_load_lds_dwordx4 v[208:209], off
	s_add_i32 m0, s26, 0x2000
	s_add_u32 s26, s30, 0xb0000
	v_lshl_add_u64 v[210:211], s[30:31], 0, v[190:191]
	s_addc_u32 s27, s31, 0
	s_add_i32 s65, s57, s43
	global_load_lds_dwordx4 v[210:211], off
	v_lshl_add_u64 v[212:213], s[26:27], 0, v[186:187]
	s_mov_b32 m0, s65
	v_lshl_add_u64 v[214:215], s[36:37], 0, v[188:189]
	global_load_lds_dwordx4 v[212:213], off
	s_add_i32 m0, s65, 0x2000
	v_lshl_add_u64 v[212:213], s[26:27], 0, v[190:191]
	global_load_lds_dwordx4 v[212:213], off
	s_mov_b32 m0, s44
	v_lshl_add_u64 v[212:213], s[36:37], 0, v[184:185]
	global_load_lds_dwordx4 v[212:213], off
	s_mov_b32 m0, s45
	s_nop 0
	global_load_lds_dwordx4 v[214:215], off
	s_waitcnt vmcnt(8) lgkmcnt(0)
	s_barrier
	s_setprio 1
	v_mfma_f32_16x16x32_bf16 v[60:63], v[120:123], v[160:163], v[60:63]
	v_mfma_f32_16x16x32_bf16 v[56:59], v[136:139], v[160:163], v[56:59]
	v_mfma_f32_16x16x32_bf16 v[44:47], v[120:123], v[168:171], v[44:47]
	v_mfma_f32_16x16x32_bf16 v[40:43], v[136:139], v[168:171], v[40:43]
	v_mfma_f32_16x16x32_bf16 v[28:31], v[120:123], v[176:179], v[28:31]
	v_mfma_f32_16x16x32_bf16 v[24:27], v[136:139], v[176:179], v[24:27]
	v_mfma_f32_16x16x32_bf16 v[12:15], v[120:123], v[200:203], v[12:15]
	v_mfma_f32_16x16x32_bf16 v[8:11], v[136:139], v[200:203], v[8:11]
	v_mfma_f32_16x16x32_bf16 v[60:63], v[124:127], v[164:167], v[60:63]
	v_mfma_f32_16x16x32_bf16 v[56:59], v[140:143], v[164:167], v[56:59]
	v_mfma_f32_16x16x32_bf16 v[44:47], v[124:127], v[172:175], v[44:47]
	v_mfma_f32_16x16x32_bf16 v[40:43], v[140:143], v[172:175], v[40:43]
	v_mfma_f32_16x16x32_bf16 v[28:31], v[124:127], v[180:183], v[28:31]
	v_mfma_f32_16x16x32_bf16 v[24:27], v[140:143], v[180:183], v[24:27]
	v_mfma_f32_16x16x32_bf16 v[12:15], v[124:127], v[204:207], v[12:15]
	v_mfma_f32_16x16x32_bf16 v[8:11], v[140:143], v[204:207], v[8:11]
	s_setprio 0
	s_setprio 1
	v_mfma_f32_16x16x32_bf16 v[52:55], v[144:147], v[160:163], v[52:55]
	v_mfma_f32_16x16x32_bf16 v[48:51], v[152:155], v[160:163], v[48:51]
	v_mfma_f32_16x16x32_bf16 v[36:39], v[144:147], v[168:171], v[36:39]
	v_mfma_f32_16x16x32_bf16 v[32:35], v[152:155], v[168:171], v[32:35]
	v_mfma_f32_16x16x32_bf16 v[20:23], v[144:147], v[176:179], v[20:23]
	v_mfma_f32_16x16x32_bf16 v[16:19], v[152:155], v[176:179], v[16:19]
	v_mfma_f32_16x16x32_bf16 v[4:7], v[144:147], v[200:203], v[4:7]
	v_mfma_f32_16x16x32_bf16 v[0:3], v[152:155], v[200:203], v[0:3]
	v_mfma_f32_16x16x32_bf16 v[52:55], v[148:151], v[164:167], v[52:55]
	v_mfma_f32_16x16x32_bf16 v[48:51], v[156:159], v[164:167], v[48:51]
	v_mfma_f32_16x16x32_bf16 v[36:39], v[148:151], v[172:175], v[36:39]
	v_mfma_f32_16x16x32_bf16 v[32:35], v[156:159], v[172:175], v[32:35]
	s_setprio 2
	s_barrier
	v_mfma_f32_16x16x32_bf16 v[20:23], v[148:151], v[180:183], v[20:23]
	v_mfma_f32_16x16x32_bf16 v[16:19], v[156:159], v[180:183], v[16:19]
	v_mfma_f32_16x16x32_bf16 v[4:7], v[148:151], v[204:207], v[4:7]
	v_mfma_f32_16x16x32_bf16 v[0:3], v[156:159], v[204:207], v[0:3]
	s_setprio 0
	s_add_i32 s65, 0, 0x18000
	s_add_i32 s66, 0, 0x1c000
	v_add_u32_e32 v140, s65, v232
	v_add_u32_e32 v156, s66, v232
	ds_read_b128 v[120:123], v140
	ds_read_b128 v[124:127], v140 offset:1024
	ds_read_b128 v[136:139], v140 offset:2048
	ds_read_b128 v[140:143], v140 offset:3072
	ds_read_b128 v[144:147], v156
	ds_read_b128 v[148:151], v156 offset:1024
	ds_read_b128 v[152:155], v156 offset:2048
	ds_read_b128 v[156:159], v156 offset:3072
	s_add_u32 s26, s36, 0xb0000
	s_addc_u32 s27, s37, 0
	s_mov_b32 m0, s46
	v_lshl_add_u64 v[216:217], s[26:27], 0, v[184:185]
	ds_read_b128 v[160:163], v235 offset:32768
	ds_read_b128 v[164:167], v235 offset:33792
	ds_read_b128 v[168:171], v235 offset:34816
	ds_read_b128 v[172:175], v235 offset:35840
	ds_read_b128 v[176:179], v235 offset:36864
	ds_read_b128 v[180:183], v235 offset:37888
	ds_read_b128 v[200:203], v235 offset:38912
	ds_read_b128 v[204:207], v235 offset:39936
	global_load_lds_dwordx4 v[216:217], off
	s_mov_b32 m0, s47
	v_lshl_add_u64 v[216:217], s[26:27], 0, v[188:189]
	global_load_lds_dwordx4 v[216:217], off
	s_waitcnt vmcnt(8) lgkmcnt(0)
	s_barrier
	s_setprio 1
	v_mfma_f32_16x16x32_bf16 v[132:135], v[120:123], v[160:163], v[132:135]
	v_mfma_f32_16x16x32_bf16 v[128:131], v[136:139], v[160:163], v[128:131]
	v_mfma_f32_16x16x32_bf16 v[108:111], v[120:123], v[168:171], v[108:111]
	v_mfma_f32_16x16x32_bf16 v[104:107], v[136:139], v[168:171], v[104:107]
	v_mfma_f32_16x16x32_bf16 v[92:95], v[120:123], v[176:179], v[92:95]
	v_mfma_f32_16x16x32_bf16 v[88:91], v[136:139], v[176:179], v[88:91]
	v_mfma_f32_16x16x32_bf16 v[76:79], v[120:123], v[200:203], v[76:79]
	v_mfma_f32_16x16x32_bf16 v[72:75], v[136:139], v[200:203], v[72:75]
	v_mfma_f32_16x16x32_bf16 v[132:135], v[124:127], v[164:167], v[132:135]
	v_mfma_f32_16x16x32_bf16 v[128:131], v[140:143], v[164:167], v[128:131]
	v_mfma_f32_16x16x32_bf16 v[108:111], v[124:127], v[172:175], v[108:111]
	v_mfma_f32_16x16x32_bf16 v[104:107], v[140:143], v[172:175], v[104:107]
	v_mfma_f32_16x16x32_bf16 v[92:95], v[124:127], v[180:183], v[92:95]
	v_mfma_f32_16x16x32_bf16 v[88:91], v[140:143], v[180:183], v[88:91]
	v_mfma_f32_16x16x32_bf16 v[76:79], v[124:127], v[204:207], v[76:79]
	v_mfma_f32_16x16x32_bf16 v[72:75], v[140:143], v[204:207], v[72:75]
	s_setprio 0
	s_setprio 1
	v_mfma_f32_16x16x32_bf16 v[116:119], v[144:147], v[160:163], v[116:119]
	v_mfma_f32_16x16x32_bf16 v[112:115], v[152:155], v[160:163], v[112:115]
	v_mfma_f32_16x16x32_bf16 v[100:103], v[144:147], v[168:171], v[100:103]
	v_mfma_f32_16x16x32_bf16 v[96:99], v[152:155], v[168:171], v[96:99]
	v_mfma_f32_16x16x32_bf16 v[84:87], v[144:147], v[176:179], v[84:87]
	v_mfma_f32_16x16x32_bf16 v[80:83], v[152:155], v[176:179], v[80:83]
	v_mfma_f32_16x16x32_bf16 v[68:71], v[144:147], v[200:203], v[68:71]
	v_mfma_f32_16x16x32_bf16 v[64:67], v[152:155], v[200:203], v[64:67]
	v_mfma_f32_16x16x32_bf16 v[116:119], v[148:151], v[164:167], v[116:119]
	v_mfma_f32_16x16x32_bf16 v[112:115], v[156:159], v[164:167], v[112:115]
	v_mfma_f32_16x16x32_bf16 v[100:103], v[148:151], v[172:175], v[100:103]
	v_mfma_f32_16x16x32_bf16 v[96:99], v[156:159], v[172:175], v[96:99]
	s_setprio 2
	s_barrier
	v_mfma_f32_16x16x32_bf16 v[84:87], v[148:151], v[180:183], v[84:87]
	v_mfma_f32_16x16x32_bf16 v[80:83], v[156:159], v[180:183], v[80:83]
	v_mfma_f32_16x16x32_bf16 v[68:71], v[148:151], v[204:207], v[68:71]
	v_mfma_f32_16x16x32_bf16 v[64:67], v[156:159], v[204:207], v[64:67]
	s_setprio 2
	s_add_i32 s26, s65, s43
	v_lshl_add_u64 v[208:209], v[208:209], 0, s[20:21]
	s_mov_b32 m0, s26
	ds_read_b128 v[160:163], v235 offset:49152
	ds_read_b128 v[164:167], v235 offset:50176
	ds_read_b128 v[168:171], v235 offset:51200
	ds_read_b128 v[172:175], v235 offset:52224
	ds_read_b128 v[176:179], v235 offset:53248
	ds_read_b128 v[180:183], v235 offset:54272
	ds_read_b128 v[200:203], v235 offset:55296
	ds_read_b128 v[204:207], v235 offset:56320
	global_load_lds_dwordx4 v[208:209], off
	s_add_i32 m0, s26, 0x2000
	s_add_u32 s26, s30, 0xb0080
	v_lshl_add_u64 v[208:209], v[210:211], 0, s[20:21]
	s_addc_u32 s27, s31, 0
	s_add_i32 s30, s66, s43
	global_load_lds_dwordx4 v[208:209], off
	s_mov_b32 m0, s30
	v_lshl_add_u64 v[208:209], s[26:27], 0, v[186:187]
	global_load_lds_dwordx4 v[208:209], off
	s_add_i32 m0, s30, 0x2000
	v_lshl_add_u64 v[208:209], s[26:27], 0, v[190:191]
	global_load_lds_dwordx4 v[208:209], off
	s_mov_b32 m0, s49
	v_lshl_add_u64 v[208:209], v[212:213], 0, s[20:21]
	global_load_lds_dwordx4 v[208:209], off
	s_mov_b32 m0, s50
	v_lshl_add_u64 v[208:209], v[214:215], 0, s[20:21]
	global_load_lds_dwordx4 v[208:209], off
	s_waitcnt vmcnt(8) lgkmcnt(0)
	s_barrier
	s_setprio 1
	v_mfma_f32_16x16x32_bf16 v[60:63], v[120:123], v[160:163], v[60:63]
	v_mfma_f32_16x16x32_bf16 v[56:59], v[136:139], v[160:163], v[56:59]
	v_mfma_f32_16x16x32_bf16 v[44:47], v[120:123], v[168:171], v[44:47]
	v_mfma_f32_16x16x32_bf16 v[40:43], v[136:139], v[168:171], v[40:43]
	v_mfma_f32_16x16x32_bf16 v[28:31], v[120:123], v[176:179], v[28:31]
	v_mfma_f32_16x16x32_bf16 v[24:27], v[136:139], v[176:179], v[24:27]
	v_mfma_f32_16x16x32_bf16 v[12:15], v[120:123], v[200:203], v[12:15]
	v_mfma_f32_16x16x32_bf16 v[8:11], v[136:139], v[200:203], v[8:11]
	v_mfma_f32_16x16x32_bf16 v[60:63], v[124:127], v[164:167], v[60:63]
	v_mfma_f32_16x16x32_bf16 v[56:59], v[140:143], v[164:167], v[56:59]
	v_mfma_f32_16x16x32_bf16 v[44:47], v[124:127], v[172:175], v[44:47]
	v_mfma_f32_16x16x32_bf16 v[40:43], v[140:143], v[172:175], v[40:43]
	v_mfma_f32_16x16x32_bf16 v[28:31], v[124:127], v[180:183], v[28:31]
	v_mfma_f32_16x16x32_bf16 v[24:27], v[140:143], v[180:183], v[24:27]
	v_mfma_f32_16x16x32_bf16 v[12:15], v[124:127], v[204:207], v[12:15]
	v_mfma_f32_16x16x32_bf16 v[8:11], v[140:143], v[204:207], v[8:11]
	s_setprio 0
	s_setprio 1
	v_mfma_f32_16x16x32_bf16 v[52:55], v[144:147], v[160:163], v[52:55]
	v_mfma_f32_16x16x32_bf16 v[48:51], v[152:155], v[160:163], v[48:51]
	v_mfma_f32_16x16x32_bf16 v[36:39], v[144:147], v[168:171], v[36:39]
	v_mfma_f32_16x16x32_bf16 v[32:35], v[152:155], v[168:171], v[32:35]
	v_mfma_f32_16x16x32_bf16 v[20:23], v[144:147], v[176:179], v[20:23]
	v_mfma_f32_16x16x32_bf16 v[16:19], v[152:155], v[176:179], v[16:19]
	v_mfma_f32_16x16x32_bf16 v[4:7], v[144:147], v[200:203], v[4:7]
	v_mfma_f32_16x16x32_bf16 v[0:3], v[152:155], v[200:203], v[0:3]
	v_mfma_f32_16x16x32_bf16 v[52:55], v[148:151], v[164:167], v[52:55]
	v_mfma_f32_16x16x32_bf16 v[48:51], v[156:159], v[164:167], v[48:51]
	v_mfma_f32_16x16x32_bf16 v[36:39], v[148:151], v[172:175], v[36:39]
	v_mfma_f32_16x16x32_bf16 v[32:35], v[156:159], v[172:175], v[32:35]
	s_setprio 2
	s_barrier
	v_mfma_f32_16x16x32_bf16 v[20:23], v[148:151], v[180:183], v[20:23]
	v_mfma_f32_16x16x32_bf16 v[16:19], v[156:159], v[180:183], v[16:19]
	v_mfma_f32_16x16x32_bf16 v[4:7], v[148:151], v[204:207], v[4:7]
	v_mfma_f32_16x16x32_bf16 v[0:3], v[156:159], v[204:207], v[0:3]
	s_setprio 0
	s_add_i32 s64, s64, 2
	s_add_u32 s62, s62, 0x100
	s_addc_u32 s63, s63, 0
	s_cmp_gt_u32 s64, 41
	s_mov_b64 s[26:27], s[28:29]
	s_cbranch_scc0 .LBB0_866

.LBB0_951:
	s_ashr_i32 s27, s26, 31
	s_lshl_b64 s[30:31], s[26:27], 19
	s_add_u32 s30, s47, s30
	s_addc_u32 s31, s48, s31
	s_and_b64 s[36:37], s[4:5], exec
	s_cselect_b32 s27, s31, s7
	s_cselect_b32 s39, s30, s6
	s_ashr_i32 s29, s28, 31
	s_lshl_b64 s[36:37], s[28:29], 19
	s_add_u32 s36, s49, s36
	s_addc_u32 s37, s50, s37
	s_and_b64 s[44:45], s[4:5], exec
	s_cselect_b32 s29, s37, s41
	s_cselect_b32 s43, s36, s40
	s_add_u32 s6, s6, 0x40080
	s_addc_u32 s7, s7, 0
	s_add_u32 s71, s40, 0x100
	s_addc_u32 s72, s41, 0
	s_mov_b32 s73, -2
	ds_read_b128 v[144:147], v179
	ds_read_b128 v[148:151], v179 offset:1024
	ds_read_b128 v[152:155], v179 offset:2048
	ds_read_b128 v[156:159], v179 offset:3072
	ds_read_b128 v[160:163], v180
	ds_read_b128 v[164:167], v180 offset:1024
	ds_read_b128 v[168:171], v180 offset:2048
	ds_read_b128 v[172:175], v180 offset:3072
	s_add_u32 s40, s6, 0xfffc0080
	s_addc_u32 s41, s7, -1
	s_cmp_eq_u32 s73, 12
	s_cselect_b32 s45, s27, s41
	s_cselect_b32 s44, s39, s40
	s_cselect_b32 s41, s29, s72
	s_cselect_b32 s40, s43, s71
	v_lshl_add_u64 v[176:177], s[6:7], 0, v[136:137]
	s_add_i32 m0, s54, 0xc000
	ds_read_b128 v[184:187], v181
	ds_read_b128 v[188:191], v181 offset:1024
	ds_read_b128 v[192:195], v181 offset:2048
	ds_read_b128 v[196:199], v181 offset:3072
	ds_read_b128 v[200:203], v181 offset:4096
	ds_read_b128 v[204:207], v181 offset:5120
	ds_read_b128 v[208:211], v181 offset:6144
	ds_read_b128 v[212:215], v181 offset:7168
	global_load_lds_dwordx4 v[176:177], off
	s_add_i32 m0, s54, 0xe000
	v_lshl_add_u64 v[176:177], s[6:7], 0, v[138:139]
	global_load_lds_dwordx4 v[176:177], off
	s_waitcnt vmcnt(8) lgkmcnt(0)
	s_barrier
	s_setprio 1
	v_mfma_f32_16x16x32_bf16 v[124:127], v[144:147], v[184:187], 0
	v_mfma_f32_16x16x32_bf16 v[120:123], v[152:155], v[184:187], 0
	v_mfma_f32_16x16x32_bf16 v[108:111], v[144:147], v[192:195], 0
	v_mfma_f32_16x16x32_bf16 v[104:107], v[152:155], v[192:195], 0
	v_mfma_f32_16x16x32_bf16 v[92:95], v[144:147], v[200:203], 0
	v_mfma_f32_16x16x32_bf16 v[88:91], v[152:155], v[200:203], 0
	v_mfma_f32_16x16x32_bf16 v[76:79], v[144:147], v[208:211], 0
	v_mfma_f32_16x16x32_bf16 v[72:75], v[152:155], v[208:211], 0
	v_mfma_f32_16x16x32_bf16 v[124:127], v[148:151], v[188:191], v[124:127]
	v_mfma_f32_16x16x32_bf16 v[120:123], v[156:159], v[188:191], v[120:123]
	v_mfma_f32_16x16x32_bf16 v[108:111], v[148:151], v[196:199], v[108:111]
	v_mfma_f32_16x16x32_bf16 v[104:107], v[156:159], v[196:199], v[104:107]
	v_mfma_f32_16x16x32_bf16 v[92:95], v[148:151], v[204:207], v[92:95]
	v_mfma_f32_16x16x32_bf16 v[88:91], v[156:159], v[204:207], v[88:91]
	v_mfma_f32_16x16x32_bf16 v[76:79], v[148:151], v[212:215], v[76:79]
	v_mfma_f32_16x16x32_bf16 v[72:75], v[156:159], v[212:215], v[72:75]
	s_setprio 0
	s_setprio 1
	v_mfma_f32_16x16x32_bf16 v[116:119], v[160:163], v[184:187], 0
	v_mfma_f32_16x16x32_bf16 v[112:115], v[168:171], v[184:187], 0
	v_mfma_f32_16x16x32_bf16 v[100:103], v[160:163], v[192:195], 0
	v_mfma_f32_16x16x32_bf16 v[96:99], v[168:171], v[192:195], 0
	v_mfma_f32_16x16x32_bf16 v[84:87], v[160:163], v[200:203], 0
	v_mfma_f32_16x16x32_bf16 v[80:83], v[168:171], v[200:203], 0
	v_mfma_f32_16x16x32_bf16 v[68:71], v[160:163], v[208:211], 0
	v_mfma_f32_16x16x32_bf16 v[64:67], v[168:171], v[208:211], 0
	v_mfma_f32_16x16x32_bf16 v[116:119], v[164:167], v[188:191], v[116:119]
	v_mfma_f32_16x16x32_bf16 v[112:115], v[172:175], v[188:191], v[112:115]
	v_mfma_f32_16x16x32_bf16 v[100:103], v[164:167], v[196:199], v[100:103]
	v_mfma_f32_16x16x32_bf16 v[96:99], v[172:175], v[196:199], v[96:99]
	s_setprio 2
	s_barrier
	v_mfma_f32_16x16x32_bf16 v[84:87], v[164:167], v[204:207], v[84:87]
	v_mfma_f32_16x16x32_bf16 v[80:83], v[172:175], v[204:207], v[80:83]
	v_mfma_f32_16x16x32_bf16 v[68:71], v[164:167], v[212:215], v[68:71]
	v_mfma_f32_16x16x32_bf16 v[64:67], v[172:175], v[212:215], v[64:67]
	s_setprio 2
	s_add_i32 s74, s69, s51
	v_lshl_add_u64 v[176:177], s[40:41], 0, v[130:131]
	s_mov_b32 m0, s74
	ds_read_b128 v[184:187], v181 offset:16384
	ds_read_b128 v[188:191], v181 offset:17408
	ds_read_b128 v[192:195], v181 offset:18432
	ds_read_b128 v[196:199], v181 offset:19456
	ds_read_b128 v[200:203], v181 offset:20480
	ds_read_b128 v[204:207], v181 offset:21504
	ds_read_b128 v[208:211], v181 offset:22528
	ds_read_b128 v[212:215], v181 offset:23552
	global_load_lds_dwordx4 v[176:177], off
	s_add_i32 m0, s74, 0x2000
	s_add_u32 s74, s40, 0x40000
	v_lshl_add_u64 v[216:217], s[40:41], 0, v[134:135]
	s_addc_u32 s75, s41, 0
	s_add_i32 s76, s70, s51
	global_load_lds_dwordx4 v[216:217], off
	v_lshl_add_u64 v[218:219], s[74:75], 0, v[130:131]
	s_mov_b32 m0, s76
	v_lshl_add_u64 v[220:221], s[44:45], 0, v[132:133]
	global_load_lds_dwordx4 v[218:219], off
	s_add_i32 m0, s76, 0x2000
	v_lshl_add_u64 v[218:219], s[74:75], 0, v[134:135]
	global_load_lds_dwordx4 v[218:219], off
	s_mov_b32 m0, s54
	v_lshl_add_u64 v[218:219], s[44:45], 0, v[128:129]
	global_load_lds_dwordx4 v[218:219], off
	s_mov_b32 m0, s55
	s_nop 0
	global_load_lds_dwordx4 v[220:221], off
	s_waitcnt vmcnt(8) lgkmcnt(0)
	s_barrier
	s_setprio 1
	v_mfma_f32_16x16x32_bf16 v[60:63], v[144:147], v[184:187], 0
	v_mfma_f32_16x16x32_bf16 v[56:59], v[152:155], v[184:187], 0
	v_mfma_f32_16x16x32_bf16 v[44:47], v[144:147], v[192:195], 0
	v_mfma_f32_16x16x32_bf16 v[40:43], v[152:155], v[192:195], 0
	v_mfma_f32_16x16x32_bf16 v[28:31], v[144:147], v[200:203], 0
	v_mfma_f32_16x16x32_bf16 v[24:27], v[152:155], v[200:203], 0
	v_mfma_f32_16x16x32_bf16 v[12:15], v[144:147], v[208:211], 0
	v_mfma_f32_16x16x32_bf16 v[8:11], v[152:155], v[208:211], 0
	v_mfma_f32_16x16x32_bf16 v[60:63], v[148:151], v[188:191], v[60:63]
	v_mfma_f32_16x16x32_bf16 v[56:59], v[156:159], v[188:191], v[56:59]
	v_mfma_f32_16x16x32_bf16 v[44:47], v[148:151], v[196:199], v[44:47]
	v_mfma_f32_16x16x32_bf16 v[40:43], v[156:159], v[196:199], v[40:43]
	v_mfma_f32_16x16x32_bf16 v[28:31], v[148:151], v[204:207], v[28:31]
	v_mfma_f32_16x16x32_bf16 v[24:27], v[156:159], v[204:207], v[24:27]
	v_mfma_f32_16x16x32_bf16 v[12:15], v[148:151], v[212:215], v[12:15]
	v_mfma_f32_16x16x32_bf16 v[8:11], v[156:159], v[212:215], v[8:11]
	s_setprio 0
	s_setprio 1
	v_mfma_f32_16x16x32_bf16 v[52:55], v[160:163], v[184:187], 0
	v_mfma_f32_16x16x32_bf16 v[48:51], v[168:171], v[184:187], 0
	v_mfma_f32_16x16x32_bf16 v[36:39], v[160:163], v[192:195], 0
	v_mfma_f32_16x16x32_bf16 v[32:35], v[168:171], v[192:195], 0
	v_mfma_f32_16x16x32_bf16 v[20:23], v[160:163], v[200:203], 0
	v_mfma_f32_16x16x32_bf16 v[16:19], v[168:171], v[200:203], 0
	v_mfma_f32_16x16x32_bf16 v[4:7], v[160:163], v[208:211], 0
	v_mfma_f32_16x16x32_bf16 v[0:3], v[168:171], v[208:211], 0
	v_mfma_f32_16x16x32_bf16 v[52:55], v[164:167], v[188:191], v[52:55]
	v_mfma_f32_16x16x32_bf16 v[48:51], v[172:175], v[188:191], v[48:51]
	v_mfma_f32_16x16x32_bf16 v[36:39], v[164:167], v[196:199], v[36:39]
	v_mfma_f32_16x16x32_bf16 v[32:35], v[172:175], v[196:199], v[32:35]
	s_setprio 2
	s_barrier
	v_mfma_f32_16x16x32_bf16 v[20:23], v[164:167], v[204:207], v[20:23]
	v_mfma_f32_16x16x32_bf16 v[16:19], v[172:175], v[204:207], v[16:19]
	v_mfma_f32_16x16x32_bf16 v[4:7], v[164:167], v[212:215], v[4:7]
	v_mfma_f32_16x16x32_bf16 v[0:3], v[172:175], v[212:215], v[0:3]
	s_setprio 0
	s_add_i32 s74, 0, 0x18000
	s_add_i32 s75, 0, 0x1c000
	v_add_u32_e32 v156, s74, v178
	v_add_u32_e32 v172, s75, v178
	ds_read_b128 v[144:147], v156
	ds_read_b128 v[148:151], v156 offset:1024
	ds_read_b128 v[152:155], v156 offset:2048
	ds_read_b128 v[156:159], v156 offset:3072
	ds_read_b128 v[160:163], v172
	ds_read_b128 v[164:167], v172 offset:1024
	ds_read_b128 v[168:171], v172 offset:2048
	ds_read_b128 v[172:175], v172 offset:3072
	s_add_u32 s44, s44, 0x40000
	s_addc_u32 s45, s45, 0
	s_mov_b32 m0, s56
	v_lshl_add_u64 v[222:223], s[44:45], 0, v[128:129]
	ds_read_b128 v[184:187], v181 offset:32768
	ds_read_b128 v[188:191], v181 offset:33792
	ds_read_b128 v[192:195], v181 offset:34816
	ds_read_b128 v[196:199], v181 offset:35840
	ds_read_b128 v[200:203], v181 offset:36864
	ds_read_b128 v[204:207], v181 offset:37888
	ds_read_b128 v[208:211], v181 offset:38912
	ds_read_b128 v[212:215], v181 offset:39936
	global_load_lds_dwordx4 v[222:223], off
	s_mov_b32 m0, s57
	v_lshl_add_u64 v[222:223], s[44:45], 0, v[132:133]
	global_load_lds_dwordx4 v[222:223], off
	s_waitcnt vmcnt(8) lgkmcnt(0)
	s_barrier
	s_setprio 1
	v_mfma_f32_16x16x32_bf16 v[124:127], v[144:147], v[184:187], v[124:127]
	v_mfma_f32_16x16x32_bf16 v[120:123], v[152:155], v[184:187], v[120:123]
	v_mfma_f32_16x16x32_bf16 v[108:111], v[144:147], v[192:195], v[108:111]
	v_mfma_f32_16x16x32_bf16 v[104:107], v[152:155], v[192:195], v[104:107]
	v_mfma_f32_16x16x32_bf16 v[92:95], v[144:147], v[200:203], v[92:95]
	v_mfma_f32_16x16x32_bf16 v[88:91], v[152:155], v[200:203], v[88:91]
	v_mfma_f32_16x16x32_bf16 v[76:79], v[144:147], v[208:211], v[76:79]
	v_mfma_f32_16x16x32_bf16 v[72:75], v[152:155], v[208:211], v[72:75]
	v_mfma_f32_16x16x32_bf16 v[124:127], v[148:151], v[188:191], v[124:127]
	v_mfma_f32_16x16x32_bf16 v[120:123], v[156:159], v[188:191], v[120:123]
	v_mfma_f32_16x16x32_bf16 v[108:111], v[148:151], v[196:199], v[108:111]
	v_mfma_f32_16x16x32_bf16 v[104:107], v[156:159], v[196:199], v[104:107]
	v_mfma_f32_16x16x32_bf16 v[92:95], v[148:151], v[204:207], v[92:95]
	v_mfma_f32_16x16x32_bf16 v[88:91], v[156:159], v[204:207], v[88:91]
	v_mfma_f32_16x16x32_bf16 v[76:79], v[148:151], v[212:215], v[76:79]
	v_mfma_f32_16x16x32_bf16 v[72:75], v[156:159], v[212:215], v[72:75]
	s_setprio 0
	s_setprio 1
	v_mfma_f32_16x16x32_bf16 v[116:119], v[160:163], v[184:187], v[116:119]
	v_mfma_f32_16x16x32_bf16 v[112:115], v[168:171], v[184:187], v[112:115]
	v_mfma_f32_16x16x32_bf16 v[100:103], v[160:163], v[192:195], v[100:103]
	v_mfma_f32_16x16x32_bf16 v[96:99], v[168:171], v[192:195], v[96:99]
	v_mfma_f32_16x16x32_bf16 v[84:87], v[160:163], v[200:203], v[84:87]
	v_mfma_f32_16x16x32_bf16 v[80:83], v[168:171], v[200:203], v[80:83]
	v_mfma_f32_16x16x32_bf16 v[68:71], v[160:163], v[208:211], v[68:71]
	v_mfma_f32_16x16x32_bf16 v[64:67], v[168:171], v[208:211], v[64:67]
	v_mfma_f32_16x16x32_bf16 v[116:119], v[164:167], v[188:191], v[116:119]
	v_mfma_f32_16x16x32_bf16 v[112:115], v[172:175], v[188:191], v[112:115]
	v_mfma_f32_16x16x32_bf16 v[100:103], v[164:167], v[196:199], v[100:103]
	v_mfma_f32_16x16x32_bf16 v[96:99], v[172:175], v[196:199], v[96:99]
	s_setprio 2
	s_barrier
	v_mfma_f32_16x16x32_bf16 v[84:87], v[164:167], v[204:207], v[84:87]
	v_mfma_f32_16x16x32_bf16 v[80:83], v[172:175], v[204:207], v[80:83]
	v_mfma_f32_16x16x32_bf16 v[68:71], v[164:167], v[212:215], v[68:71]
	v_mfma_f32_16x16x32_bf16 v[64:67], v[172:175], v[212:215], v[64:67]
	s_setprio 2
	s_add_i32 s44, s74, s51
	v_lshl_add_u64 v[176:177], v[176:177], 0, s[22:23]
	s_mov_b32 m0, s44
	ds_read_b128 v[184:187], v181 offset:49152
	ds_read_b128 v[188:191], v181 offset:50176
	ds_read_b128 v[192:195], v181 offset:51200
	ds_read_b128 v[196:199], v181 offset:52224
	ds_read_b128 v[200:203], v181 offset:53248
	ds_read_b128 v[204:207], v181 offset:54272
	ds_read_b128 v[208:211], v181 offset:55296
	ds_read_b128 v[212:215], v181 offset:56320
	global_load_lds_dwordx4 v[176:177], off
	s_add_i32 m0, s44, 0x2000
	s_add_u32 s40, s40, 0x40080
	v_lshl_add_u64 v[176:177], v[216:217], 0, s[22:23]
	s_addc_u32 s41, s41, 0
	s_add_i32 s44, s75, s51
	global_load_lds_dwordx4 v[176:177], off
	s_mov_b32 m0, s44
	v_lshl_add_u64 v[176:177], s[40:41], 0, v[130:131]
	global_load_lds_dwordx4 v[176:177], off
	s_add_i32 m0, s44, 0x2000
	v_lshl_add_u64 v[176:177], s[40:41], 0, v[134:135]
	global_load_lds_dwordx4 v[176:177], off
	s_mov_b32 m0, s64
	v_lshl_add_u64 v[176:177], v[218:219], 0, s[22:23]
	global_load_lds_dwordx4 v[176:177], off
	s_mov_b32 m0, s65
	v_lshl_add_u64 v[176:177], v[220:221], 0, s[22:23]
	global_load_lds_dwordx4 v[176:177], off
	s_waitcnt vmcnt(8) lgkmcnt(0)
	s_barrier
	s_setprio 1
	v_mfma_f32_16x16x32_bf16 v[60:63], v[144:147], v[184:187], v[60:63]
	v_mfma_f32_16x16x32_bf16 v[56:59], v[152:155], v[184:187], v[56:59]
	v_mfma_f32_16x16x32_bf16 v[44:47], v[144:147], v[192:195], v[44:47]
	v_mfma_f32_16x16x32_bf16 v[40:43], v[152:155], v[192:195], v[40:43]
	v_mfma_f32_16x16x32_bf16 v[28:31], v[144:147], v[200:203], v[28:31]
	v_mfma_f32_16x16x32_bf16 v[24:27], v[152:155], v[200:203], v[24:27]
	v_mfma_f32_16x16x32_bf16 v[12:15], v[144:147], v[208:211], v[12:15]
	v_mfma_f32_16x16x32_bf16 v[8:11], v[152:155], v[208:211], v[8:11]
	v_mfma_f32_16x16x32_bf16 v[60:63], v[148:151], v[188:191], v[60:63]
	v_mfma_f32_16x16x32_bf16 v[56:59], v[156:159], v[188:191], v[56:59]
	v_mfma_f32_16x16x32_bf16 v[44:47], v[148:151], v[196:199], v[44:47]
	v_mfma_f32_16x16x32_bf16 v[40:43], v[156:159], v[196:199], v[40:43]
	v_mfma_f32_16x16x32_bf16 v[28:31], v[148:151], v[204:207], v[28:31]
	v_mfma_f32_16x16x32_bf16 v[24:27], v[156:159], v[204:207], v[24:27]
	v_mfma_f32_16x16x32_bf16 v[12:15], v[148:151], v[212:215], v[12:15]
	v_mfma_f32_16x16x32_bf16 v[8:11], v[156:159], v[212:215], v[8:11]
	s_setprio 0
	s_setprio 1
	v_mfma_f32_16x16x32_bf16 v[52:55], v[160:163], v[184:187], v[52:55]
	v_mfma_f32_16x16x32_bf16 v[48:51], v[168:171], v[184:187], v[48:51]
	v_mfma_f32_16x16x32_bf16 v[36:39], v[160:163], v[192:195], v[36:39]
	v_mfma_f32_16x16x32_bf16 v[32:35], v[168:171], v[192:195], v[32:35]
	v_mfma_f32_16x16x32_bf16 v[20:23], v[160:163], v[200:203], v[20:23]
	v_mfma_f32_16x16x32_bf16 v[16:19], v[168:171], v[200:203], v[16:19]
	v_mfma_f32_16x16x32_bf16 v[4:7], v[160:163], v[208:211], v[4:7]
	v_mfma_f32_16x16x32_bf16 v[0:3], v[168:171], v[208:211], v[0:3]
	v_mfma_f32_16x16x32_bf16 v[52:55], v[164:167], v[188:191], v[52:55]
	v_mfma_f32_16x16x32_bf16 v[48:51], v[172:175], v[188:191], v[48:51]
	v_mfma_f32_16x16x32_bf16 v[36:39], v[164:167], v[196:199], v[36:39]
	v_mfma_f32_16x16x32_bf16 v[32:35], v[172:175], v[196:199], v[32:35]
	s_setprio 2
	s_barrier
	v_mfma_f32_16x16x32_bf16 v[20:23], v[164:167], v[204:207], v[20:23]
	v_mfma_f32_16x16x32_bf16 v[16:19], v[172:175], v[204:207], v[16:19]
	v_mfma_f32_16x16x32_bf16 v[4:7], v[164:167], v[212:215], v[4:7]
	v_mfma_f32_16x16x32_bf16 v[0:3], v[172:175], v[212:215], v[0:3]
	s_setprio 0
	s_add_i32 s73, s73, 2
	s_add_u32 s6, s6, 0x100
	s_addc_u32 s7, s7, 0
	s_add_u32 s71, s71, 0x100
	s_addc_u32 s72, s72, 0
	s_cmp_gt_u32 s73, 13
.LBB0_952:
	ds_read_b128 v[144:147], v179
	ds_read_b128 v[148:151], v179 offset:1024
	ds_read_b128 v[152:155], v179 offset:2048
	ds_read_b128 v[156:159], v179 offset:3072
	ds_read_b128 v[160:163], v180
	ds_read_b128 v[164:167], v180 offset:1024
	ds_read_b128 v[168:171], v180 offset:2048
	ds_read_b128 v[172:175], v180 offset:3072
	s_add_u32 s40, s6, 0xfffc0080
	s_addc_u32 s41, s7, -1
	s_cmp_eq_u32 s73, 12
	s_cselect_b32 s45, s27, s41
	s_cselect_b32 s44, s39, s40
	s_cselect_b32 s41, s29, s72
	s_cselect_b32 s40, s43, s71
	v_lshl_add_u64 v[176:177], s[6:7], 0, v[136:137]
	s_add_i32 m0, s54, 0xc000
	ds_read_b128 v[184:187], v181
	ds_read_b128 v[188:191], v181 offset:1024
	ds_read_b128 v[192:195], v181 offset:2048
	ds_read_b128 v[196:199], v181 offset:3072
	ds_read_b128 v[200:203], v181 offset:4096
	ds_read_b128 v[204:207], v181 offset:5120
	ds_read_b128 v[208:211], v181 offset:6144
	ds_read_b128 v[212:215], v181 offset:7168
	global_load_lds_dwordx4 v[176:177], off
	s_add_i32 m0, s54, 0xe000
	v_lshl_add_u64 v[176:177], s[6:7], 0, v[138:139]
	global_load_lds_dwordx4 v[176:177], off
	s_waitcnt vmcnt(8) lgkmcnt(0)
	s_barrier
	s_setprio 1
	v_mfma_f32_16x16x32_bf16 v[124:127], v[144:147], v[184:187], v[124:127]
	v_mfma_f32_16x16x32_bf16 v[120:123], v[152:155], v[184:187], v[120:123]
	v_mfma_f32_16x16x32_bf16 v[108:111], v[144:147], v[192:195], v[108:111]
	v_mfma_f32_16x16x32_bf16 v[104:107], v[152:155], v[192:195], v[104:107]
	v_mfma_f32_16x16x32_bf16 v[92:95], v[144:147], v[200:203], v[92:95]
	v_mfma_f32_16x16x32_bf16 v[88:91], v[152:155], v[200:203], v[88:91]
	v_mfma_f32_16x16x32_bf16 v[76:79], v[144:147], v[208:211], v[76:79]
	v_mfma_f32_16x16x32_bf16 v[72:75], v[152:155], v[208:211], v[72:75]
	v_mfma_f32_16x16x32_bf16 v[124:127], v[148:151], v[188:191], v[124:127]
	v_mfma_f32_16x16x32_bf16 v[120:123], v[156:159], v[188:191], v[120:123]
	v_mfma_f32_16x16x32_bf16 v[108:111], v[148:151], v[196:199], v[108:111]
	v_mfma_f32_16x16x32_bf16 v[104:107], v[156:159], v[196:199], v[104:107]
	v_mfma_f32_16x16x32_bf16 v[92:95], v[148:151], v[204:207], v[92:95]
	v_mfma_f32_16x16x32_bf16 v[88:91], v[156:159], v[204:207], v[88:91]
	v_mfma_f32_16x16x32_bf16 v[76:79], v[148:151], v[212:215], v[76:79]
	v_mfma_f32_16x16x32_bf16 v[72:75], v[156:159], v[212:215], v[72:75]
	s_setprio 0
	s_setprio 1
	v_mfma_f32_16x16x32_bf16 v[116:119], v[160:163], v[184:187], v[116:119]
	v_mfma_f32_16x16x32_bf16 v[112:115], v[168:171], v[184:187], v[112:115]
	v_mfma_f32_16x16x32_bf16 v[100:103], v[160:163], v[192:195], v[100:103]
	v_mfma_f32_16x16x32_bf16 v[96:99], v[168:171], v[192:195], v[96:99]
	v_mfma_f32_16x16x32_bf16 v[84:87], v[160:163], v[200:203], v[84:87]
	v_mfma_f32_16x16x32_bf16 v[80:83], v[168:171], v[200:203], v[80:83]
	v_mfma_f32_16x16x32_bf16 v[68:71], v[160:163], v[208:211], v[68:71]
	v_mfma_f32_16x16x32_bf16 v[64:67], v[168:171], v[208:211], v[64:67]
	v_mfma_f32_16x16x32_bf16 v[116:119], v[164:167], v[188:191], v[116:119]
	v_mfma_f32_16x16x32_bf16 v[112:115], v[172:175], v[188:191], v[112:115]
	v_mfma_f32_16x16x32_bf16 v[100:103], v[164:167], v[196:199], v[100:103]
	v_mfma_f32_16x16x32_bf16 v[96:99], v[172:175], v[196:199], v[96:99]
	s_setprio 2
	s_barrier
	v_mfma_f32_16x16x32_bf16 v[84:87], v[164:167], v[204:207], v[84:87]
	v_mfma_f32_16x16x32_bf16 v[80:83], v[172:175], v[204:207], v[80:83]
	v_mfma_f32_16x16x32_bf16 v[68:71], v[164:167], v[212:215], v[68:71]
	v_mfma_f32_16x16x32_bf16 v[64:67], v[172:175], v[212:215], v[64:67]
	s_setprio 2
	s_add_i32 s74, s69, s51
	v_lshl_add_u64 v[176:177], s[40:41], 0, v[130:131]
	s_mov_b32 m0, s74
	ds_read_b128 v[184:187], v181 offset:16384
	ds_read_b128 v[188:191], v181 offset:17408
	ds_read_b128 v[192:195], v181 offset:18432
	ds_read_b128 v[196:199], v181 offset:19456
	ds_read_b128 v[200:203], v181 offset:20480
	ds_read_b128 v[204:207], v181 offset:21504
	ds_read_b128 v[208:211], v181 offset:22528
	ds_read_b128 v[212:215], v181 offset:23552
	global_load_lds_dwordx4 v[176:177], off
	s_add_i32 m0, s74, 0x2000
	s_add_u32 s74, s40, 0x40000
	v_lshl_add_u64 v[216:217], s[40:41], 0, v[134:135]
	s_addc_u32 s75, s41, 0
	s_add_i32 s76, s70, s51
	global_load_lds_dwordx4 v[216:217], off
	v_lshl_add_u64 v[218:219], s[74:75], 0, v[130:131]
	s_mov_b32 m0, s76
	v_lshl_add_u64 v[220:221], s[44:45], 0, v[132:133]
	global_load_lds_dwordx4 v[218:219], off
	s_add_i32 m0, s76, 0x2000
	v_lshl_add_u64 v[218:219], s[74:75], 0, v[134:135]
	global_load_lds_dwordx4 v[218:219], off
	s_mov_b32 m0, s54
	v_lshl_add_u64 v[218:219], s[44:45], 0, v[128:129]
	global_load_lds_dwordx4 v[218:219], off
	s_mov_b32 m0, s55
	s_nop 0
	global_load_lds_dwordx4 v[220:221], off
	s_waitcnt vmcnt(8) lgkmcnt(0)
	s_barrier
	s_setprio 1
	v_mfma_f32_16x16x32_bf16 v[60:63], v[144:147], v[184:187], v[60:63]
	v_mfma_f32_16x16x32_bf16 v[56:59], v[152:155], v[184:187], v[56:59]
	v_mfma_f32_16x16x32_bf16 v[44:47], v[144:147], v[192:195], v[44:47]
	v_mfma_f32_16x16x32_bf16 v[40:43], v[152:155], v[192:195], v[40:43]
	v_mfma_f32_16x16x32_bf16 v[28:31], v[144:147], v[200:203], v[28:31]
	v_mfma_f32_16x16x32_bf16 v[24:27], v[152:155], v[200:203], v[24:27]
	v_mfma_f32_16x16x32_bf16 v[12:15], v[144:147], v[208:211], v[12:15]
	v_mfma_f32_16x16x32_bf16 v[8:11], v[152:155], v[208:211], v[8:11]
	v_mfma_f32_16x16x32_bf16 v[60:63], v[148:151], v[188:191], v[60:63]
	v_mfma_f32_16x16x32_bf16 v[56:59], v[156:159], v[188:191], v[56:59]
	v_mfma_f32_16x16x32_bf16 v[44:47], v[148:151], v[196:199], v[44:47]
	v_mfma_f32_16x16x32_bf16 v[40:43], v[156:159], v[196:199], v[40:43]
	v_mfma_f32_16x16x32_bf16 v[28:31], v[148:151], v[204:207], v[28:31]
	v_mfma_f32_16x16x32_bf16 v[24:27], v[156:159], v[204:207], v[24:27]
	v_mfma_f32_16x16x32_bf16 v[12:15], v[148:151], v[212:215], v[12:15]
	v_mfma_f32_16x16x32_bf16 v[8:11], v[156:159], v[212:215], v[8:11]
	s_setprio 0
	s_setprio 1
	v_mfma_f32_16x16x32_bf16 v[52:55], v[160:163], v[184:187], v[52:55]
	v_mfma_f32_16x16x32_bf16 v[48:51], v[168:171], v[184:187], v[48:51]
	v_mfma_f32_16x16x32_bf16 v[36:39], v[160:163], v[192:195], v[36:39]
	v_mfma_f32_16x16x32_bf16 v[32:35], v[168:171], v[192:195], v[32:35]
	v_mfma_f32_16x16x32_bf16 v[20:23], v[160:163], v[200:203], v[20:23]
	v_mfma_f32_16x16x32_bf16 v[16:19], v[168:171], v[200:203], v[16:19]
	v_mfma_f32_16x16x32_bf16 v[4:7], v[160:163], v[208:211], v[4:7]
	v_mfma_f32_16x16x32_bf16 v[0:3], v[168:171], v[208:211], v[0:3]
	v_mfma_f32_16x16x32_bf16 v[52:55], v[164:167], v[188:191], v[52:55]
	v_mfma_f32_16x16x32_bf16 v[48:51], v[172:175], v[188:191], v[48:51]
	v_mfma_f32_16x16x32_bf16 v[36:39], v[164:167], v[196:199], v[36:39]
	v_mfma_f32_16x16x32_bf16 v[32:35], v[172:175], v[196:199], v[32:35]
	s_setprio 2
	s_barrier
	v_mfma_f32_16x16x32_bf16 v[20:23], v[164:167], v[204:207], v[20:23]
	v_mfma_f32_16x16x32_bf16 v[16:19], v[172:175], v[204:207], v[16:19]
	v_mfma_f32_16x16x32_bf16 v[4:7], v[164:167], v[212:215], v[4:7]
	v_mfma_f32_16x16x32_bf16 v[0:3], v[172:175], v[212:215], v[0:3]
	s_setprio 0
	s_add_i32 s74, 0, 0x18000
	s_add_i32 s75, 0, 0x1c000
	v_add_u32_e32 v156, s74, v178
	v_add_u32_e32 v172, s75, v178
	ds_read_b128 v[144:147], v156
	ds_read_b128 v[148:151], v156 offset:1024
	ds_read_b128 v[152:155], v156 offset:2048
	ds_read_b128 v[156:159], v156 offset:3072
	ds_read_b128 v[160:163], v172
	ds_read_b128 v[164:167], v172 offset:1024
	ds_read_b128 v[168:171], v172 offset:2048
	ds_read_b128 v[172:175], v172 offset:3072
	s_add_u32 s44, s44, 0x40000
	s_addc_u32 s45, s45, 0
	s_mov_b32 m0, s56
	v_lshl_add_u64 v[222:223], s[44:45], 0, v[128:129]
	ds_read_b128 v[184:187], v181 offset:32768
	ds_read_b128 v[188:191], v181 offset:33792
	ds_read_b128 v[192:195], v181 offset:34816
	ds_read_b128 v[196:199], v181 offset:35840
	ds_read_b128 v[200:203], v181 offset:36864
	ds_read_b128 v[204:207], v181 offset:37888
	ds_read_b128 v[208:211], v181 offset:38912
	ds_read_b128 v[212:215], v181 offset:39936
	global_load_lds_dwordx4 v[222:223], off
	s_mov_b32 m0, s57
	v_lshl_add_u64 v[222:223], s[44:45], 0, v[132:133]
	global_load_lds_dwordx4 v[222:223], off
	s_waitcnt vmcnt(8) lgkmcnt(0)
	s_barrier
	s_setprio 1
	v_mfma_f32_16x16x32_bf16 v[124:127], v[144:147], v[184:187], v[124:127]
	v_mfma_f32_16x16x32_bf16 v[120:123], v[152:155], v[184:187], v[120:123]
	v_mfma_f32_16x16x32_bf16 v[108:111], v[144:147], v[192:195], v[108:111]
	v_mfma_f32_16x16x32_bf16 v[104:107], v[152:155], v[192:195], v[104:107]
	v_mfma_f32_16x16x32_bf16 v[92:95], v[144:147], v[200:203], v[92:95]
	v_mfma_f32_16x16x32_bf16 v[88:91], v[152:155], v[200:203], v[88:91]
	v_mfma_f32_16x16x32_bf16 v[76:79], v[144:147], v[208:211], v[76:79]
	v_mfma_f32_16x16x32_bf16 v[72:75], v[152:155], v[208:211], v[72:75]
	v_mfma_f32_16x16x32_bf16 v[124:127], v[148:151], v[188:191], v[124:127]
	v_mfma_f32_16x16x32_bf16 v[120:123], v[156:159], v[188:191], v[120:123]
	v_mfma_f32_16x16x32_bf16 v[108:111], v[148:151], v[196:199], v[108:111]
	v_mfma_f32_16x16x32_bf16 v[104:107], v[156:159], v[196:199], v[104:107]
	v_mfma_f32_16x16x32_bf16 v[92:95], v[148:151], v[204:207], v[92:95]
	v_mfma_f32_16x16x32_bf16 v[88:91], v[156:159], v[204:207], v[88:91]
	v_mfma_f32_16x16x32_bf16 v[76:79], v[148:151], v[212:215], v[76:79]
	v_mfma_f32_16x16x32_bf16 v[72:75], v[156:159], v[212:215], v[72:75]
	s_setprio 0
	s_setprio 1
	v_mfma_f32_16x16x32_bf16 v[116:119], v[160:163], v[184:187], v[116:119]
	v_mfma_f32_16x16x32_bf16 v[112:115], v[168:171], v[184:187], v[112:115]
	v_mfma_f32_16x16x32_bf16 v[100:103], v[160:163], v[192:195], v[100:103]
	v_mfma_f32_16x16x32_bf16 v[96:99], v[168:171], v[192:195], v[96:99]
	v_mfma_f32_16x16x32_bf16 v[84:87], v[160:163], v[200:203], v[84:87]
	v_mfma_f32_16x16x32_bf16 v[80:83], v[168:171], v[200:203], v[80:83]
	v_mfma_f32_16x16x32_bf16 v[68:71], v[160:163], v[208:211], v[68:71]
	v_mfma_f32_16x16x32_bf16 v[64:67], v[168:171], v[208:211], v[64:67]
	v_mfma_f32_16x16x32_bf16 v[116:119], v[164:167], v[188:191], v[116:119]
	v_mfma_f32_16x16x32_bf16 v[112:115], v[172:175], v[188:191], v[112:115]
	v_mfma_f32_16x16x32_bf16 v[100:103], v[164:167], v[196:199], v[100:103]
	v_mfma_f32_16x16x32_bf16 v[96:99], v[172:175], v[196:199], v[96:99]
	s_setprio 2
	s_barrier
	v_mfma_f32_16x16x32_bf16 v[84:87], v[164:167], v[204:207], v[84:87]
	v_mfma_f32_16x16x32_bf16 v[80:83], v[172:175], v[204:207], v[80:83]
	v_mfma_f32_16x16x32_bf16 v[68:71], v[164:167], v[212:215], v[68:71]
	v_mfma_f32_16x16x32_bf16 v[64:67], v[172:175], v[212:215], v[64:67]
	s_setprio 2
	s_add_i32 s44, s74, s51
	v_lshl_add_u64 v[176:177], v[176:177], 0, s[22:23]
	s_mov_b32 m0, s44
	ds_read_b128 v[184:187], v181 offset:49152
	ds_read_b128 v[188:191], v181 offset:50176
	ds_read_b128 v[192:195], v181 offset:51200
	ds_read_b128 v[196:199], v181 offset:52224
	ds_read_b128 v[200:203], v181 offset:53248
	ds_read_b128 v[204:207], v181 offset:54272
	ds_read_b128 v[208:211], v181 offset:55296
	ds_read_b128 v[212:215], v181 offset:56320
	global_load_lds_dwordx4 v[176:177], off
	s_add_i32 m0, s44, 0x2000
	s_add_u32 s40, s40, 0x40080
	v_lshl_add_u64 v[176:177], v[216:217], 0, s[22:23]
	s_addc_u32 s41, s41, 0
	s_add_i32 s44, s75, s51
	global_load_lds_dwordx4 v[176:177], off
	s_mov_b32 m0, s44
	v_lshl_add_u64 v[176:177], s[40:41], 0, v[130:131]
	global_load_lds_dwordx4 v[176:177], off
	s_add_i32 m0, s44, 0x2000
	v_lshl_add_u64 v[176:177], s[40:41], 0, v[134:135]
	global_load_lds_dwordx4 v[176:177], off
	s_mov_b32 m0, s64
	v_lshl_add_u64 v[176:177], v[218:219], 0, s[22:23]
	global_load_lds_dwordx4 v[176:177], off
	s_mov_b32 m0, s65
	v_lshl_add_u64 v[176:177], v[220:221], 0, s[22:23]
	global_load_lds_dwordx4 v[176:177], off
	s_waitcnt vmcnt(8) lgkmcnt(0)
	s_barrier
	s_setprio 1
	v_mfma_f32_16x16x32_bf16 v[60:63], v[144:147], v[184:187], v[60:63]
	v_mfma_f32_16x16x32_bf16 v[56:59], v[152:155], v[184:187], v[56:59]
	v_mfma_f32_16x16x32_bf16 v[44:47], v[144:147], v[192:195], v[44:47]
	v_mfma_f32_16x16x32_bf16 v[40:43], v[152:155], v[192:195], v[40:43]
	v_mfma_f32_16x16x32_bf16 v[28:31], v[144:147], v[200:203], v[28:31]
	v_mfma_f32_16x16x32_bf16 v[24:27], v[152:155], v[200:203], v[24:27]
	v_mfma_f32_16x16x32_bf16 v[12:15], v[144:147], v[208:211], v[12:15]
	v_mfma_f32_16x16x32_bf16 v[8:11], v[152:155], v[208:211], v[8:11]
	v_mfma_f32_16x16x32_bf16 v[60:63], v[148:151], v[188:191], v[60:63]
	v_mfma_f32_16x16x32_bf16 v[56:59], v[156:159], v[188:191], v[56:59]
	v_mfma_f32_16x16x32_bf16 v[44:47], v[148:151], v[196:199], v[44:47]
	v_mfma_f32_16x16x32_bf16 v[40:43], v[156:159], v[196:199], v[40:43]
	v_mfma_f32_16x16x32_bf16 v[28:31], v[148:151], v[204:207], v[28:31]
	v_mfma_f32_16x16x32_bf16 v[24:27], v[156:159], v[204:207], v[24:27]
	v_mfma_f32_16x16x32_bf16 v[12:15], v[148:151], v[212:215], v[12:15]
	v_mfma_f32_16x16x32_bf16 v[8:11], v[156:159], v[212:215], v[8:11]
	s_setprio 0
	s_setprio 1
	v_mfma_f32_16x16x32_bf16 v[52:55], v[160:163], v[184:187], v[52:55]
	v_mfma_f32_16x16x32_bf16 v[48:51], v[168:171], v[184:187], v[48:51]
	v_mfma_f32_16x16x32_bf16 v[36:39], v[160:163], v[192:195], v[36:39]
	v_mfma_f32_16x16x32_bf16 v[32:35], v[168:171], v[192:195], v[32:35]
	v_mfma_f32_16x16x32_bf16 v[20:23], v[160:163], v[200:203], v[20:23]
	v_mfma_f32_16x16x32_bf16 v[16:19], v[168:171], v[200:203], v[16:19]
	v_mfma_f32_16x16x32_bf16 v[4:7], v[160:163], v[208:211], v[4:7]
	v_mfma_f32_16x16x32_bf16 v[0:3], v[168:171], v[208:211], v[0:3]
	v_mfma_f32_16x16x32_bf16 v[52:55], v[164:167], v[188:191], v[52:55]
	v_mfma_f32_16x16x32_bf16 v[48:51], v[172:175], v[188:191], v[48:51]
	v_mfma_f32_16x16x32_bf16 v[36:39], v[164:167], v[196:199], v[36:39]
	v_mfma_f32_16x16x32_bf16 v[32:35], v[172:175], v[196:199], v[32:35]
	s_setprio 2
	s_barrier
	v_mfma_f32_16x16x32_bf16 v[20:23], v[164:167], v[204:207], v[20:23]
	v_mfma_f32_16x16x32_bf16 v[16:19], v[172:175], v[204:207], v[16:19]
	v_mfma_f32_16x16x32_bf16 v[4:7], v[164:167], v[212:215], v[4:7]
	v_mfma_f32_16x16x32_bf16 v[0:3], v[172:175], v[212:215], v[0:3]
	s_setprio 0
	s_add_i32 s73, s73, 2
	s_add_u32 s6, s6, 0x100
	s_addc_u32 s7, s7, 0
	s_add_u32 s71, s71, 0x100
	s_addc_u32 s72, s72, 0
	s_cmp_gt_u32 s73, 13
	s_cbranch_scc0 .LBB0_952

.LBB0_1145:
	s_ashr_i32 s23, s22, 31
	s_lshl_b64 s[26:27], s[22:23], 19
	s_add_u32 s26, s45, s26
	s_addc_u32 s27, s46, s27
	s_and_b64 s[28:29], s[4:5], exec
	s_cselect_b32 s23, s27, s39
	s_cselect_b32 s31, s26, s38
	s_ashr_i32 s25, s24, 31
	s_lshl_b64 s[28:29], s[24:25], 19
	s_add_u32 s28, s47, s28
	s_addc_u32 s29, s48, s29
	s_and_b64 s[42:43], s[4:5], exec
	s_cselect_b32 s25, s29, s41
	s_cselect_b32 s37, s28, s40
	s_add_u32 s38, s38, 0x40080
	s_addc_u32 s39, s39, 0
	s_add_u32 s64, s40, 0x100
	s_addc_u32 s65, s41, 0
	s_mov_b32 s66, -2
	ds_read_b128 v[120:123], v233
	ds_read_b128 v[132:135], v233 offset:1024
	ds_read_b128 v[136:139], v233 offset:2048
	ds_read_b128 v[140:143], v233 offset:3072
	ds_read_b128 v[144:147], v234
	ds_read_b128 v[148:151], v234 offset:1024
	ds_read_b128 v[152:155], v234 offset:2048
	ds_read_b128 v[156:159], v234 offset:3072
	s_add_u32 s40, s38, 0xfffc0080
	s_addc_u32 s41, s39, -1
	s_cmp_eq_u32 s66, 12
	s_cselect_b32 s43, s23, s41
	s_cselect_b32 s42, s31, s40
	s_cselect_b32 s41, s25, s65
	s_cselect_b32 s40, s37, s64
	v_lshl_add_u64 v[208:209], s[38:39], 0, v[192:193]
	s_add_i32 m0, s50, 0xc000
	ds_read_b128 v[160:163], v235
	ds_read_b128 v[164:167], v235 offset:1024
	ds_read_b128 v[168:171], v235 offset:2048
	ds_read_b128 v[172:175], v235 offset:3072
	ds_read_b128 v[176:179], v235 offset:4096
	ds_read_b128 v[180:183], v235 offset:5120
	ds_read_b128 v[200:203], v235 offset:6144
	ds_read_b128 v[204:207], v235 offset:7168
	global_load_lds_dwordx4 v[208:209], off
	s_add_i32 m0, s50, 0xe000
	v_lshl_add_u64 v[208:209], s[38:39], 0, v[194:195]
	global_load_lds_dwordx4 v[208:209], off
	s_waitcnt vmcnt(8) lgkmcnt(0)
	s_barrier
	s_setprio 1
	v_mfma_f32_16x16x32_bf16 v[128:131], v[120:123], v[160:163], 0
	v_mfma_f32_16x16x32_bf16 v[124:127], v[136:139], v[160:163], 0
	v_mfma_f32_16x16x32_bf16 v[108:111], v[120:123], v[168:171], 0
	v_mfma_f32_16x16x32_bf16 v[104:107], v[136:139], v[168:171], 0
	v_mfma_f32_16x16x32_bf16 v[92:95], v[120:123], v[176:179], 0
	v_mfma_f32_16x16x32_bf16 v[88:91], v[136:139], v[176:179], 0
	v_mfma_f32_16x16x32_bf16 v[76:79], v[120:123], v[200:203], 0
	v_mfma_f32_16x16x32_bf16 v[72:75], v[136:139], v[200:203], 0
	v_mfma_f32_16x16x32_bf16 v[128:131], v[132:135], v[164:167], v[128:131]
	v_mfma_f32_16x16x32_bf16 v[124:127], v[140:143], v[164:167], v[124:127]
	v_mfma_f32_16x16x32_bf16 v[108:111], v[132:135], v[172:175], v[108:111]
	v_mfma_f32_16x16x32_bf16 v[104:107], v[140:143], v[172:175], v[104:107]
	v_mfma_f32_16x16x32_bf16 v[92:95], v[132:135], v[180:183], v[92:95]
	v_mfma_f32_16x16x32_bf16 v[88:91], v[140:143], v[180:183], v[88:91]
	v_mfma_f32_16x16x32_bf16 v[76:79], v[132:135], v[204:207], v[76:79]
	v_mfma_f32_16x16x32_bf16 v[72:75], v[140:143], v[204:207], v[72:75]
	s_setprio 0
	s_setprio 1
	v_mfma_f32_16x16x32_bf16 v[116:119], v[144:147], v[160:163], 0
	v_mfma_f32_16x16x32_bf16 v[112:115], v[152:155], v[160:163], 0
	v_mfma_f32_16x16x32_bf16 v[100:103], v[144:147], v[168:171], 0
	v_mfma_f32_16x16x32_bf16 v[96:99], v[152:155], v[168:171], 0
	v_mfma_f32_16x16x32_bf16 v[84:87], v[144:147], v[176:179], 0
	v_mfma_f32_16x16x32_bf16 v[80:83], v[152:155], v[176:179], 0
	v_mfma_f32_16x16x32_bf16 v[68:71], v[144:147], v[200:203], 0
	v_mfma_f32_16x16x32_bf16 v[64:67], v[152:155], v[200:203], 0
	v_mfma_f32_16x16x32_bf16 v[116:119], v[148:151], v[164:167], v[116:119]
	v_mfma_f32_16x16x32_bf16 v[112:115], v[156:159], v[164:167], v[112:115]
	v_mfma_f32_16x16x32_bf16 v[100:103], v[148:151], v[172:175], v[100:103]
	v_mfma_f32_16x16x32_bf16 v[96:99], v[156:159], v[172:175], v[96:99]
	s_setprio 2
	s_barrier
	v_mfma_f32_16x16x32_bf16 v[84:87], v[148:151], v[180:183], v[84:87]
	v_mfma_f32_16x16x32_bf16 v[80:83], v[156:159], v[180:183], v[80:83]
	v_mfma_f32_16x16x32_bf16 v[68:71], v[148:151], v[204:207], v[68:71]
	v_mfma_f32_16x16x32_bf16 v[64:67], v[156:159], v[204:207], v[64:67]
	s_setprio 2
	s_add_i32 s67, s62, s49
	v_lshl_add_u64 v[208:209], s[40:41], 0, v[186:187]
	s_mov_b32 m0, s67
	ds_read_b128 v[160:163], v235 offset:16384
	ds_read_b128 v[164:167], v235 offset:17408
	ds_read_b128 v[168:171], v235 offset:18432
	ds_read_b128 v[172:175], v235 offset:19456
	ds_read_b128 v[176:179], v235 offset:20480
	ds_read_b128 v[180:183], v235 offset:21504
	ds_read_b128 v[200:203], v235 offset:22528
	ds_read_b128 v[204:207], v235 offset:23552
	global_load_lds_dwordx4 v[208:209], off
	s_add_i32 m0, s67, 0x2000
	s_add_u32 s68, s40, 0x40000
	v_lshl_add_u64 v[210:211], s[40:41], 0, v[190:191]
	s_addc_u32 s69, s41, 0
	s_add_i32 s67, s63, s49
	global_load_lds_dwordx4 v[210:211], off
	v_lshl_add_u64 v[212:213], s[68:69], 0, v[186:187]
	s_mov_b32 m0, s67
	v_lshl_add_u64 v[214:215], s[42:43], 0, v[188:189]
	global_load_lds_dwordx4 v[212:213], off
	s_add_i32 m0, s67, 0x2000
	v_lshl_add_u64 v[212:213], s[68:69], 0, v[190:191]
	global_load_lds_dwordx4 v[212:213], off
	s_mov_b32 m0, s50
	v_lshl_add_u64 v[212:213], s[42:43], 0, v[184:185]
	global_load_lds_dwordx4 v[212:213], off
	s_mov_b32 m0, s51
	s_nop 0
	global_load_lds_dwordx4 v[214:215], off
	s_waitcnt vmcnt(8) lgkmcnt(0)
	s_barrier
	s_setprio 1
	v_mfma_f32_16x16x32_bf16 v[60:63], v[120:123], v[160:163], 0
	v_mfma_f32_16x16x32_bf16 v[56:59], v[136:139], v[160:163], 0
	v_mfma_f32_16x16x32_bf16 v[44:47], v[120:123], v[168:171], 0
	v_mfma_f32_16x16x32_bf16 v[40:43], v[136:139], v[168:171], 0
	v_mfma_f32_16x16x32_bf16 v[28:31], v[120:123], v[176:179], 0
	v_mfma_f32_16x16x32_bf16 v[24:27], v[136:139], v[176:179], 0
	v_mfma_f32_16x16x32_bf16 v[12:15], v[120:123], v[200:203], 0
	v_mfma_f32_16x16x32_bf16 v[8:11], v[136:139], v[200:203], 0
	v_mfma_f32_16x16x32_bf16 v[60:63], v[132:135], v[164:167], v[60:63]
	v_mfma_f32_16x16x32_bf16 v[56:59], v[140:143], v[164:167], v[56:59]
	v_mfma_f32_16x16x32_bf16 v[44:47], v[132:135], v[172:175], v[44:47]
	v_mfma_f32_16x16x32_bf16 v[40:43], v[140:143], v[172:175], v[40:43]
	v_mfma_f32_16x16x32_bf16 v[28:31], v[132:135], v[180:183], v[28:31]
	v_mfma_f32_16x16x32_bf16 v[24:27], v[140:143], v[180:183], v[24:27]
	v_mfma_f32_16x16x32_bf16 v[12:15], v[132:135], v[204:207], v[12:15]
	v_mfma_f32_16x16x32_bf16 v[8:11], v[140:143], v[204:207], v[8:11]
	s_setprio 0
	s_setprio 1
	v_mfma_f32_16x16x32_bf16 v[52:55], v[144:147], v[160:163], 0
	v_mfma_f32_16x16x32_bf16 v[48:51], v[152:155], v[160:163], 0
	v_mfma_f32_16x16x32_bf16 v[36:39], v[144:147], v[168:171], 0
	v_mfma_f32_16x16x32_bf16 v[32:35], v[152:155], v[168:171], 0
	v_mfma_f32_16x16x32_bf16 v[20:23], v[144:147], v[176:179], 0
	v_mfma_f32_16x16x32_bf16 v[16:19], v[152:155], v[176:179], 0
	v_mfma_f32_16x16x32_bf16 v[4:7], v[144:147], v[200:203], 0
	v_mfma_f32_16x16x32_bf16 v[0:3], v[152:155], v[200:203], 0
	v_mfma_f32_16x16x32_bf16 v[52:55], v[148:151], v[164:167], v[52:55]
	v_mfma_f32_16x16x32_bf16 v[48:51], v[156:159], v[164:167], v[48:51]
	v_mfma_f32_16x16x32_bf16 v[36:39], v[148:151], v[172:175], v[36:39]
	v_mfma_f32_16x16x32_bf16 v[32:35], v[156:159], v[172:175], v[32:35]
	s_setprio 2
	s_barrier
	v_mfma_f32_16x16x32_bf16 v[20:23], v[148:151], v[180:183], v[20:23]
	v_mfma_f32_16x16x32_bf16 v[16:19], v[156:159], v[180:183], v[16:19]
	v_mfma_f32_16x16x32_bf16 v[4:7], v[148:151], v[204:207], v[4:7]
	v_mfma_f32_16x16x32_bf16 v[0:3], v[156:159], v[204:207], v[0:3]
	s_setprio 0
	s_add_i32 s67, 0, 0x18000
	s_add_i32 s68, 0, 0x1c000
	v_add_u32_e32 v140, s67, v232
	v_add_u32_e32 v156, s68, v232
	ds_read_b128 v[120:123], v140
	ds_read_b128 v[132:135], v140 offset:1024
	ds_read_b128 v[136:139], v140 offset:2048
	ds_read_b128 v[140:143], v140 offset:3072
	ds_read_b128 v[144:147], v156
	ds_read_b128 v[148:151], v156 offset:1024
	ds_read_b128 v[152:155], v156 offset:2048
	ds_read_b128 v[156:159], v156 offset:3072
	s_add_u32 s42, s42, 0x40000
	s_addc_u32 s43, s43, 0
	s_mov_b32 m0, s54
	v_lshl_add_u64 v[216:217], s[42:43], 0, v[184:185]
	ds_read_b128 v[160:163], v235 offset:32768
	ds_read_b128 v[164:167], v235 offset:33792
	ds_read_b128 v[168:171], v235 offset:34816
	ds_read_b128 v[172:175], v235 offset:35840
	ds_read_b128 v[176:179], v235 offset:36864
	ds_read_b128 v[180:183], v235 offset:37888
	ds_read_b128 v[200:203], v235 offset:38912
	ds_read_b128 v[204:207], v235 offset:39936
	global_load_lds_dwordx4 v[216:217], off
	s_mov_b32 m0, s55
	v_lshl_add_u64 v[216:217], s[42:43], 0, v[188:189]
	global_load_lds_dwordx4 v[216:217], off
	s_waitcnt vmcnt(8) lgkmcnt(0)
	s_barrier
	s_setprio 1
	v_mfma_f32_16x16x32_bf16 v[128:131], v[120:123], v[160:163], v[128:131]
	v_mfma_f32_16x16x32_bf16 v[124:127], v[136:139], v[160:163], v[124:127]
	v_mfma_f32_16x16x32_bf16 v[108:111], v[120:123], v[168:171], v[108:111]
	v_mfma_f32_16x16x32_bf16 v[104:107], v[136:139], v[168:171], v[104:107]
	v_mfma_f32_16x16x32_bf16 v[92:95], v[120:123], v[176:179], v[92:95]
	v_mfma_f32_16x16x32_bf16 v[88:91], v[136:139], v[176:179], v[88:91]
	v_mfma_f32_16x16x32_bf16 v[76:79], v[120:123], v[200:203], v[76:79]
	v_mfma_f32_16x16x32_bf16 v[72:75], v[136:139], v[200:203], v[72:75]
	v_mfma_f32_16x16x32_bf16 v[128:131], v[132:135], v[164:167], v[128:131]
	v_mfma_f32_16x16x32_bf16 v[124:127], v[140:143], v[164:167], v[124:127]
	v_mfma_f32_16x16x32_bf16 v[108:111], v[132:135], v[172:175], v[108:111]
	v_mfma_f32_16x16x32_bf16 v[104:107], v[140:143], v[172:175], v[104:107]
	v_mfma_f32_16x16x32_bf16 v[92:95], v[132:135], v[180:183], v[92:95]
	v_mfma_f32_16x16x32_bf16 v[88:91], v[140:143], v[180:183], v[88:91]
	v_mfma_f32_16x16x32_bf16 v[76:79], v[132:135], v[204:207], v[76:79]
	v_mfma_f32_16x16x32_bf16 v[72:75], v[140:143], v[204:207], v[72:75]
	s_setprio 0
	s_setprio 1
	v_mfma_f32_16x16x32_bf16 v[116:119], v[144:147], v[160:163], v[116:119]
	v_mfma_f32_16x16x32_bf16 v[112:115], v[152:155], v[160:163], v[112:115]
	v_mfma_f32_16x16x32_bf16 v[100:103], v[144:147], v[168:171], v[100:103]
	v_mfma_f32_16x16x32_bf16 v[96:99], v[152:155], v[168:171], v[96:99]
	v_mfma_f32_16x16x32_bf16 v[84:87], v[144:147], v[176:179], v[84:87]
	v_mfma_f32_16x16x32_bf16 v[80:83], v[152:155], v[176:179], v[80:83]
	v_mfma_f32_16x16x32_bf16 v[68:71], v[144:147], v[200:203], v[68:71]
	v_mfma_f32_16x16x32_bf16 v[64:67], v[152:155], v[200:203], v[64:67]
	v_mfma_f32_16x16x32_bf16 v[116:119], v[148:151], v[164:167], v[116:119]
	v_mfma_f32_16x16x32_bf16 v[112:115], v[156:159], v[164:167], v[112:115]
	v_mfma_f32_16x16x32_bf16 v[100:103], v[148:151], v[172:175], v[100:103]
	v_mfma_f32_16x16x32_bf16 v[96:99], v[156:159], v[172:175], v[96:99]
	s_setprio 2
	s_barrier
	v_mfma_f32_16x16x32_bf16 v[84:87], v[148:151], v[180:183], v[84:87]
	v_mfma_f32_16x16x32_bf16 v[80:83], v[156:159], v[180:183], v[80:83]
	v_mfma_f32_16x16x32_bf16 v[68:71], v[148:151], v[204:207], v[68:71]
	v_mfma_f32_16x16x32_bf16 v[64:67], v[156:159], v[204:207], v[64:67]
	s_setprio 2
	s_add_i32 s42, s67, s49
	v_lshl_add_u64 v[208:209], v[208:209], 0, s[18:19]
	s_mov_b32 m0, s42
	ds_read_b128 v[160:163], v235 offset:49152
	ds_read_b128 v[164:167], v235 offset:50176
	ds_read_b128 v[168:171], v235 offset:51200
	ds_read_b128 v[172:175], v235 offset:52224
	ds_read_b128 v[176:179], v235 offset:53248
	ds_read_b128 v[180:183], v235 offset:54272
	ds_read_b128 v[200:203], v235 offset:55296
	ds_read_b128 v[204:207], v235 offset:56320
	global_load_lds_dwordx4 v[208:209], off
	s_add_i32 m0, s42, 0x2000
	s_add_u32 s40, s40, 0x40080
	v_lshl_add_u64 v[208:209], v[210:211], 0, s[18:19]
	s_addc_u32 s41, s41, 0
	s_add_i32 s42, s68, s49
	global_load_lds_dwordx4 v[208:209], off
	s_mov_b32 m0, s42
	v_lshl_add_u64 v[208:209], s[40:41], 0, v[186:187]
	global_load_lds_dwordx4 v[208:209], off
	s_add_i32 m0, s42, 0x2000
	v_lshl_add_u64 v[208:209], s[40:41], 0, v[190:191]
	global_load_lds_dwordx4 v[208:209], off
	s_mov_b32 m0, s57
	v_lshl_add_u64 v[208:209], v[212:213], 0, s[18:19]
	global_load_lds_dwordx4 v[208:209], off
	s_mov_b32 m0, s58
	v_lshl_add_u64 v[208:209], v[214:215], 0, s[18:19]
	global_load_lds_dwordx4 v[208:209], off
	s_waitcnt vmcnt(8) lgkmcnt(0)
	s_barrier
	s_setprio 1
	v_mfma_f32_16x16x32_bf16 v[60:63], v[120:123], v[160:163], v[60:63]
	v_mfma_f32_16x16x32_bf16 v[56:59], v[136:139], v[160:163], v[56:59]
	v_mfma_f32_16x16x32_bf16 v[44:47], v[120:123], v[168:171], v[44:47]
	v_mfma_f32_16x16x32_bf16 v[40:43], v[136:139], v[168:171], v[40:43]
	v_mfma_f32_16x16x32_bf16 v[28:31], v[120:123], v[176:179], v[28:31]
	v_mfma_f32_16x16x32_bf16 v[24:27], v[136:139], v[176:179], v[24:27]
	v_mfma_f32_16x16x32_bf16 v[12:15], v[120:123], v[200:203], v[12:15]
	v_mfma_f32_16x16x32_bf16 v[8:11], v[136:139], v[200:203], v[8:11]
	v_mfma_f32_16x16x32_bf16 v[60:63], v[132:135], v[164:167], v[60:63]
	v_mfma_f32_16x16x32_bf16 v[56:59], v[140:143], v[164:167], v[56:59]
	v_mfma_f32_16x16x32_bf16 v[44:47], v[132:135], v[172:175], v[44:47]
	v_mfma_f32_16x16x32_bf16 v[40:43], v[140:143], v[172:175], v[40:43]
	v_mfma_f32_16x16x32_bf16 v[28:31], v[132:135], v[180:183], v[28:31]
	v_mfma_f32_16x16x32_bf16 v[24:27], v[140:143], v[180:183], v[24:27]
	v_mfma_f32_16x16x32_bf16 v[12:15], v[132:135], v[204:207], v[12:15]
	v_mfma_f32_16x16x32_bf16 v[8:11], v[140:143], v[204:207], v[8:11]
	s_setprio 0
	s_setprio 1
	v_mfma_f32_16x16x32_bf16 v[52:55], v[144:147], v[160:163], v[52:55]
	v_mfma_f32_16x16x32_bf16 v[48:51], v[152:155], v[160:163], v[48:51]
	v_mfma_f32_16x16x32_bf16 v[36:39], v[144:147], v[168:171], v[36:39]
	v_mfma_f32_16x16x32_bf16 v[32:35], v[152:155], v[168:171], v[32:35]
	v_mfma_f32_16x16x32_bf16 v[20:23], v[144:147], v[176:179], v[20:23]
	v_mfma_f32_16x16x32_bf16 v[16:19], v[152:155], v[176:179], v[16:19]
	v_mfma_f32_16x16x32_bf16 v[4:7], v[144:147], v[200:203], v[4:7]
	v_mfma_f32_16x16x32_bf16 v[0:3], v[152:155], v[200:203], v[0:3]
	v_mfma_f32_16x16x32_bf16 v[52:55], v[148:151], v[164:167], v[52:55]
	v_mfma_f32_16x16x32_bf16 v[48:51], v[156:159], v[164:167], v[48:51]
	v_mfma_f32_16x16x32_bf16 v[36:39], v[148:151], v[172:175], v[36:39]
	v_mfma_f32_16x16x32_bf16 v[32:35], v[156:159], v[172:175], v[32:35]
	s_setprio 2
	s_barrier
	v_mfma_f32_16x16x32_bf16 v[20:23], v[148:151], v[180:183], v[20:23]
	v_mfma_f32_16x16x32_bf16 v[16:19], v[156:159], v[180:183], v[16:19]
	v_mfma_f32_16x16x32_bf16 v[4:7], v[148:151], v[204:207], v[4:7]
	v_mfma_f32_16x16x32_bf16 v[0:3], v[156:159], v[204:207], v[0:3]
	s_setprio 0
	s_add_i32 s66, s66, 2
	s_add_u32 s38, s38, 0x100
	s_addc_u32 s39, s39, 0
	s_add_u32 s64, s64, 0x100
	s_addc_u32 s65, s65, 0
	s_cmp_gt_u32 s66, 13
.LBB0_1146:
	ds_read_b128 v[120:123], v233
	ds_read_b128 v[132:135], v233 offset:1024
	ds_read_b128 v[136:139], v233 offset:2048
	ds_read_b128 v[140:143], v233 offset:3072
	ds_read_b128 v[144:147], v234
	ds_read_b128 v[148:151], v234 offset:1024
	ds_read_b128 v[152:155], v234 offset:2048
	ds_read_b128 v[156:159], v234 offset:3072
	s_add_u32 s40, s38, 0xfffc0080
	s_addc_u32 s41, s39, -1
	s_cmp_eq_u32 s66, 12
	s_cselect_b32 s43, s23, s41
	s_cselect_b32 s42, s31, s40
	s_cselect_b32 s41, s25, s65
	s_cselect_b32 s40, s37, s64
	v_lshl_add_u64 v[208:209], s[38:39], 0, v[192:193]
	s_add_i32 m0, s50, 0xc000
	ds_read_b128 v[160:163], v235
	ds_read_b128 v[164:167], v235 offset:1024
	ds_read_b128 v[168:171], v235 offset:2048
	ds_read_b128 v[172:175], v235 offset:3072
	ds_read_b128 v[176:179], v235 offset:4096
	ds_read_b128 v[180:183], v235 offset:5120
	ds_read_b128 v[200:203], v235 offset:6144
	ds_read_b128 v[204:207], v235 offset:7168
	global_load_lds_dwordx4 v[208:209], off
	s_add_i32 m0, s50, 0xe000
	v_lshl_add_u64 v[208:209], s[38:39], 0, v[194:195]
	global_load_lds_dwordx4 v[208:209], off
	s_waitcnt vmcnt(8) lgkmcnt(0)
	s_barrier
	s_setprio 1
	v_mfma_f32_16x16x32_bf16 v[128:131], v[120:123], v[160:163], v[128:131]
	v_mfma_f32_16x16x32_bf16 v[124:127], v[136:139], v[160:163], v[124:127]
	v_mfma_f32_16x16x32_bf16 v[108:111], v[120:123], v[168:171], v[108:111]
	v_mfma_f32_16x16x32_bf16 v[104:107], v[136:139], v[168:171], v[104:107]
	v_mfma_f32_16x16x32_bf16 v[92:95], v[120:123], v[176:179], v[92:95]
	v_mfma_f32_16x16x32_bf16 v[88:91], v[136:139], v[176:179], v[88:91]
	v_mfma_f32_16x16x32_bf16 v[76:79], v[120:123], v[200:203], v[76:79]
	v_mfma_f32_16x16x32_bf16 v[72:75], v[136:139], v[200:203], v[72:75]
	v_mfma_f32_16x16x32_bf16 v[128:131], v[132:135], v[164:167], v[128:131]
	v_mfma_f32_16x16x32_bf16 v[124:127], v[140:143], v[164:167], v[124:127]
	v_mfma_f32_16x16x32_bf16 v[108:111], v[132:135], v[172:175], v[108:111]
	v_mfma_f32_16x16x32_bf16 v[104:107], v[140:143], v[172:175], v[104:107]
	v_mfma_f32_16x16x32_bf16 v[92:95], v[132:135], v[180:183], v[92:95]
	v_mfma_f32_16x16x32_bf16 v[88:91], v[140:143], v[180:183], v[88:91]
	v_mfma_f32_16x16x32_bf16 v[76:79], v[132:135], v[204:207], v[76:79]
	v_mfma_f32_16x16x32_bf16 v[72:75], v[140:143], v[204:207], v[72:75]
	s_setprio 0
	s_setprio 1
	v_mfma_f32_16x16x32_bf16 v[116:119], v[144:147], v[160:163], v[116:119]
	v_mfma_f32_16x16x32_bf16 v[112:115], v[152:155], v[160:163], v[112:115]
	v_mfma_f32_16x16x32_bf16 v[100:103], v[144:147], v[168:171], v[100:103]
	v_mfma_f32_16x16x32_bf16 v[96:99], v[152:155], v[168:171], v[96:99]
	v_mfma_f32_16x16x32_bf16 v[84:87], v[144:147], v[176:179], v[84:87]
	v_mfma_f32_16x16x32_bf16 v[80:83], v[152:155], v[176:179], v[80:83]
	v_mfma_f32_16x16x32_bf16 v[68:71], v[144:147], v[200:203], v[68:71]
	v_mfma_f32_16x16x32_bf16 v[64:67], v[152:155], v[200:203], v[64:67]
	v_mfma_f32_16x16x32_bf16 v[116:119], v[148:151], v[164:167], v[116:119]
	v_mfma_f32_16x16x32_bf16 v[112:115], v[156:159], v[164:167], v[112:115]
	v_mfma_f32_16x16x32_bf16 v[100:103], v[148:151], v[172:175], v[100:103]
	v_mfma_f32_16x16x32_bf16 v[96:99], v[156:159], v[172:175], v[96:99]
	s_setprio 2
	s_barrier
	v_mfma_f32_16x16x32_bf16 v[84:87], v[148:151], v[180:183], v[84:87]
	v_mfma_f32_16x16x32_bf16 v[80:83], v[156:159], v[180:183], v[80:83]
	v_mfma_f32_16x16x32_bf16 v[68:71], v[148:151], v[204:207], v[68:71]
	v_mfma_f32_16x16x32_bf16 v[64:67], v[156:159], v[204:207], v[64:67]
	s_setprio 2
	s_add_i32 s67, s62, s49
	v_lshl_add_u64 v[208:209], s[40:41], 0, v[186:187]
	s_mov_b32 m0, s67
	ds_read_b128 v[160:163], v235 offset:16384
	ds_read_b128 v[164:167], v235 offset:17408
	ds_read_b128 v[168:171], v235 offset:18432
	ds_read_b128 v[172:175], v235 offset:19456
	ds_read_b128 v[176:179], v235 offset:20480
	ds_read_b128 v[180:183], v235 offset:21504
	ds_read_b128 v[200:203], v235 offset:22528
	ds_read_b128 v[204:207], v235 offset:23552
	global_load_lds_dwordx4 v[208:209], off
	s_add_i32 m0, s67, 0x2000
	s_add_u32 s68, s40, 0x40000
	v_lshl_add_u64 v[210:211], s[40:41], 0, v[190:191]
	s_addc_u32 s69, s41, 0
	s_add_i32 s67, s63, s49
	global_load_lds_dwordx4 v[210:211], off
	v_lshl_add_u64 v[212:213], s[68:69], 0, v[186:187]
	s_mov_b32 m0, s67
	v_lshl_add_u64 v[214:215], s[42:43], 0, v[188:189]
	global_load_lds_dwordx4 v[212:213], off
	s_add_i32 m0, s67, 0x2000
	v_lshl_add_u64 v[212:213], s[68:69], 0, v[190:191]
	global_load_lds_dwordx4 v[212:213], off
	s_mov_b32 m0, s50
	v_lshl_add_u64 v[212:213], s[42:43], 0, v[184:185]
	global_load_lds_dwordx4 v[212:213], off
	s_mov_b32 m0, s51
	s_nop 0
	global_load_lds_dwordx4 v[214:215], off
	s_waitcnt vmcnt(8) lgkmcnt(0)
	s_barrier
	s_setprio 1
	v_mfma_f32_16x16x32_bf16 v[60:63], v[120:123], v[160:163], v[60:63]
	v_mfma_f32_16x16x32_bf16 v[56:59], v[136:139], v[160:163], v[56:59]
	v_mfma_f32_16x16x32_bf16 v[44:47], v[120:123], v[168:171], v[44:47]
	v_mfma_f32_16x16x32_bf16 v[40:43], v[136:139], v[168:171], v[40:43]
	v_mfma_f32_16x16x32_bf16 v[28:31], v[120:123], v[176:179], v[28:31]
	v_mfma_f32_16x16x32_bf16 v[24:27], v[136:139], v[176:179], v[24:27]
	v_mfma_f32_16x16x32_bf16 v[12:15], v[120:123], v[200:203], v[12:15]
	v_mfma_f32_16x16x32_bf16 v[8:11], v[136:139], v[200:203], v[8:11]
	v_mfma_f32_16x16x32_bf16 v[60:63], v[132:135], v[164:167], v[60:63]
	v_mfma_f32_16x16x32_bf16 v[56:59], v[140:143], v[164:167], v[56:59]
	v_mfma_f32_16x16x32_bf16 v[44:47], v[132:135], v[172:175], v[44:47]
	v_mfma_f32_16x16x32_bf16 v[40:43], v[140:143], v[172:175], v[40:43]
	v_mfma_f32_16x16x32_bf16 v[28:31], v[132:135], v[180:183], v[28:31]
	v_mfma_f32_16x16x32_bf16 v[24:27], v[140:143], v[180:183], v[24:27]
	v_mfma_f32_16x16x32_bf16 v[12:15], v[132:135], v[204:207], v[12:15]
	v_mfma_f32_16x16x32_bf16 v[8:11], v[140:143], v[204:207], v[8:11]
	s_setprio 0
	s_setprio 1
	v_mfma_f32_16x16x32_bf16 v[52:55], v[144:147], v[160:163], v[52:55]
	v_mfma_f32_16x16x32_bf16 v[48:51], v[152:155], v[160:163], v[48:51]
	v_mfma_f32_16x16x32_bf16 v[36:39], v[144:147], v[168:171], v[36:39]
	v_mfma_f32_16x16x32_bf16 v[32:35], v[152:155], v[168:171], v[32:35]
	v_mfma_f32_16x16x32_bf16 v[20:23], v[144:147], v[176:179], v[20:23]
	v_mfma_f32_16x16x32_bf16 v[16:19], v[152:155], v[176:179], v[16:19]
	v_mfma_f32_16x16x32_bf16 v[4:7], v[144:147], v[200:203], v[4:7]
	v_mfma_f32_16x16x32_bf16 v[0:3], v[152:155], v[200:203], v[0:3]
	v_mfma_f32_16x16x32_bf16 v[52:55], v[148:151], v[164:167], v[52:55]
	v_mfma_f32_16x16x32_bf16 v[48:51], v[156:159], v[164:167], v[48:51]
	v_mfma_f32_16x16x32_bf16 v[36:39], v[148:151], v[172:175], v[36:39]
	v_mfma_f32_16x16x32_bf16 v[32:35], v[156:159], v[172:175], v[32:35]
	s_setprio 2
	s_barrier
	v_mfma_f32_16x16x32_bf16 v[20:23], v[148:151], v[180:183], v[20:23]
	v_mfma_f32_16x16x32_bf16 v[16:19], v[156:159], v[180:183], v[16:19]
	v_mfma_f32_16x16x32_bf16 v[4:7], v[148:151], v[204:207], v[4:7]
	v_mfma_f32_16x16x32_bf16 v[0:3], v[156:159], v[204:207], v[0:3]
	s_setprio 0
	s_add_i32 s67, 0, 0x18000
	s_add_i32 s68, 0, 0x1c000
	v_add_u32_e32 v140, s67, v232
	v_add_u32_e32 v156, s68, v232
	ds_read_b128 v[120:123], v140
	ds_read_b128 v[132:135], v140 offset:1024
	ds_read_b128 v[136:139], v140 offset:2048
	ds_read_b128 v[140:143], v140 offset:3072
	ds_read_b128 v[144:147], v156
	ds_read_b128 v[148:151], v156 offset:1024
	ds_read_b128 v[152:155], v156 offset:2048
	ds_read_b128 v[156:159], v156 offset:3072
	s_add_u32 s42, s42, 0x40000
	s_addc_u32 s43, s43, 0
	s_mov_b32 m0, s54
	v_lshl_add_u64 v[216:217], s[42:43], 0, v[184:185]
	ds_read_b128 v[160:163], v235 offset:32768
	ds_read_b128 v[164:167], v235 offset:33792
	ds_read_b128 v[168:171], v235 offset:34816
	ds_read_b128 v[172:175], v235 offset:35840
	ds_read_b128 v[176:179], v235 offset:36864
	ds_read_b128 v[180:183], v235 offset:37888
	ds_read_b128 v[200:203], v235 offset:38912
	ds_read_b128 v[204:207], v235 offset:39936
	global_load_lds_dwordx4 v[216:217], off
	s_mov_b32 m0, s55
	v_lshl_add_u64 v[216:217], s[42:43], 0, v[188:189]
	global_load_lds_dwordx4 v[216:217], off
	s_waitcnt vmcnt(8) lgkmcnt(0)
	s_barrier
	s_setprio 1
	v_mfma_f32_16x16x32_bf16 v[128:131], v[120:123], v[160:163], v[128:131]
	v_mfma_f32_16x16x32_bf16 v[124:127], v[136:139], v[160:163], v[124:127]
	v_mfma_f32_16x16x32_bf16 v[108:111], v[120:123], v[168:171], v[108:111]
	v_mfma_f32_16x16x32_bf16 v[104:107], v[136:139], v[168:171], v[104:107]
	v_mfma_f32_16x16x32_bf16 v[92:95], v[120:123], v[176:179], v[92:95]
	v_mfma_f32_16x16x32_bf16 v[88:91], v[136:139], v[176:179], v[88:91]
	v_mfma_f32_16x16x32_bf16 v[76:79], v[120:123], v[200:203], v[76:79]
	v_mfma_f32_16x16x32_bf16 v[72:75], v[136:139], v[200:203], v[72:75]
	v_mfma_f32_16x16x32_bf16 v[128:131], v[132:135], v[164:167], v[128:131]
	v_mfma_f32_16x16x32_bf16 v[124:127], v[140:143], v[164:167], v[124:127]
	v_mfma_f32_16x16x32_bf16 v[108:111], v[132:135], v[172:175], v[108:111]
	v_mfma_f32_16x16x32_bf16 v[104:107], v[140:143], v[172:175], v[104:107]
	v_mfma_f32_16x16x32_bf16 v[92:95], v[132:135], v[180:183], v[92:95]
	v_mfma_f32_16x16x32_bf16 v[88:91], v[140:143], v[180:183], v[88:91]
	v_mfma_f32_16x16x32_bf16 v[76:79], v[132:135], v[204:207], v[76:79]
	v_mfma_f32_16x16x32_bf16 v[72:75], v[140:143], v[204:207], v[72:75]
	s_setprio 0
	s_setprio 1
	v_mfma_f32_16x16x32_bf16 v[116:119], v[144:147], v[160:163], v[116:119]
	v_mfma_f32_16x16x32_bf16 v[112:115], v[152:155], v[160:163], v[112:115]
	v_mfma_f32_16x16x32_bf16 v[100:103], v[144:147], v[168:171], v[100:103]
	v_mfma_f32_16x16x32_bf16 v[96:99], v[152:155], v[168:171], v[96:99]
	v_mfma_f32_16x16x32_bf16 v[84:87], v[144:147], v[176:179], v[84:87]
	v_mfma_f32_16x16x32_bf16 v[80:83], v[152:155], v[176:179], v[80:83]
	v_mfma_f32_16x16x32_bf16 v[68:71], v[144:147], v[200:203], v[68:71]
	v_mfma_f32_16x16x32_bf16 v[64:67], v[152:155], v[200:203], v[64:67]
	v_mfma_f32_16x16x32_bf16 v[116:119], v[148:151], v[164:167], v[116:119]
	v_mfma_f32_16x16x32_bf16 v[112:115], v[156:159], v[164:167], v[112:115]
	v_mfma_f32_16x16x32_bf16 v[100:103], v[148:151], v[172:175], v[100:103]
	v_mfma_f32_16x16x32_bf16 v[96:99], v[156:159], v[172:175], v[96:99]
	s_setprio 2
	s_barrier
	v_mfma_f32_16x16x32_bf16 v[84:87], v[148:151], v[180:183], v[84:87]
	v_mfma_f32_16x16x32_bf16 v[80:83], v[156:159], v[180:183], v[80:83]
	v_mfma_f32_16x16x32_bf16 v[68:71], v[148:151], v[204:207], v[68:71]
	v_mfma_f32_16x16x32_bf16 v[64:67], v[156:159], v[204:207], v[64:67]
	s_setprio 2
	s_add_i32 s42, s67, s49
	v_lshl_add_u64 v[208:209], v[208:209], 0, s[18:19]
	s_mov_b32 m0, s42
	ds_read_b128 v[160:163], v235 offset:49152
	ds_read_b128 v[164:167], v235 offset:50176
	ds_read_b128 v[168:171], v235 offset:51200
	ds_read_b128 v[172:175], v235 offset:52224
	ds_read_b128 v[176:179], v235 offset:53248
	ds_read_b128 v[180:183], v235 offset:54272
	ds_read_b128 v[200:203], v235 offset:55296
	ds_read_b128 v[204:207], v235 offset:56320
	global_load_lds_dwordx4 v[208:209], off
	s_add_i32 m0, s42, 0x2000
	s_add_u32 s40, s40, 0x40080
	v_lshl_add_u64 v[208:209], v[210:211], 0, s[18:19]
	s_addc_u32 s41, s41, 0
	s_add_i32 s42, s68, s49
	global_load_lds_dwordx4 v[208:209], off
	s_mov_b32 m0, s42
	v_lshl_add_u64 v[208:209], s[40:41], 0, v[186:187]
	global_load_lds_dwordx4 v[208:209], off
	s_add_i32 m0, s42, 0x2000
	v_lshl_add_u64 v[208:209], s[40:41], 0, v[190:191]
	global_load_lds_dwordx4 v[208:209], off
	s_mov_b32 m0, s57
	v_lshl_add_u64 v[208:209], v[212:213], 0, s[18:19]
	global_load_lds_dwordx4 v[208:209], off
	s_mov_b32 m0, s58
	v_lshl_add_u64 v[208:209], v[214:215], 0, s[18:19]
	global_load_lds_dwordx4 v[208:209], off
	s_waitcnt vmcnt(8) lgkmcnt(0)
	s_barrier
	s_setprio 1
	v_mfma_f32_16x16x32_bf16 v[60:63], v[120:123], v[160:163], v[60:63]
	v_mfma_f32_16x16x32_bf16 v[56:59], v[136:139], v[160:163], v[56:59]
	v_mfma_f32_16x16x32_bf16 v[44:47], v[120:123], v[168:171], v[44:47]
	v_mfma_f32_16x16x32_bf16 v[40:43], v[136:139], v[168:171], v[40:43]
	v_mfma_f32_16x16x32_bf16 v[28:31], v[120:123], v[176:179], v[28:31]
	v_mfma_f32_16x16x32_bf16 v[24:27], v[136:139], v[176:179], v[24:27]
	v_mfma_f32_16x16x32_bf16 v[12:15], v[120:123], v[200:203], v[12:15]
	v_mfma_f32_16x16x32_bf16 v[8:11], v[136:139], v[200:203], v[8:11]
	v_mfma_f32_16x16x32_bf16 v[60:63], v[132:135], v[164:167], v[60:63]
	v_mfma_f32_16x16x32_bf16 v[56:59], v[140:143], v[164:167], v[56:59]
	v_mfma_f32_16x16x32_bf16 v[44:47], v[132:135], v[172:175], v[44:47]
	v_mfma_f32_16x16x32_bf16 v[40:43], v[140:143], v[172:175], v[40:43]
	v_mfma_f32_16x16x32_bf16 v[28:31], v[132:135], v[180:183], v[28:31]
	v_mfma_f32_16x16x32_bf16 v[24:27], v[140:143], v[180:183], v[24:27]
	v_mfma_f32_16x16x32_bf16 v[12:15], v[132:135], v[204:207], v[12:15]
	v_mfma_f32_16x16x32_bf16 v[8:11], v[140:143], v[204:207], v[8:11]
	s_setprio 0
	s_setprio 1
	v_mfma_f32_16x16x32_bf16 v[52:55], v[144:147], v[160:163], v[52:55]
	v_mfma_f32_16x16x32_bf16 v[48:51], v[152:155], v[160:163], v[48:51]
	v_mfma_f32_16x16x32_bf16 v[36:39], v[144:147], v[168:171], v[36:39]
	v_mfma_f32_16x16x32_bf16 v[32:35], v[152:155], v[168:171], v[32:35]
	v_mfma_f32_16x16x32_bf16 v[20:23], v[144:147], v[176:179], v[20:23]
	v_mfma_f32_16x16x32_bf16 v[16:19], v[152:155], v[176:179], v[16:19]
	v_mfma_f32_16x16x32_bf16 v[4:7], v[144:147], v[200:203], v[4:7]
	v_mfma_f32_16x16x32_bf16 v[0:3], v[152:155], v[200:203], v[0:3]
	v_mfma_f32_16x16x32_bf16 v[52:55], v[148:151], v[164:167], v[52:55]
	v_mfma_f32_16x16x32_bf16 v[48:51], v[156:159], v[164:167], v[48:51]
	v_mfma_f32_16x16x32_bf16 v[36:39], v[148:151], v[172:175], v[36:39]
	v_mfma_f32_16x16x32_bf16 v[32:35], v[156:159], v[172:175], v[32:35]
	s_setprio 2
	s_barrier
	v_mfma_f32_16x16x32_bf16 v[20:23], v[148:151], v[180:183], v[20:23]
	v_mfma_f32_16x16x32_bf16 v[16:19], v[156:159], v[180:183], v[16:19]
	v_mfma_f32_16x16x32_bf16 v[4:7], v[148:151], v[204:207], v[4:7]
	v_mfma_f32_16x16x32_bf16 v[0:3], v[156:159], v[204:207], v[0:3]
	s_setprio 0
	s_add_i32 s66, s66, 2
	s_add_u32 s38, s38, 0x100
	s_addc_u32 s39, s39, 0
	s_add_u32 s64, s64, 0x100
	s_addc_u32 s65, s65, 0
	s_cmp_gt_u32 s66, 13
	s_cbranch_scc0 .LBB0_1146

.LBB0_1309:
	s_add_u32 s51, s26, 0x100
	s_addc_u32 s52, s27, 0
	s_mov_b32 s53, -2
	ds_read_b128 v[128:131], v197
	ds_read_b128 v[132:135], v197 offset:1024
	ds_read_b128 v[136:139], v197 offset:2048
	ds_read_b128 v[140:143], v197 offset:3072
	ds_read_b128 v[144:147], v198
	ds_read_b128 v[148:151], v198 offset:1024
	ds_read_b128 v[152:155], v198 offset:2048
	ds_read_b128 v[156:159], v198 offset:3072
	s_add_u32 s4, s24, 0x100
	s_addc_u32 s5, s25, 0
	s_cmp_eq_u32 s53, 40
	s_cselect_b32 s29, s21, s5
	s_cselect_b32 s28, s20, s4
	s_cselect_b32 s27, s23, s52
	s_cselect_b32 s26, s22, s51
	v_lshl_add_u64 v[212:213], s[24:25], 0, v[172:173]
	s_add_i32 m0, s36, 0xc000
	ds_read_b128 v[160:163], v199
	ds_read_b128 v[180:183], v199 offset:1024
	ds_read_b128 v[184:187], v199 offset:2048
	ds_read_b128 v[188:191], v199 offset:3072
	ds_read_b128 v[192:195], v199 offset:4096
	ds_read_b128 v[200:203], v199 offset:5120
	ds_read_b128 v[204:207], v199 offset:6144
	ds_read_b128 v[208:211], v199 offset:7168
	global_load_lds_dwordx4 v[212:213], off
	s_add_i32 m0, s36, 0xe000
	v_lshl_add_u64 v[212:213], s[24:25], 0, v[174:175]
	global_load_lds_dwordx4 v[212:213], off
	s_waitcnt vmcnt(8) lgkmcnt(0)
	s_barrier
	s_setprio 1
	v_mfma_f32_16x16x32_bf16 v[124:127], v[128:131], v[160:163], 0
	v_mfma_f32_16x16x32_bf16 v[120:123], v[136:139], v[160:163], 0
	v_mfma_f32_16x16x32_bf16 v[116:119], v[128:131], v[184:187], 0
	v_mfma_f32_16x16x32_bf16 v[108:111], v[136:139], v[184:187], 0
	v_mfma_f32_16x16x32_bf16 v[88:91], v[128:131], v[192:195], 0
	v_mfma_f32_16x16x32_bf16 v[100:103], v[136:139], v[192:195], 0
	v_mfma_f32_16x16x32_bf16 v[72:75], v[128:131], v[204:207], 0
	v_mfma_f32_16x16x32_bf16 v[76:79], v[136:139], v[204:207], 0
	v_mfma_f32_16x16x32_bf16 v[124:127], v[132:135], v[180:183], v[124:127]
	v_mfma_f32_16x16x32_bf16 v[120:123], v[140:143], v[180:183], v[120:123]
	v_mfma_f32_16x16x32_bf16 v[116:119], v[132:135], v[188:191], v[116:119]
	v_mfma_f32_16x16x32_bf16 v[108:111], v[140:143], v[188:191], v[108:111]
	v_mfma_f32_16x16x32_bf16 v[88:91], v[132:135], v[200:203], v[88:91]
	v_mfma_f32_16x16x32_bf16 v[100:103], v[140:143], v[200:203], v[100:103]
	v_mfma_f32_16x16x32_bf16 v[72:75], v[132:135], v[208:211], v[72:75]
	v_mfma_f32_16x16x32_bf16 v[76:79], v[140:143], v[208:211], v[76:79]
	s_setprio 0
	s_setprio 1
	v_mfma_f32_16x16x32_bf16 v[112:115], v[144:147], v[160:163], 0
	v_mfma_f32_16x16x32_bf16 v[104:107], v[152:155], v[160:163], 0
	v_mfma_f32_16x16x32_bf16 v[96:99], v[144:147], v[184:187], 0
	v_mfma_f32_16x16x32_bf16 v[92:95], v[152:155], v[184:187], 0
	v_mfma_f32_16x16x32_bf16 v[80:83], v[144:147], v[192:195], 0
	v_mfma_f32_16x16x32_bf16 v[84:87], v[152:155], v[192:195], 0
	v_mfma_f32_16x16x32_bf16 v[64:67], v[144:147], v[204:207], 0
	v_mfma_f32_16x16x32_bf16 v[68:71], v[152:155], v[204:207], 0
	v_mfma_f32_16x16x32_bf16 v[112:115], v[148:151], v[180:183], v[112:115]
	v_mfma_f32_16x16x32_bf16 v[104:107], v[156:159], v[180:183], v[104:107]
	v_mfma_f32_16x16x32_bf16 v[96:99], v[148:151], v[188:191], v[96:99]
	v_mfma_f32_16x16x32_bf16 v[92:95], v[156:159], v[188:191], v[92:95]
	s_setprio 2
	s_barrier
	v_mfma_f32_16x16x32_bf16 v[80:83], v[148:151], v[200:203], v[80:83]
	v_mfma_f32_16x16x32_bf16 v[84:87], v[156:159], v[200:203], v[84:87]
	v_mfma_f32_16x16x32_bf16 v[64:67], v[148:151], v[208:211], v[64:67]
	v_mfma_f32_16x16x32_bf16 v[68:71], v[156:159], v[208:211], v[68:71]
	s_setprio 2
	s_add_i32 s24, s45, s35
	v_lshl_add_u64 v[212:213], s[26:27], 0, v[166:167]
	s_mov_b32 m0, s24
	ds_read_b128 v[160:163], v199 offset:16384
	ds_read_b128 v[180:183], v199 offset:17408
	ds_read_b128 v[184:187], v199 offset:18432
	ds_read_b128 v[188:191], v199 offset:19456
	ds_read_b128 v[192:195], v199 offset:20480
	ds_read_b128 v[200:203], v199 offset:21504
	ds_read_b128 v[204:207], v199 offset:22528
	ds_read_b128 v[208:211], v199 offset:23552
	global_load_lds_dwordx4 v[212:213], off
	s_add_i32 m0, s24, 0x2000
	s_add_u32 s24, s26, 0xb0000
	v_lshl_add_u64 v[214:215], s[26:27], 0, v[170:171]
	s_addc_u32 s25, s27, 0
	s_add_i32 s54, s46, s35
	global_load_lds_dwordx4 v[214:215], off
	v_lshl_add_u64 v[216:217], s[24:25], 0, v[166:167]
	s_mov_b32 m0, s54
	v_lshl_add_u64 v[218:219], s[28:29], 0, v[168:169]
	global_load_lds_dwordx4 v[216:217], off
	s_add_i32 m0, s54, 0x2000
	v_lshl_add_u64 v[216:217], s[24:25], 0, v[170:171]
	global_load_lds_dwordx4 v[216:217], off
	s_mov_b32 m0, s36
	v_lshl_add_u64 v[216:217], s[28:29], 0, v[164:165]
	global_load_lds_dwordx4 v[216:217], off
	s_mov_b32 m0, s37
	s_nop 0
	global_load_lds_dwordx4 v[218:219], off
	s_waitcnt vmcnt(8) lgkmcnt(0)
	s_barrier
	s_setprio 1
	v_mfma_f32_16x16x32_bf16 v[56:59], v[128:131], v[160:163], 0
	v_mfma_f32_16x16x32_bf16 v[60:63], v[136:139], v[160:163], 0
	v_mfma_f32_16x16x32_bf16 v[40:43], v[128:131], v[184:187], 0
	v_mfma_f32_16x16x32_bf16 v[44:47], v[136:139], v[184:187], 0
	v_mfma_f32_16x16x32_bf16 v[24:27], v[128:131], v[192:195], 0
	v_mfma_f32_16x16x32_bf16 v[28:31], v[136:139], v[192:195], 0
	v_mfma_f32_16x16x32_bf16 v[8:11], v[128:131], v[204:207], 0
	v_mfma_f32_16x16x32_bf16 v[12:15], v[136:139], v[204:207], 0
	v_mfma_f32_16x16x32_bf16 v[56:59], v[132:135], v[180:183], v[56:59]
	v_mfma_f32_16x16x32_bf16 v[60:63], v[140:143], v[180:183], v[60:63]
	v_mfma_f32_16x16x32_bf16 v[40:43], v[132:135], v[188:191], v[40:43]
	v_mfma_f32_16x16x32_bf16 v[44:47], v[140:143], v[188:191], v[44:47]
	v_mfma_f32_16x16x32_bf16 v[24:27], v[132:135], v[200:203], v[24:27]
	v_mfma_f32_16x16x32_bf16 v[28:31], v[140:143], v[200:203], v[28:31]
	v_mfma_f32_16x16x32_bf16 v[8:11], v[132:135], v[208:211], v[8:11]
	v_mfma_f32_16x16x32_bf16 v[12:15], v[140:143], v[208:211], v[12:15]
	s_setprio 0
	s_setprio 1
	v_mfma_f32_16x16x32_bf16 v[48:51], v[144:147], v[160:163], 0
	v_mfma_f32_16x16x32_bf16 v[52:55], v[152:155], v[160:163], 0
	v_mfma_f32_16x16x32_bf16 v[32:35], v[144:147], v[184:187], 0
	v_mfma_f32_16x16x32_bf16 v[36:39], v[152:155], v[184:187], 0
	v_mfma_f32_16x16x32_bf16 v[16:19], v[144:147], v[192:195], 0
	v_mfma_f32_16x16x32_bf16 v[20:23], v[152:155], v[192:195], 0
	v_mfma_f32_16x16x32_bf16 v[0:3], v[144:147], v[204:207], 0
	v_mfma_f32_16x16x32_bf16 v[4:7], v[152:155], v[204:207], 0
	v_mfma_f32_16x16x32_bf16 v[48:51], v[148:151], v[180:183], v[48:51]
	v_mfma_f32_16x16x32_bf16 v[52:55], v[156:159], v[180:183], v[52:55]
	v_mfma_f32_16x16x32_bf16 v[32:35], v[148:151], v[188:191], v[32:35]
	v_mfma_f32_16x16x32_bf16 v[36:39], v[156:159], v[188:191], v[36:39]
	s_setprio 2
	s_barrier
	v_mfma_f32_16x16x32_bf16 v[16:19], v[148:151], v[200:203], v[16:19]
	v_mfma_f32_16x16x32_bf16 v[20:23], v[156:159], v[200:203], v[20:23]
	v_mfma_f32_16x16x32_bf16 v[0:3], v[148:151], v[208:211], v[0:3]
	v_mfma_f32_16x16x32_bf16 v[4:7], v[156:159], v[208:211], v[4:7]
	s_setprio 0
	s_add_i32 s54, 0, 0x18000
	s_add_i32 s55, 0, 0x1c000
	v_add_u32_e32 v140, s54, v196
	v_add_u32_e32 v156, s55, v196
	ds_read_b128 v[128:131], v140
	ds_read_b128 v[132:135], v140 offset:1024
	ds_read_b128 v[136:139], v140 offset:2048
	ds_read_b128 v[140:143], v140 offset:3072
	ds_read_b128 v[144:147], v156
	ds_read_b128 v[148:151], v156 offset:1024
	ds_read_b128 v[152:155], v156 offset:2048
	ds_read_b128 v[156:159], v156 offset:3072
	s_add_u32 s24, s28, 0xb0000
	s_addc_u32 s25, s29, 0
	s_mov_b32 m0, s38
	v_lshl_add_u64 v[220:221], s[24:25], 0, v[164:165]
	ds_read_b128 v[160:163], v199 offset:32768
	ds_read_b128 v[180:183], v199 offset:33792
	ds_read_b128 v[184:187], v199 offset:34816
	ds_read_b128 v[188:191], v199 offset:35840
	ds_read_b128 v[192:195], v199 offset:36864
	ds_read_b128 v[200:203], v199 offset:37888
	ds_read_b128 v[204:207], v199 offset:38912
	ds_read_b128 v[208:211], v199 offset:39936
	global_load_lds_dwordx4 v[220:221], off
	s_mov_b32 m0, s39
	v_lshl_add_u64 v[220:221], s[24:25], 0, v[168:169]
	global_load_lds_dwordx4 v[220:221], off
	s_waitcnt vmcnt(8) lgkmcnt(0)
	s_barrier
	s_setprio 1
	v_mfma_f32_16x16x32_bf16 v[124:127], v[128:131], v[160:163], v[124:127]
	v_mfma_f32_16x16x32_bf16 v[120:123], v[136:139], v[160:163], v[120:123]
	v_mfma_f32_16x16x32_bf16 v[116:119], v[128:131], v[184:187], v[116:119]
	v_mfma_f32_16x16x32_bf16 v[108:111], v[136:139], v[184:187], v[108:111]
	v_mfma_f32_16x16x32_bf16 v[88:91], v[128:131], v[192:195], v[88:91]
	v_mfma_f32_16x16x32_bf16 v[100:103], v[136:139], v[192:195], v[100:103]
	v_mfma_f32_16x16x32_bf16 v[72:75], v[128:131], v[204:207], v[72:75]
	v_mfma_f32_16x16x32_bf16 v[76:79], v[136:139], v[204:207], v[76:79]
	v_mfma_f32_16x16x32_bf16 v[124:127], v[132:135], v[180:183], v[124:127]
	v_mfma_f32_16x16x32_bf16 v[120:123], v[140:143], v[180:183], v[120:123]
	v_mfma_f32_16x16x32_bf16 v[116:119], v[132:135], v[188:191], v[116:119]
	v_mfma_f32_16x16x32_bf16 v[108:111], v[140:143], v[188:191], v[108:111]
	v_mfma_f32_16x16x32_bf16 v[88:91], v[132:135], v[200:203], v[88:91]
	v_mfma_f32_16x16x32_bf16 v[100:103], v[140:143], v[200:203], v[100:103]
	v_mfma_f32_16x16x32_bf16 v[72:75], v[132:135], v[208:211], v[72:75]
	v_mfma_f32_16x16x32_bf16 v[76:79], v[140:143], v[208:211], v[76:79]
	s_setprio 0
	s_setprio 1
	v_mfma_f32_16x16x32_bf16 v[112:115], v[144:147], v[160:163], v[112:115]
	v_mfma_f32_16x16x32_bf16 v[104:107], v[152:155], v[160:163], v[104:107]
	v_mfma_f32_16x16x32_bf16 v[96:99], v[144:147], v[184:187], v[96:99]
	v_mfma_f32_16x16x32_bf16 v[92:95], v[152:155], v[184:187], v[92:95]
	v_mfma_f32_16x16x32_bf16 v[80:83], v[144:147], v[192:195], v[80:83]
	v_mfma_f32_16x16x32_bf16 v[84:87], v[152:155], v[192:195], v[84:87]
	v_mfma_f32_16x16x32_bf16 v[64:67], v[144:147], v[204:207], v[64:67]
	v_mfma_f32_16x16x32_bf16 v[68:71], v[152:155], v[204:207], v[68:71]
	v_mfma_f32_16x16x32_bf16 v[112:115], v[148:151], v[180:183], v[112:115]
	v_mfma_f32_16x16x32_bf16 v[104:107], v[156:159], v[180:183], v[104:107]
	v_mfma_f32_16x16x32_bf16 v[96:99], v[148:151], v[188:191], v[96:99]
	v_mfma_f32_16x16x32_bf16 v[92:95], v[156:159], v[188:191], v[92:95]
	s_setprio 2
	s_barrier
	v_mfma_f32_16x16x32_bf16 v[80:83], v[148:151], v[200:203], v[80:83]
	v_mfma_f32_16x16x32_bf16 v[84:87], v[156:159], v[200:203], v[84:87]
	v_mfma_f32_16x16x32_bf16 v[64:67], v[148:151], v[208:211], v[64:67]
	v_mfma_f32_16x16x32_bf16 v[68:71], v[156:159], v[208:211], v[68:71]
	s_setprio 2
	s_add_i32 s24, s54, s35
	v_lshl_add_u64 v[212:213], v[212:213], 0, s[16:17]
	s_mov_b32 m0, s24
	ds_read_b128 v[160:163], v199 offset:49152
	ds_read_b128 v[180:183], v199 offset:50176
	ds_read_b128 v[184:187], v199 offset:51200
	ds_read_b128 v[188:191], v199 offset:52224
	ds_read_b128 v[192:195], v199 offset:53248
	ds_read_b128 v[200:203], v199 offset:54272
	ds_read_b128 v[204:207], v199 offset:55296
	ds_read_b128 v[208:211], v199 offset:56320
	global_load_lds_dwordx4 v[212:213], off
	s_add_i32 m0, s24, 0x2000
	s_add_u32 s24, s26, 0xb0080
	v_lshl_add_u64 v[212:213], v[214:215], 0, s[16:17]
	s_addc_u32 s25, s27, 0
	s_add_i32 s26, s55, s35
	global_load_lds_dwordx4 v[212:213], off
	s_mov_b32 m0, s26
	v_lshl_add_u64 v[212:213], s[24:25], 0, v[166:167]
	global_load_lds_dwordx4 v[212:213], off
	s_add_i32 m0, s26, 0x2000
	v_lshl_add_u64 v[212:213], s[24:25], 0, v[170:171]
	global_load_lds_dwordx4 v[212:213], off
	s_mov_b32 m0, s41
	v_lshl_add_u64 v[212:213], v[216:217], 0, s[16:17]
	global_load_lds_dwordx4 v[212:213], off
	s_mov_b32 m0, s42
	v_lshl_add_u64 v[212:213], v[218:219], 0, s[16:17]
	global_load_lds_dwordx4 v[212:213], off
	s_waitcnt vmcnt(8) lgkmcnt(0)
	s_barrier
	s_setprio 1
	v_mfma_f32_16x16x32_bf16 v[56:59], v[128:131], v[160:163], v[56:59]
	v_mfma_f32_16x16x32_bf16 v[60:63], v[136:139], v[160:163], v[60:63]
	v_mfma_f32_16x16x32_bf16 v[40:43], v[128:131], v[184:187], v[40:43]
	v_mfma_f32_16x16x32_bf16 v[44:47], v[136:139], v[184:187], v[44:47]
	v_mfma_f32_16x16x32_bf16 v[24:27], v[128:131], v[192:195], v[24:27]
	v_mfma_f32_16x16x32_bf16 v[28:31], v[136:139], v[192:195], v[28:31]
	v_mfma_f32_16x16x32_bf16 v[8:11], v[128:131], v[204:207], v[8:11]
	v_mfma_f32_16x16x32_bf16 v[12:15], v[136:139], v[204:207], v[12:15]
	v_mfma_f32_16x16x32_bf16 v[56:59], v[132:135], v[180:183], v[56:59]
	v_mfma_f32_16x16x32_bf16 v[60:63], v[140:143], v[180:183], v[60:63]
	v_mfma_f32_16x16x32_bf16 v[40:43], v[132:135], v[188:191], v[40:43]
	v_mfma_f32_16x16x32_bf16 v[44:47], v[140:143], v[188:191], v[44:47]
	v_mfma_f32_16x16x32_bf16 v[24:27], v[132:135], v[200:203], v[24:27]
	v_mfma_f32_16x16x32_bf16 v[28:31], v[140:143], v[200:203], v[28:31]
	v_mfma_f32_16x16x32_bf16 v[8:11], v[132:135], v[208:211], v[8:11]
	v_mfma_f32_16x16x32_bf16 v[12:15], v[140:143], v[208:211], v[12:15]
	s_setprio 0
	s_setprio 1
	v_mfma_f32_16x16x32_bf16 v[48:51], v[144:147], v[160:163], v[48:51]
	v_mfma_f32_16x16x32_bf16 v[52:55], v[152:155], v[160:163], v[52:55]
	v_mfma_f32_16x16x32_bf16 v[32:35], v[144:147], v[184:187], v[32:35]
	v_mfma_f32_16x16x32_bf16 v[36:39], v[152:155], v[184:187], v[36:39]
	v_mfma_f32_16x16x32_bf16 v[16:19], v[144:147], v[192:195], v[16:19]
	v_mfma_f32_16x16x32_bf16 v[20:23], v[152:155], v[192:195], v[20:23]
	v_mfma_f32_16x16x32_bf16 v[0:3], v[144:147], v[204:207], v[0:3]
	v_mfma_f32_16x16x32_bf16 v[4:7], v[152:155], v[204:207], v[4:7]
	v_mfma_f32_16x16x32_bf16 v[48:51], v[148:151], v[180:183], v[48:51]
	v_mfma_f32_16x16x32_bf16 v[52:55], v[156:159], v[180:183], v[52:55]
	v_mfma_f32_16x16x32_bf16 v[32:35], v[148:151], v[188:191], v[32:35]
	v_mfma_f32_16x16x32_bf16 v[36:39], v[156:159], v[188:191], v[36:39]
	s_setprio 2
	s_barrier
	v_mfma_f32_16x16x32_bf16 v[16:19], v[148:151], v[200:203], v[16:19]
	v_mfma_f32_16x16x32_bf16 v[20:23], v[156:159], v[200:203], v[20:23]
	v_mfma_f32_16x16x32_bf16 v[0:3], v[148:151], v[208:211], v[0:3]
	v_mfma_f32_16x16x32_bf16 v[4:7], v[156:159], v[208:211], v[4:7]
	s_setprio 0
	s_add_i32 s53, s53, 2
	s_add_u32 s51, s51, 0x100
	s_addc_u32 s52, s52, 0
	s_cmp_gt_u32 s53, 41
	s_mov_b64 s[24:25], s[4:5]
.LBB0_1310:
	ds_read_b128 v[128:131], v197
	ds_read_b128 v[132:135], v197 offset:1024
	ds_read_b128 v[136:139], v197 offset:2048
	ds_read_b128 v[140:143], v197 offset:3072
	ds_read_b128 v[144:147], v198
	ds_read_b128 v[148:151], v198 offset:1024
	ds_read_b128 v[152:155], v198 offset:2048
	ds_read_b128 v[156:159], v198 offset:3072
	s_add_u32 s4, s24, 0x100
	s_addc_u32 s5, s25, 0
	s_cmp_eq_u32 s53, 40
	s_cselect_b32 s29, s21, s5
	s_cselect_b32 s28, s20, s4
	s_cselect_b32 s27, s23, s52
	s_cselect_b32 s26, s22, s51
	v_lshl_add_u64 v[212:213], s[24:25], 0, v[172:173]
	s_add_i32 m0, s36, 0xc000
	ds_read_b128 v[160:163], v199
	ds_read_b128 v[180:183], v199 offset:1024
	ds_read_b128 v[184:187], v199 offset:2048
	ds_read_b128 v[188:191], v199 offset:3072
	ds_read_b128 v[192:195], v199 offset:4096
	ds_read_b128 v[200:203], v199 offset:5120
	ds_read_b128 v[204:207], v199 offset:6144
	ds_read_b128 v[208:211], v199 offset:7168
	global_load_lds_dwordx4 v[212:213], off
	s_add_i32 m0, s36, 0xe000
	v_lshl_add_u64 v[212:213], s[24:25], 0, v[174:175]
	global_load_lds_dwordx4 v[212:213], off
	s_waitcnt vmcnt(8) lgkmcnt(0)
	s_barrier
	s_setprio 1
	v_mfma_f32_16x16x32_bf16 v[124:127], v[128:131], v[160:163], v[124:127]
	v_mfma_f32_16x16x32_bf16 v[120:123], v[136:139], v[160:163], v[120:123]
	v_mfma_f32_16x16x32_bf16 v[116:119], v[128:131], v[184:187], v[116:119]
	v_mfma_f32_16x16x32_bf16 v[108:111], v[136:139], v[184:187], v[108:111]
	v_mfma_f32_16x16x32_bf16 v[88:91], v[128:131], v[192:195], v[88:91]
	v_mfma_f32_16x16x32_bf16 v[100:103], v[136:139], v[192:195], v[100:103]
	v_mfma_f32_16x16x32_bf16 v[72:75], v[128:131], v[204:207], v[72:75]
	v_mfma_f32_16x16x32_bf16 v[76:79], v[136:139], v[204:207], v[76:79]
	v_mfma_f32_16x16x32_bf16 v[124:127], v[132:135], v[180:183], v[124:127]
	v_mfma_f32_16x16x32_bf16 v[120:123], v[140:143], v[180:183], v[120:123]
	v_mfma_f32_16x16x32_bf16 v[116:119], v[132:135], v[188:191], v[116:119]
	v_mfma_f32_16x16x32_bf16 v[108:111], v[140:143], v[188:191], v[108:111]
	v_mfma_f32_16x16x32_bf16 v[88:91], v[132:135], v[200:203], v[88:91]
	v_mfma_f32_16x16x32_bf16 v[100:103], v[140:143], v[200:203], v[100:103]
	v_mfma_f32_16x16x32_bf16 v[72:75], v[132:135], v[208:211], v[72:75]
	v_mfma_f32_16x16x32_bf16 v[76:79], v[140:143], v[208:211], v[76:79]
	s_setprio 0
	s_setprio 1
	v_mfma_f32_16x16x32_bf16 v[112:115], v[144:147], v[160:163], v[112:115]
	v_mfma_f32_16x16x32_bf16 v[104:107], v[152:155], v[160:163], v[104:107]
	v_mfma_f32_16x16x32_bf16 v[96:99], v[144:147], v[184:187], v[96:99]
	v_mfma_f32_16x16x32_bf16 v[92:95], v[152:155], v[184:187], v[92:95]
	v_mfma_f32_16x16x32_bf16 v[80:83], v[144:147], v[192:195], v[80:83]
	v_mfma_f32_16x16x32_bf16 v[84:87], v[152:155], v[192:195], v[84:87]
	v_mfma_f32_16x16x32_bf16 v[64:67], v[144:147], v[204:207], v[64:67]
	v_mfma_f32_16x16x32_bf16 v[68:71], v[152:155], v[204:207], v[68:71]
	v_mfma_f32_16x16x32_bf16 v[112:115], v[148:151], v[180:183], v[112:115]
	v_mfma_f32_16x16x32_bf16 v[104:107], v[156:159], v[180:183], v[104:107]
	v_mfma_f32_16x16x32_bf16 v[96:99], v[148:151], v[188:191], v[96:99]
	v_mfma_f32_16x16x32_bf16 v[92:95], v[156:159], v[188:191], v[92:95]
	s_setprio 2
	s_barrier
	v_mfma_f32_16x16x32_bf16 v[80:83], v[148:151], v[200:203], v[80:83]
	v_mfma_f32_16x16x32_bf16 v[84:87], v[156:159], v[200:203], v[84:87]
	v_mfma_f32_16x16x32_bf16 v[64:67], v[148:151], v[208:211], v[64:67]
	v_mfma_f32_16x16x32_bf16 v[68:71], v[156:159], v[208:211], v[68:71]
	s_setprio 2
	s_add_i32 s24, s45, s35
	v_lshl_add_u64 v[212:213], s[26:27], 0, v[166:167]
	s_mov_b32 m0, s24
	ds_read_b128 v[160:163], v199 offset:16384
	ds_read_b128 v[180:183], v199 offset:17408
	ds_read_b128 v[184:187], v199 offset:18432
	ds_read_b128 v[188:191], v199 offset:19456
	ds_read_b128 v[192:195], v199 offset:20480
	ds_read_b128 v[200:203], v199 offset:21504
	ds_read_b128 v[204:207], v199 offset:22528
	ds_read_b128 v[208:211], v199 offset:23552
	global_load_lds_dwordx4 v[212:213], off
	s_add_i32 m0, s24, 0x2000
	s_add_u32 s24, s26, 0xb0000
	v_lshl_add_u64 v[214:215], s[26:27], 0, v[170:171]
	s_addc_u32 s25, s27, 0
	s_add_i32 s54, s46, s35
	global_load_lds_dwordx4 v[214:215], off
	v_lshl_add_u64 v[216:217], s[24:25], 0, v[166:167]
	s_mov_b32 m0, s54
	v_lshl_add_u64 v[218:219], s[28:29], 0, v[168:169]
	global_load_lds_dwordx4 v[216:217], off
	s_add_i32 m0, s54, 0x2000
	v_lshl_add_u64 v[216:217], s[24:25], 0, v[170:171]
	global_load_lds_dwordx4 v[216:217], off
	s_mov_b32 m0, s36
	v_lshl_add_u64 v[216:217], s[28:29], 0, v[164:165]
	global_load_lds_dwordx4 v[216:217], off
	s_mov_b32 m0, s37
	s_nop 0
	global_load_lds_dwordx4 v[218:219], off
	s_waitcnt vmcnt(8) lgkmcnt(0)
	s_barrier
	s_setprio 1
	v_mfma_f32_16x16x32_bf16 v[56:59], v[128:131], v[160:163], v[56:59]
	v_mfma_f32_16x16x32_bf16 v[60:63], v[136:139], v[160:163], v[60:63]
	v_mfma_f32_16x16x32_bf16 v[40:43], v[128:131], v[184:187], v[40:43]
	v_mfma_f32_16x16x32_bf16 v[44:47], v[136:139], v[184:187], v[44:47]
	v_mfma_f32_16x16x32_bf16 v[24:27], v[128:131], v[192:195], v[24:27]
	v_mfma_f32_16x16x32_bf16 v[28:31], v[136:139], v[192:195], v[28:31]
	v_mfma_f32_16x16x32_bf16 v[8:11], v[128:131], v[204:207], v[8:11]
	v_mfma_f32_16x16x32_bf16 v[12:15], v[136:139], v[204:207], v[12:15]
	v_mfma_f32_16x16x32_bf16 v[56:59], v[132:135], v[180:183], v[56:59]
	v_mfma_f32_16x16x32_bf16 v[60:63], v[140:143], v[180:183], v[60:63]
	v_mfma_f32_16x16x32_bf16 v[40:43], v[132:135], v[188:191], v[40:43]
	v_mfma_f32_16x16x32_bf16 v[44:47], v[140:143], v[188:191], v[44:47]
	v_mfma_f32_16x16x32_bf16 v[24:27], v[132:135], v[200:203], v[24:27]
	v_mfma_f32_16x16x32_bf16 v[28:31], v[140:143], v[200:203], v[28:31]
	v_mfma_f32_16x16x32_bf16 v[8:11], v[132:135], v[208:211], v[8:11]
	v_mfma_f32_16x16x32_bf16 v[12:15], v[140:143], v[208:211], v[12:15]
	s_setprio 0
	s_setprio 1
	v_mfma_f32_16x16x32_bf16 v[48:51], v[144:147], v[160:163], v[48:51]
	v_mfma_f32_16x16x32_bf16 v[52:55], v[152:155], v[160:163], v[52:55]
	v_mfma_f32_16x16x32_bf16 v[32:35], v[144:147], v[184:187], v[32:35]
	v_mfma_f32_16x16x32_bf16 v[36:39], v[152:155], v[184:187], v[36:39]
	v_mfma_f32_16x16x32_bf16 v[16:19], v[144:147], v[192:195], v[16:19]
	v_mfma_f32_16x16x32_bf16 v[20:23], v[152:155], v[192:195], v[20:23]
	v_mfma_f32_16x16x32_bf16 v[0:3], v[144:147], v[204:207], v[0:3]
	v_mfma_f32_16x16x32_bf16 v[4:7], v[152:155], v[204:207], v[4:7]
	v_mfma_f32_16x16x32_bf16 v[48:51], v[148:151], v[180:183], v[48:51]
	v_mfma_f32_16x16x32_bf16 v[52:55], v[156:159], v[180:183], v[52:55]
	v_mfma_f32_16x16x32_bf16 v[32:35], v[148:151], v[188:191], v[32:35]
	v_mfma_f32_16x16x32_bf16 v[36:39], v[156:159], v[188:191], v[36:39]
	s_setprio 2
	s_barrier
	v_mfma_f32_16x16x32_bf16 v[16:19], v[148:151], v[200:203], v[16:19]
	v_mfma_f32_16x16x32_bf16 v[20:23], v[156:159], v[200:203], v[20:23]
	v_mfma_f32_16x16x32_bf16 v[0:3], v[148:151], v[208:211], v[0:3]
	v_mfma_f32_16x16x32_bf16 v[4:7], v[156:159], v[208:211], v[4:7]
	s_setprio 0
	s_add_i32 s54, 0, 0x18000
	s_add_i32 s55, 0, 0x1c000
	v_add_u32_e32 v140, s54, v196
	v_add_u32_e32 v156, s55, v196
	ds_read_b128 v[128:131], v140
	ds_read_b128 v[132:135], v140 offset:1024
	ds_read_b128 v[136:139], v140 offset:2048
	ds_read_b128 v[140:143], v140 offset:3072
	ds_read_b128 v[144:147], v156
	ds_read_b128 v[148:151], v156 offset:1024
	ds_read_b128 v[152:155], v156 offset:2048
	ds_read_b128 v[156:159], v156 offset:3072
	s_add_u32 s24, s28, 0xb0000
	s_addc_u32 s25, s29, 0
	s_mov_b32 m0, s38
	v_lshl_add_u64 v[220:221], s[24:25], 0, v[164:165]
	ds_read_b128 v[160:163], v199 offset:32768
	ds_read_b128 v[180:183], v199 offset:33792
	ds_read_b128 v[184:187], v199 offset:34816
	ds_read_b128 v[188:191], v199 offset:35840
	ds_read_b128 v[192:195], v199 offset:36864
	ds_read_b128 v[200:203], v199 offset:37888
	ds_read_b128 v[204:207], v199 offset:38912
	ds_read_b128 v[208:211], v199 offset:39936
	global_load_lds_dwordx4 v[220:221], off
	s_mov_b32 m0, s39
	v_lshl_add_u64 v[220:221], s[24:25], 0, v[168:169]
	global_load_lds_dwordx4 v[220:221], off
	s_waitcnt vmcnt(8) lgkmcnt(0)
	s_barrier
	s_setprio 1
	v_mfma_f32_16x16x32_bf16 v[124:127], v[128:131], v[160:163], v[124:127]
	v_mfma_f32_16x16x32_bf16 v[120:123], v[136:139], v[160:163], v[120:123]
	v_mfma_f32_16x16x32_bf16 v[116:119], v[128:131], v[184:187], v[116:119]
	v_mfma_f32_16x16x32_bf16 v[108:111], v[136:139], v[184:187], v[108:111]
	v_mfma_f32_16x16x32_bf16 v[88:91], v[128:131], v[192:195], v[88:91]
	v_mfma_f32_16x16x32_bf16 v[100:103], v[136:139], v[192:195], v[100:103]
	v_mfma_f32_16x16x32_bf16 v[72:75], v[128:131], v[204:207], v[72:75]
	v_mfma_f32_16x16x32_bf16 v[76:79], v[136:139], v[204:207], v[76:79]
	v_mfma_f32_16x16x32_bf16 v[124:127], v[132:135], v[180:183], v[124:127]
	v_mfma_f32_16x16x32_bf16 v[120:123], v[140:143], v[180:183], v[120:123]
	v_mfma_f32_16x16x32_bf16 v[116:119], v[132:135], v[188:191], v[116:119]
	v_mfma_f32_16x16x32_bf16 v[108:111], v[140:143], v[188:191], v[108:111]
	v_mfma_f32_16x16x32_bf16 v[88:91], v[132:135], v[200:203], v[88:91]
	v_mfma_f32_16x16x32_bf16 v[100:103], v[140:143], v[200:203], v[100:103]
	v_mfma_f32_16x16x32_bf16 v[72:75], v[132:135], v[208:211], v[72:75]
	v_mfma_f32_16x16x32_bf16 v[76:79], v[140:143], v[208:211], v[76:79]
	s_setprio 0
	s_setprio 1
	v_mfma_f32_16x16x32_bf16 v[112:115], v[144:147], v[160:163], v[112:115]
	v_mfma_f32_16x16x32_bf16 v[104:107], v[152:155], v[160:163], v[104:107]
	v_mfma_f32_16x16x32_bf16 v[96:99], v[144:147], v[184:187], v[96:99]
	v_mfma_f32_16x16x32_bf16 v[92:95], v[152:155], v[184:187], v[92:95]
	v_mfma_f32_16x16x32_bf16 v[80:83], v[144:147], v[192:195], v[80:83]
	v_mfma_f32_16x16x32_bf16 v[84:87], v[152:155], v[192:195], v[84:87]
	v_mfma_f32_16x16x32_bf16 v[64:67], v[144:147], v[204:207], v[64:67]
	v_mfma_f32_16x16x32_bf16 v[68:71], v[152:155], v[204:207], v[68:71]
	v_mfma_f32_16x16x32_bf16 v[112:115], v[148:151], v[180:183], v[112:115]
	v_mfma_f32_16x16x32_bf16 v[104:107], v[156:159], v[180:183], v[104:107]
	v_mfma_f32_16x16x32_bf16 v[96:99], v[148:151], v[188:191], v[96:99]
	v_mfma_f32_16x16x32_bf16 v[92:95], v[156:159], v[188:191], v[92:95]
	s_setprio 2
	s_barrier
	v_mfma_f32_16x16x32_bf16 v[80:83], v[148:151], v[200:203], v[80:83]
	v_mfma_f32_16x16x32_bf16 v[84:87], v[156:159], v[200:203], v[84:87]
	v_mfma_f32_16x16x32_bf16 v[64:67], v[148:151], v[208:211], v[64:67]
	v_mfma_f32_16x16x32_bf16 v[68:71], v[156:159], v[208:211], v[68:71]
	s_setprio 2
	s_add_i32 s24, s54, s35
	v_lshl_add_u64 v[212:213], v[212:213], 0, s[16:17]
	s_mov_b32 m0, s24
	ds_read_b128 v[160:163], v199 offset:49152
	ds_read_b128 v[180:183], v199 offset:50176
	ds_read_b128 v[184:187], v199 offset:51200
	ds_read_b128 v[188:191], v199 offset:52224
	ds_read_b128 v[192:195], v199 offset:53248
	ds_read_b128 v[200:203], v199 offset:54272
	ds_read_b128 v[204:207], v199 offset:55296
	ds_read_b128 v[208:211], v199 offset:56320
	global_load_lds_dwordx4 v[212:213], off
	s_add_i32 m0, s24, 0x2000
	s_add_u32 s24, s26, 0xb0080
	v_lshl_add_u64 v[212:213], v[214:215], 0, s[16:17]
	s_addc_u32 s25, s27, 0
	s_add_i32 s26, s55, s35
	global_load_lds_dwordx4 v[212:213], off
	s_mov_b32 m0, s26
	v_lshl_add_u64 v[212:213], s[24:25], 0, v[166:167]
	global_load_lds_dwordx4 v[212:213], off
	s_add_i32 m0, s26, 0x2000
	v_lshl_add_u64 v[212:213], s[24:25], 0, v[170:171]
	global_load_lds_dwordx4 v[212:213], off
	s_mov_b32 m0, s41
	v_lshl_add_u64 v[212:213], v[216:217], 0, s[16:17]
	global_load_lds_dwordx4 v[212:213], off
	s_mov_b32 m0, s42
	v_lshl_add_u64 v[212:213], v[218:219], 0, s[16:17]
	global_load_lds_dwordx4 v[212:213], off
	s_waitcnt vmcnt(8) lgkmcnt(0)
	s_barrier
	s_setprio 1
	v_mfma_f32_16x16x32_bf16 v[56:59], v[128:131], v[160:163], v[56:59]
	v_mfma_f32_16x16x32_bf16 v[60:63], v[136:139], v[160:163], v[60:63]
	v_mfma_f32_16x16x32_bf16 v[40:43], v[128:131], v[184:187], v[40:43]
	v_mfma_f32_16x16x32_bf16 v[44:47], v[136:139], v[184:187], v[44:47]
	v_mfma_f32_16x16x32_bf16 v[24:27], v[128:131], v[192:195], v[24:27]
	v_mfma_f32_16x16x32_bf16 v[28:31], v[136:139], v[192:195], v[28:31]
	v_mfma_f32_16x16x32_bf16 v[8:11], v[128:131], v[204:207], v[8:11]
	v_mfma_f32_16x16x32_bf16 v[12:15], v[136:139], v[204:207], v[12:15]
	v_mfma_f32_16x16x32_bf16 v[56:59], v[132:135], v[180:183], v[56:59]
	v_mfma_f32_16x16x32_bf16 v[60:63], v[140:143], v[180:183], v[60:63]
	v_mfma_f32_16x16x32_bf16 v[40:43], v[132:135], v[188:191], v[40:43]
	v_mfma_f32_16x16x32_bf16 v[44:47], v[140:143], v[188:191], v[44:47]
	v_mfma_f32_16x16x32_bf16 v[24:27], v[132:135], v[200:203], v[24:27]
	v_mfma_f32_16x16x32_bf16 v[28:31], v[140:143], v[200:203], v[28:31]
	v_mfma_f32_16x16x32_bf16 v[8:11], v[132:135], v[208:211], v[8:11]
	v_mfma_f32_16x16x32_bf16 v[12:15], v[140:143], v[208:211], v[12:15]
	s_setprio 0
	s_setprio 1
	v_mfma_f32_16x16x32_bf16 v[48:51], v[144:147], v[160:163], v[48:51]
	v_mfma_f32_16x16x32_bf16 v[52:55], v[152:155], v[160:163], v[52:55]
	v_mfma_f32_16x16x32_bf16 v[32:35], v[144:147], v[184:187], v[32:35]
	v_mfma_f32_16x16x32_bf16 v[36:39], v[152:155], v[184:187], v[36:39]
	v_mfma_f32_16x16x32_bf16 v[16:19], v[144:147], v[192:195], v[16:19]
	v_mfma_f32_16x16x32_bf16 v[20:23], v[152:155], v[192:195], v[20:23]
	v_mfma_f32_16x16x32_bf16 v[0:3], v[144:147], v[204:207], v[0:3]
	v_mfma_f32_16x16x32_bf16 v[4:7], v[152:155], v[204:207], v[4:7]
	v_mfma_f32_16x16x32_bf16 v[48:51], v[148:151], v[180:183], v[48:51]
	v_mfma_f32_16x16x32_bf16 v[52:55], v[156:159], v[180:183], v[52:55]
	v_mfma_f32_16x16x32_bf16 v[32:35], v[148:151], v[188:191], v[32:35]
	v_mfma_f32_16x16x32_bf16 v[36:39], v[156:159], v[188:191], v[36:39]
	s_setprio 2
	s_barrier
	v_mfma_f32_16x16x32_bf16 v[16:19], v[148:151], v[200:203], v[16:19]
	v_mfma_f32_16x16x32_bf16 v[20:23], v[156:159], v[200:203], v[20:23]
	v_mfma_f32_16x16x32_bf16 v[0:3], v[148:151], v[208:211], v[0:3]
	v_mfma_f32_16x16x32_bf16 v[4:7], v[156:159], v[208:211], v[4:7]
	s_setprio 0
	s_add_i32 s53, s53, 2
	s_add_u32 s51, s51, 0x100
	s_addc_u32 s52, s52, 0
	s_cmp_gt_u32 s53, 41
	s_mov_b64 s[24:25], s[4:5]
	s_cbranch_scc0 .LBB0_1310
